# GEMM K-loops: s_setprio 1 moved in front of the pre-MFMA barrier
# baseline (speedup 1.0000x reference)
.LBB0_270:
	s_ashr_i32 s25, s24, 31
	s_lshl_b64 s[22:23], s[24:25], 19
	s_add_u32 s26, s16, s22
	s_addc_u32 s27, s17, s23
	s_and_b64 s[22:23], s[4:5], exec
	s_cselect_b32 s25, s27, s15
	s_cselect_b32 s56, s26, s14
	s_ashr_i32 s21, s20, 31
	s_lshl_b64 s[22:23], s[20:21], 19
	s_add_u32 s28, s34, s22
	s_addc_u32 s29, s35, s23
	s_and_b64 s[22:23], s[4:5], exec
	s_cselect_b32 s21, s29, s3
	s_cselect_b32 s57, s28, s2
	s_add_u32 s14, s14, 0x40080
	s_addc_u32 s15, s15, 0
	s_add_u32 s58, s2, 0x100
	s_addc_u32 s59, s3, 0
	s_mov_b32 s64, -2
	s_waitcnt lgkmcnt(0)
	s_waitcnt vmcnt(0)
	ds_read_b128 v[136:139], v159
	ds_read_b128 v[164:167], v159 offset:1024
	ds_read_b128 v[180:183], v159 offset:2048
	ds_read_b128 v[184:187], v159 offset:3072
	ds_read_b128 v[188:191], v160
	ds_read_b128 v[196:199], v160 offset:1024
	ds_read_b128 v[200:203], v160 offset:2048
	ds_read_b128 v[204:207], v160 offset:3072
	s_add_u32 s2, s14, 0xfffc0080
	s_addc_u32 s3, s15, -1
	s_cmp_eq_u32 s64, 12
	s_cselect_b32 s23, s25, s3
	s_cselect_b32 s22, s56, s2
	s_cselect_b32 s3, s21, s59
	s_cselect_b32 s2, s57, s58
	v_lshl_add_u64 v[168:169], s[14:15], 0, v[128:129]
	s_add_i32 m0, s31, 0xc000
	ds_read_b128 v[208:211], v161
	ds_read_b128 v[212:215], v161 offset:1024
	ds_read_b128 v[216:219], v161 offset:2048
	ds_read_b128 v[220:223], v161 offset:3072
	ds_read_b128 v[224:227], v161 offset:4096
	ds_read_b128 v[228:231], v161 offset:5120
	ds_read_b128 v[232:235], v161 offset:6144
	ds_read_b128 v[236:239], v161 offset:7168
	global_load_lds_dwordx4 v[168:169], off
	v_lshl_add_u64 v[168:169], s[14:15], 0, v[130:131]
	s_add_i32 m0, s31, 0xe000
	s_nop 0
	global_load_lds_dwordx4 v[168:169], off
	s_waitcnt vmcnt(8)
	s_waitcnt lgkmcnt(0)
	s_setprio 1
	s_barrier
	v_mfma_f32_16x16x32_bf16 v[116:119], v[136:139], v[208:211], 0
	v_mfma_f32_16x16x32_bf16 v[112:115], v[180:183], v[208:211], 0
	v_mfma_f32_16x16x32_bf16 v[108:111], v[136:139], v[216:219], 0
	v_mfma_f32_16x16x32_bf16 v[104:107], v[180:183], v[216:219], 0
	v_mfma_f32_16x16x32_bf16 v[92:95], v[136:139], v[224:227], 0
	v_mfma_f32_16x16x32_bf16 v[88:91], v[180:183], v[224:227], 0
	v_mfma_f32_16x16x32_bf16 v[76:79], v[136:139], v[232:235], 0
	v_mfma_f32_16x16x32_bf16 v[72:75], v[180:183], v[232:235], 0
	v_mfma_f32_16x16x32_bf16 v[116:119], v[164:167], v[212:215], v[116:119]
	v_mfma_f32_16x16x32_bf16 v[112:115], v[184:187], v[212:215], v[112:115]
	v_mfma_f32_16x16x32_bf16 v[108:111], v[164:167], v[220:223], v[108:111]
	v_mfma_f32_16x16x32_bf16 v[104:107], v[184:187], v[220:223], v[104:107]
	v_mfma_f32_16x16x32_bf16 v[92:95], v[164:167], v[228:231], v[92:95]
	v_mfma_f32_16x16x32_bf16 v[88:91], v[184:187], v[228:231], v[88:91]
	v_mfma_f32_16x16x32_bf16 v[76:79], v[164:167], v[236:239], v[76:79]
	v_mfma_f32_16x16x32_bf16 v[72:75], v[184:187], v[236:239], v[72:75]
	v_mfma_f32_16x16x32_bf16 v[124:127], v[188:191], v[208:211], 0
	v_mfma_f32_16x16x32_bf16 v[120:123], v[200:203], v[208:211], 0
	v_mfma_f32_16x16x32_bf16 v[100:103], v[188:191], v[216:219], 0
	v_mfma_f32_16x16x32_bf16 v[96:99], v[200:203], v[216:219], 0
	v_mfma_f32_16x16x32_bf16 v[84:87], v[188:191], v[224:227], 0
	v_mfma_f32_16x16x32_bf16 v[80:83], v[200:203], v[224:227], 0
	v_mfma_f32_16x16x32_bf16 v[68:71], v[188:191], v[232:235], 0
	v_mfma_f32_16x16x32_bf16 v[64:67], v[200:203], v[232:235], 0
	v_mfma_f32_16x16x32_bf16 v[124:127], v[196:199], v[212:215], v[124:127]
	v_mfma_f32_16x16x32_bf16 v[120:123], v[204:207], v[212:215], v[120:123]
	v_mfma_f32_16x16x32_bf16 v[100:103], v[196:199], v[220:223], v[100:103]
	v_mfma_f32_16x16x32_bf16 v[96:99], v[204:207], v[220:223], v[96:99]
	v_mfma_f32_16x16x32_bf16 v[84:87], v[196:199], v[228:231], v[84:87]
	v_mfma_f32_16x16x32_bf16 v[80:83], v[204:207], v[228:231], v[80:83]
	v_mfma_f32_16x16x32_bf16 v[68:71], v[196:199], v[236:239], v[68:71]
	v_mfma_f32_16x16x32_bf16 v[64:67], v[204:207], v[236:239], v[64:67]
	s_barrier
	s_setprio 0
	s_add_i32 s65, s49, s37
	v_lshl_add_u64 v[168:169], s[2:3], 0, v[142:143]
	s_mov_b32 m0, s65
	ds_read_b128 v[208:211], v161 offset:16384
	ds_read_b128 v[212:215], v161 offset:17408
	ds_read_b128 v[216:219], v161 offset:18432
	ds_read_b128 v[220:223], v161 offset:19456
	ds_read_b128 v[224:227], v161 offset:20480
	ds_read_b128 v[228:231], v161 offset:21504
	ds_read_b128 v[232:235], v161 offset:22528
	ds_read_b128 v[236:239], v161 offset:23552
	global_load_lds_dwordx4 v[168:169], off
	s_add_i32 m0, s65, 0x2000
	s_add_u32 s66, s2, 0x40000
	v_lshl_add_u64 v[192:193], s[2:3], 0, v[146:147]
	s_addc_u32 s67, s3, 0
	s_add_i32 s65, s50, s37
	global_load_lds_dwordx4 v[192:193], off
	v_lshl_add_u64 v[240:241], s[66:67], 0, v[142:143]
	s_mov_b32 m0, s65
	v_lshl_add_u64 v[242:243], s[22:23], 0, v[144:145]
	global_load_lds_dwordx4 v[240:241], off
	v_lshl_add_u64 v[240:241], s[66:67], 0, v[146:147]
	s_add_i32 m0, s65, 0x2000
	s_nop 0
	global_load_lds_dwordx4 v[240:241], off
	v_lshl_add_u64 v[240:241], s[22:23], 0, v[140:141]
	s_mov_b32 m0, s31
	s_nop 0
	global_load_lds_dwordx4 v[240:241], off
	s_mov_b32 m0, s38
	s_nop 0
	global_load_lds_dwordx4 v[242:243], off
	s_waitcnt vmcnt(8)
	s_waitcnt lgkmcnt(0)
	s_setprio 1
	s_barrier
	v_mfma_f32_16x16x32_bf16 v[52:55], v[136:139], v[208:211], 0
	v_mfma_f32_16x16x32_bf16 v[48:51], v[180:183], v[208:211], 0
	v_mfma_f32_16x16x32_bf16 v[44:47], v[136:139], v[216:219], 0
	v_mfma_f32_16x16x32_bf16 v[40:43], v[180:183], v[216:219], 0
	v_mfma_f32_16x16x32_bf16 v[28:31], v[136:139], v[224:227], 0
	v_mfma_f32_16x16x32_bf16 v[24:27], v[180:183], v[224:227], 0
	v_mfma_f32_16x16x32_bf16 v[12:15], v[136:139], v[232:235], 0
	v_mfma_f32_16x16x32_bf16 v[8:11], v[180:183], v[232:235], 0
	v_mfma_f32_16x16x32_bf16 v[52:55], v[164:167], v[212:215], v[52:55]
	v_mfma_f32_16x16x32_bf16 v[48:51], v[184:187], v[212:215], v[48:51]
	v_mfma_f32_16x16x32_bf16 v[44:47], v[164:167], v[220:223], v[44:47]
	v_mfma_f32_16x16x32_bf16 v[40:43], v[184:187], v[220:223], v[40:43]
	v_mfma_f32_16x16x32_bf16 v[28:31], v[164:167], v[228:231], v[28:31]
	v_mfma_f32_16x16x32_bf16 v[24:27], v[184:187], v[228:231], v[24:27]
	v_mfma_f32_16x16x32_bf16 v[12:15], v[164:167], v[236:239], v[12:15]
	v_mfma_f32_16x16x32_bf16 v[8:11], v[184:187], v[236:239], v[8:11]
	v_mfma_f32_16x16x32_bf16 v[60:63], v[188:191], v[208:211], 0
	v_mfma_f32_16x16x32_bf16 v[56:59], v[200:203], v[208:211], 0
	v_mfma_f32_16x16x32_bf16 v[36:39], v[188:191], v[216:219], 0
	v_mfma_f32_16x16x32_bf16 v[32:35], v[200:203], v[216:219], 0
	v_mfma_f32_16x16x32_bf16 v[20:23], v[188:191], v[224:227], 0
	v_mfma_f32_16x16x32_bf16 v[16:19], v[200:203], v[224:227], 0
	v_mfma_f32_16x16x32_bf16 v[4:7], v[188:191], v[232:235], 0
	v_mfma_f32_16x16x32_bf16 v[0:3], v[200:203], v[232:235], 0
	v_mfma_f32_16x16x32_bf16 v[60:63], v[196:199], v[212:215], v[60:63]
	v_mfma_f32_16x16x32_bf16 v[56:59], v[204:207], v[212:215], v[56:59]
	v_mfma_f32_16x16x32_bf16 v[36:39], v[196:199], v[220:223], v[36:39]
	v_mfma_f32_16x16x32_bf16 v[32:35], v[204:207], v[220:223], v[32:35]
	v_mfma_f32_16x16x32_bf16 v[20:23], v[196:199], v[228:231], v[20:23]
	v_mfma_f32_16x16x32_bf16 v[16:19], v[204:207], v[228:231], v[16:19]
	v_mfma_f32_16x16x32_bf16 v[4:7], v[196:199], v[236:239], v[4:7]
	v_mfma_f32_16x16x32_bf16 v[0:3], v[204:207], v[236:239], v[0:3]
	s_barrier
	s_setprio 0
	s_add_i32 s65, 0, 0x18000
	v_add_u32_e32 v163, s65, v156
	s_add_i32 s66, 0, 0x1c000
	ds_read_b128 v[136:139], v163
	ds_read_b128 v[164:167], v163 offset:1024
	ds_read_b128 v[180:183], v163 offset:2048
	ds_read_b128 v[184:187], v163 offset:3072
	v_add_u32_e32 v163, s66, v156
	ds_read_b128 v[188:191], v163
	ds_read_b128 v[196:199], v163 offset:1024
	ds_read_b128 v[200:203], v163 offset:2048
	ds_read_b128 v[204:207], v163 offset:3072
	s_add_u32 s22, s22, 0x40000
	s_addc_u32 s23, s23, 0
	s_mov_b32 m0, s39
	v_lshl_add_u64 v[244:245], s[22:23], 0, v[140:141]
	ds_read_b128 v[208:211], v161 offset:32768
	ds_read_b128 v[212:215], v161 offset:33792
	ds_read_b128 v[216:219], v161 offset:34816
	ds_read_b128 v[220:223], v161 offset:35840
	ds_read_b128 v[224:227], v161 offset:36864
	ds_read_b128 v[228:231], v161 offset:37888
	ds_read_b128 v[232:235], v161 offset:38912
	ds_read_b128 v[236:239], v161 offset:39936
	global_load_lds_dwordx4 v[244:245], off
	v_lshl_add_u64 v[244:245], s[22:23], 0, v[144:145]
	s_mov_b32 m0, s40
	s_nop 0
	global_load_lds_dwordx4 v[244:245], off
	s_waitcnt vmcnt(8)
	s_waitcnt lgkmcnt(0)
	s_setprio 1
	s_barrier
	v_mfma_f32_16x16x32_bf16 v[116:119], v[136:139], v[208:211], v[116:119]
	v_mfma_f32_16x16x32_bf16 v[112:115], v[180:183], v[208:211], v[112:115]
	v_mfma_f32_16x16x32_bf16 v[108:111], v[136:139], v[216:219], v[108:111]
	v_mfma_f32_16x16x32_bf16 v[104:107], v[180:183], v[216:219], v[104:107]
	v_mfma_f32_16x16x32_bf16 v[92:95], v[136:139], v[224:227], v[92:95]
	v_mfma_f32_16x16x32_bf16 v[88:91], v[180:183], v[224:227], v[88:91]
	v_mfma_f32_16x16x32_bf16 v[76:79], v[136:139], v[232:235], v[76:79]
	v_mfma_f32_16x16x32_bf16 v[72:75], v[180:183], v[232:235], v[72:75]
	v_mfma_f32_16x16x32_bf16 v[116:119], v[164:167], v[212:215], v[116:119]
	v_mfma_f32_16x16x32_bf16 v[112:115], v[184:187], v[212:215], v[112:115]
	v_mfma_f32_16x16x32_bf16 v[108:111], v[164:167], v[220:223], v[108:111]
	v_mfma_f32_16x16x32_bf16 v[104:107], v[184:187], v[220:223], v[104:107]
	v_mfma_f32_16x16x32_bf16 v[92:95], v[164:167], v[228:231], v[92:95]
	v_mfma_f32_16x16x32_bf16 v[88:91], v[184:187], v[228:231], v[88:91]
	v_mfma_f32_16x16x32_bf16 v[76:79], v[164:167], v[236:239], v[76:79]
	v_mfma_f32_16x16x32_bf16 v[72:75], v[184:187], v[236:239], v[72:75]
	v_mfma_f32_16x16x32_bf16 v[124:127], v[188:191], v[208:211], v[124:127]
	v_mfma_f32_16x16x32_bf16 v[120:123], v[200:203], v[208:211], v[120:123]
	v_mfma_f32_16x16x32_bf16 v[100:103], v[188:191], v[216:219], v[100:103]
	v_mfma_f32_16x16x32_bf16 v[96:99], v[200:203], v[216:219], v[96:99]
	v_mfma_f32_16x16x32_bf16 v[84:87], v[188:191], v[224:227], v[84:87]
	v_mfma_f32_16x16x32_bf16 v[80:83], v[200:203], v[224:227], v[80:83]
	v_mfma_f32_16x16x32_bf16 v[68:71], v[188:191], v[232:235], v[68:71]
	v_mfma_f32_16x16x32_bf16 v[64:67], v[200:203], v[232:235], v[64:67]
	v_mfma_f32_16x16x32_bf16 v[124:127], v[196:199], v[212:215], v[124:127]
	v_mfma_f32_16x16x32_bf16 v[120:123], v[204:207], v[212:215], v[120:123]
	v_mfma_f32_16x16x32_bf16 v[100:103], v[196:199], v[220:223], v[100:103]
	v_mfma_f32_16x16x32_bf16 v[96:99], v[204:207], v[220:223], v[96:99]
	v_mfma_f32_16x16x32_bf16 v[84:87], v[196:199], v[228:231], v[84:87]
	v_mfma_f32_16x16x32_bf16 v[80:83], v[204:207], v[228:231], v[80:83]
	v_mfma_f32_16x16x32_bf16 v[68:71], v[196:199], v[236:239], v[68:71]
	v_mfma_f32_16x16x32_bf16 v[64:67], v[204:207], v[236:239], v[64:67]
	s_barrier
	s_setprio 0
	s_add_i32 s22, s65, s37
	v_lshl_add_u64 v[168:169], v[168:169], 0, s[10:11]
	s_mov_b32 m0, s22
	ds_read_b128 v[208:211], v161 offset:49152
	ds_read_b128 v[212:215], v161 offset:50176
	ds_read_b128 v[216:219], v161 offset:51200
	ds_read_b128 v[220:223], v161 offset:52224
	ds_read_b128 v[224:227], v161 offset:53248
	ds_read_b128 v[228:231], v161 offset:54272
	ds_read_b128 v[232:235], v161 offset:55296
	ds_read_b128 v[236:239], v161 offset:56320
	global_load_lds_dwordx4 v[168:169], off
	s_add_i32 m0, s22, 0x2000
	s_add_u32 s2, s2, 0x40080
	v_lshl_add_u64 v[168:169], v[192:193], 0, s[10:11]
	s_addc_u32 s3, s3, 0
	s_add_i32 s22, s66, s37
	global_load_lds_dwordx4 v[168:169], off
	v_lshl_add_u64 v[168:169], s[2:3], 0, v[142:143]
	s_mov_b32 m0, s22
	s_nop 0
	global_load_lds_dwordx4 v[168:169], off
	v_lshl_add_u64 v[168:169], s[2:3], 0, v[146:147]
	s_add_i32 m0, s22, 0x2000
	s_nop 0
	global_load_lds_dwordx4 v[168:169], off
	v_lshl_add_u64 v[168:169], v[240:241], 0, s[10:11]
	s_mov_b32 m0, s43
	s_nop 0
	global_load_lds_dwordx4 v[168:169], off
	v_lshl_add_u64 v[168:169], v[242:243], 0, s[10:11]
	s_mov_b32 m0, s44
	s_nop 0
	global_load_lds_dwordx4 v[168:169], off
	s_waitcnt vmcnt(8)
	s_waitcnt lgkmcnt(0)
	s_setprio 1
	s_barrier
	v_mfma_f32_16x16x32_bf16 v[52:55], v[136:139], v[208:211], v[52:55]
	v_mfma_f32_16x16x32_bf16 v[48:51], v[180:183], v[208:211], v[48:51]
	v_mfma_f32_16x16x32_bf16 v[44:47], v[136:139], v[216:219], v[44:47]
	v_mfma_f32_16x16x32_bf16 v[40:43], v[180:183], v[216:219], v[40:43]
	v_mfma_f32_16x16x32_bf16 v[28:31], v[136:139], v[224:227], v[28:31]
	v_mfma_f32_16x16x32_bf16 v[24:27], v[180:183], v[224:227], v[24:27]
	v_mfma_f32_16x16x32_bf16 v[12:15], v[136:139], v[232:235], v[12:15]
	v_mfma_f32_16x16x32_bf16 v[8:11], v[180:183], v[232:235], v[8:11]
	v_mfma_f32_16x16x32_bf16 v[52:55], v[164:167], v[212:215], v[52:55]
	v_mfma_f32_16x16x32_bf16 v[48:51], v[184:187], v[212:215], v[48:51]
	v_mfma_f32_16x16x32_bf16 v[44:47], v[164:167], v[220:223], v[44:47]
	v_mfma_f32_16x16x32_bf16 v[40:43], v[184:187], v[220:223], v[40:43]
	v_mfma_f32_16x16x32_bf16 v[28:31], v[164:167], v[228:231], v[28:31]
	v_mfma_f32_16x16x32_bf16 v[24:27], v[184:187], v[228:231], v[24:27]
	v_mfma_f32_16x16x32_bf16 v[12:15], v[164:167], v[236:239], v[12:15]
	v_mfma_f32_16x16x32_bf16 v[8:11], v[184:187], v[236:239], v[8:11]
	v_mfma_f32_16x16x32_bf16 v[60:63], v[188:191], v[208:211], v[60:63]
	v_mfma_f32_16x16x32_bf16 v[56:59], v[200:203], v[208:211], v[56:59]
	v_mfma_f32_16x16x32_bf16 v[36:39], v[188:191], v[216:219], v[36:39]
	v_mfma_f32_16x16x32_bf16 v[32:35], v[200:203], v[216:219], v[32:35]
	v_mfma_f32_16x16x32_bf16 v[20:23], v[188:191], v[224:227], v[20:23]
	v_mfma_f32_16x16x32_bf16 v[16:19], v[200:203], v[224:227], v[16:19]
	v_mfma_f32_16x16x32_bf16 v[4:7], v[188:191], v[232:235], v[4:7]
	v_mfma_f32_16x16x32_bf16 v[0:3], v[200:203], v[232:235], v[0:3]
	v_mfma_f32_16x16x32_bf16 v[60:63], v[196:199], v[212:215], v[60:63]
	v_mfma_f32_16x16x32_bf16 v[56:59], v[204:207], v[212:215], v[56:59]
	v_mfma_f32_16x16x32_bf16 v[36:39], v[196:199], v[220:223], v[36:39]
	v_mfma_f32_16x16x32_bf16 v[32:35], v[204:207], v[220:223], v[32:35]
	v_mfma_f32_16x16x32_bf16 v[20:23], v[196:199], v[228:231], v[20:23]
	v_mfma_f32_16x16x32_bf16 v[16:19], v[204:207], v[228:231], v[16:19]
	v_mfma_f32_16x16x32_bf16 v[4:7], v[196:199], v[236:239], v[4:7]
	v_mfma_f32_16x16x32_bf16 v[0:3], v[204:207], v[236:239], v[0:3]
	s_barrier
	s_setprio 0
	s_add_i32 s64, s64, 2
	s_add_u32 s14, s14, 0x100
	s_addc_u32 s15, s15, 0
	s_add_u32 s58, s58, 0x100
	s_addc_u32 s59, s59, 0
	s_cmp_gt_u32 s64, 13
	s_cbranch_scc1 .Lgemm_kdone_0
.LBB0_271:
	ds_read_b128 v[136:139], v159
	ds_read_b128 v[164:167], v159 offset:1024
	ds_read_b128 v[180:183], v159 offset:2048
	ds_read_b128 v[184:187], v159 offset:3072
	ds_read_b128 v[188:191], v160
	ds_read_b128 v[196:199], v160 offset:1024
	ds_read_b128 v[200:203], v160 offset:2048
	ds_read_b128 v[204:207], v160 offset:3072
	s_add_u32 s2, s14, 0xfffc0080
	s_addc_u32 s3, s15, -1
	s_cmp_eq_u32 s64, 12
	s_cselect_b32 s23, s25, s3
	s_cselect_b32 s22, s56, s2
	s_cselect_b32 s3, s21, s59
	s_cselect_b32 s2, s57, s58
	v_lshl_add_u64 v[168:169], s[14:15], 0, v[128:129]
	s_add_i32 m0, s31, 0xc000
	ds_read_b128 v[208:211], v161
	ds_read_b128 v[212:215], v161 offset:1024
	ds_read_b128 v[216:219], v161 offset:2048
	ds_read_b128 v[220:223], v161 offset:3072
	ds_read_b128 v[224:227], v161 offset:4096
	ds_read_b128 v[228:231], v161 offset:5120
	ds_read_b128 v[232:235], v161 offset:6144
	ds_read_b128 v[236:239], v161 offset:7168
	global_load_lds_dwordx4 v[168:169], off
	v_lshl_add_u64 v[168:169], s[14:15], 0, v[130:131]
	s_add_i32 m0, s31, 0xe000
	s_nop 0
	global_load_lds_dwordx4 v[168:169], off
	s_waitcnt vmcnt(8)
	s_waitcnt lgkmcnt(0)
	s_setprio 1
	s_barrier
	v_mfma_f32_16x16x32_bf16 v[116:119], v[136:139], v[208:211], v[116:119]
	v_mfma_f32_16x16x32_bf16 v[112:115], v[180:183], v[208:211], v[112:115]
	v_mfma_f32_16x16x32_bf16 v[108:111], v[136:139], v[216:219], v[108:111]
	v_mfma_f32_16x16x32_bf16 v[104:107], v[180:183], v[216:219], v[104:107]
	v_mfma_f32_16x16x32_bf16 v[92:95], v[136:139], v[224:227], v[92:95]
	v_mfma_f32_16x16x32_bf16 v[88:91], v[180:183], v[224:227], v[88:91]
	v_mfma_f32_16x16x32_bf16 v[76:79], v[136:139], v[232:235], v[76:79]
	v_mfma_f32_16x16x32_bf16 v[72:75], v[180:183], v[232:235], v[72:75]
	v_mfma_f32_16x16x32_bf16 v[116:119], v[164:167], v[212:215], v[116:119]
	v_mfma_f32_16x16x32_bf16 v[112:115], v[184:187], v[212:215], v[112:115]
	v_mfma_f32_16x16x32_bf16 v[108:111], v[164:167], v[220:223], v[108:111]
	v_mfma_f32_16x16x32_bf16 v[104:107], v[184:187], v[220:223], v[104:107]
	v_mfma_f32_16x16x32_bf16 v[92:95], v[164:167], v[228:231], v[92:95]
	v_mfma_f32_16x16x32_bf16 v[88:91], v[184:187], v[228:231], v[88:91]
	v_mfma_f32_16x16x32_bf16 v[76:79], v[164:167], v[236:239], v[76:79]
	v_mfma_f32_16x16x32_bf16 v[72:75], v[184:187], v[236:239], v[72:75]
	v_mfma_f32_16x16x32_bf16 v[124:127], v[188:191], v[208:211], v[124:127]
	v_mfma_f32_16x16x32_bf16 v[120:123], v[200:203], v[208:211], v[120:123]
	v_mfma_f32_16x16x32_bf16 v[100:103], v[188:191], v[216:219], v[100:103]
	v_mfma_f32_16x16x32_bf16 v[96:99], v[200:203], v[216:219], v[96:99]
	v_mfma_f32_16x16x32_bf16 v[84:87], v[188:191], v[224:227], v[84:87]
	v_mfma_f32_16x16x32_bf16 v[80:83], v[200:203], v[224:227], v[80:83]
	v_mfma_f32_16x16x32_bf16 v[68:71], v[188:191], v[232:235], v[68:71]
	v_mfma_f32_16x16x32_bf16 v[64:67], v[200:203], v[232:235], v[64:67]
	v_mfma_f32_16x16x32_bf16 v[124:127], v[196:199], v[212:215], v[124:127]
	v_mfma_f32_16x16x32_bf16 v[120:123], v[204:207], v[212:215], v[120:123]
	v_mfma_f32_16x16x32_bf16 v[100:103], v[196:199], v[220:223], v[100:103]
	v_mfma_f32_16x16x32_bf16 v[96:99], v[204:207], v[220:223], v[96:99]
	v_mfma_f32_16x16x32_bf16 v[84:87], v[196:199], v[228:231], v[84:87]
	v_mfma_f32_16x16x32_bf16 v[80:83], v[204:207], v[228:231], v[80:83]
	v_mfma_f32_16x16x32_bf16 v[68:71], v[196:199], v[236:239], v[68:71]
	v_mfma_f32_16x16x32_bf16 v[64:67], v[204:207], v[236:239], v[64:67]
	s_barrier
	s_setprio 0
	s_add_i32 s65, s49, s37
	v_lshl_add_u64 v[168:169], s[2:3], 0, v[142:143]
	s_mov_b32 m0, s65
	ds_read_b128 v[208:211], v161 offset:16384
	ds_read_b128 v[212:215], v161 offset:17408
	ds_read_b128 v[216:219], v161 offset:18432
	ds_read_b128 v[220:223], v161 offset:19456
	ds_read_b128 v[224:227], v161 offset:20480
	ds_read_b128 v[228:231], v161 offset:21504
	ds_read_b128 v[232:235], v161 offset:22528
	ds_read_b128 v[236:239], v161 offset:23552
	global_load_lds_dwordx4 v[168:169], off
	s_add_i32 m0, s65, 0x2000
	s_add_u32 s66, s2, 0x40000
	v_lshl_add_u64 v[192:193], s[2:3], 0, v[146:147]
	s_addc_u32 s67, s3, 0
	s_add_i32 s65, s50, s37
	global_load_lds_dwordx4 v[192:193], off
	v_lshl_add_u64 v[240:241], s[66:67], 0, v[142:143]
	s_mov_b32 m0, s65
	v_lshl_add_u64 v[242:243], s[22:23], 0, v[144:145]
	global_load_lds_dwordx4 v[240:241], off
	v_lshl_add_u64 v[240:241], s[66:67], 0, v[146:147]
	s_add_i32 m0, s65, 0x2000
	s_nop 0
	global_load_lds_dwordx4 v[240:241], off
	v_lshl_add_u64 v[240:241], s[22:23], 0, v[140:141]
	s_mov_b32 m0, s31
	s_nop 0
	global_load_lds_dwordx4 v[240:241], off
	s_mov_b32 m0, s38
	s_nop 0
	global_load_lds_dwordx4 v[242:243], off
	s_waitcnt vmcnt(8)
	s_waitcnt lgkmcnt(0)
	s_setprio 1
	s_barrier
	v_mfma_f32_16x16x32_bf16 v[52:55], v[136:139], v[208:211], v[52:55]
	v_mfma_f32_16x16x32_bf16 v[48:51], v[180:183], v[208:211], v[48:51]
	v_mfma_f32_16x16x32_bf16 v[44:47], v[136:139], v[216:219], v[44:47]
	v_mfma_f32_16x16x32_bf16 v[40:43], v[180:183], v[216:219], v[40:43]
	v_mfma_f32_16x16x32_bf16 v[28:31], v[136:139], v[224:227], v[28:31]
	v_mfma_f32_16x16x32_bf16 v[24:27], v[180:183], v[224:227], v[24:27]
	v_mfma_f32_16x16x32_bf16 v[12:15], v[136:139], v[232:235], v[12:15]
	v_mfma_f32_16x16x32_bf16 v[8:11], v[180:183], v[232:235], v[8:11]
	v_mfma_f32_16x16x32_bf16 v[52:55], v[164:167], v[212:215], v[52:55]
	v_mfma_f32_16x16x32_bf16 v[48:51], v[184:187], v[212:215], v[48:51]
	v_mfma_f32_16x16x32_bf16 v[44:47], v[164:167], v[220:223], v[44:47]
	v_mfma_f32_16x16x32_bf16 v[40:43], v[184:187], v[220:223], v[40:43]
	v_mfma_f32_16x16x32_bf16 v[28:31], v[164:167], v[228:231], v[28:31]
	v_mfma_f32_16x16x32_bf16 v[24:27], v[184:187], v[228:231], v[24:27]
	v_mfma_f32_16x16x32_bf16 v[12:15], v[164:167], v[236:239], v[12:15]
	v_mfma_f32_16x16x32_bf16 v[8:11], v[184:187], v[236:239], v[8:11]
	v_mfma_f32_16x16x32_bf16 v[60:63], v[188:191], v[208:211], v[60:63]
	v_mfma_f32_16x16x32_bf16 v[56:59], v[200:203], v[208:211], v[56:59]
	v_mfma_f32_16x16x32_bf16 v[36:39], v[188:191], v[216:219], v[36:39]
	v_mfma_f32_16x16x32_bf16 v[32:35], v[200:203], v[216:219], v[32:35]
	v_mfma_f32_16x16x32_bf16 v[20:23], v[188:191], v[224:227], v[20:23]
	v_mfma_f32_16x16x32_bf16 v[16:19], v[200:203], v[224:227], v[16:19]
	v_mfma_f32_16x16x32_bf16 v[4:7], v[188:191], v[232:235], v[4:7]
	v_mfma_f32_16x16x32_bf16 v[0:3], v[200:203], v[232:235], v[0:3]
	v_mfma_f32_16x16x32_bf16 v[60:63], v[196:199], v[212:215], v[60:63]
	v_mfma_f32_16x16x32_bf16 v[56:59], v[204:207], v[212:215], v[56:59]
	v_mfma_f32_16x16x32_bf16 v[36:39], v[196:199], v[220:223], v[36:39]
	v_mfma_f32_16x16x32_bf16 v[32:35], v[204:207], v[220:223], v[32:35]
	v_mfma_f32_16x16x32_bf16 v[20:23], v[196:199], v[228:231], v[20:23]
	v_mfma_f32_16x16x32_bf16 v[16:19], v[204:207], v[228:231], v[16:19]
	v_mfma_f32_16x16x32_bf16 v[4:7], v[196:199], v[236:239], v[4:7]
	v_mfma_f32_16x16x32_bf16 v[0:3], v[204:207], v[236:239], v[0:3]
	s_barrier
	s_setprio 0
	s_add_i32 s65, 0, 0x18000
	v_add_u32_e32 v163, s65, v156
	s_add_i32 s66, 0, 0x1c000
	ds_read_b128 v[136:139], v163
	ds_read_b128 v[164:167], v163 offset:1024
	ds_read_b128 v[180:183], v163 offset:2048
	ds_read_b128 v[184:187], v163 offset:3072
	v_add_u32_e32 v163, s66, v156
	ds_read_b128 v[188:191], v163
	ds_read_b128 v[196:199], v163 offset:1024
	ds_read_b128 v[200:203], v163 offset:2048
	ds_read_b128 v[204:207], v163 offset:3072
	s_add_u32 s22, s22, 0x40000
	s_addc_u32 s23, s23, 0
	s_mov_b32 m0, s39
	v_lshl_add_u64 v[244:245], s[22:23], 0, v[140:141]
	ds_read_b128 v[208:211], v161 offset:32768
	ds_read_b128 v[212:215], v161 offset:33792
	ds_read_b128 v[216:219], v161 offset:34816
	ds_read_b128 v[220:223], v161 offset:35840
	ds_read_b128 v[224:227], v161 offset:36864
	ds_read_b128 v[228:231], v161 offset:37888
	ds_read_b128 v[232:235], v161 offset:38912
	ds_read_b128 v[236:239], v161 offset:39936
	global_load_lds_dwordx4 v[244:245], off
	v_lshl_add_u64 v[244:245], s[22:23], 0, v[144:145]
	s_mov_b32 m0, s40
	s_nop 0
	global_load_lds_dwordx4 v[244:245], off
	s_waitcnt vmcnt(8)
	s_waitcnt lgkmcnt(0)
	s_setprio 1
	s_barrier
	v_mfma_f32_16x16x32_bf16 v[116:119], v[136:139], v[208:211], v[116:119]
	v_mfma_f32_16x16x32_bf16 v[112:115], v[180:183], v[208:211], v[112:115]
	v_mfma_f32_16x16x32_bf16 v[108:111], v[136:139], v[216:219], v[108:111]
	v_mfma_f32_16x16x32_bf16 v[104:107], v[180:183], v[216:219], v[104:107]
	v_mfma_f32_16x16x32_bf16 v[92:95], v[136:139], v[224:227], v[92:95]
	v_mfma_f32_16x16x32_bf16 v[88:91], v[180:183], v[224:227], v[88:91]
	v_mfma_f32_16x16x32_bf16 v[76:79], v[136:139], v[232:235], v[76:79]
	v_mfma_f32_16x16x32_bf16 v[72:75], v[180:183], v[232:235], v[72:75]
	v_mfma_f32_16x16x32_bf16 v[116:119], v[164:167], v[212:215], v[116:119]
	v_mfma_f32_16x16x32_bf16 v[112:115], v[184:187], v[212:215], v[112:115]
	v_mfma_f32_16x16x32_bf16 v[108:111], v[164:167], v[220:223], v[108:111]
	v_mfma_f32_16x16x32_bf16 v[104:107], v[184:187], v[220:223], v[104:107]
	v_mfma_f32_16x16x32_bf16 v[92:95], v[164:167], v[228:231], v[92:95]
	v_mfma_f32_16x16x32_bf16 v[88:91], v[184:187], v[228:231], v[88:91]
	v_mfma_f32_16x16x32_bf16 v[76:79], v[164:167], v[236:239], v[76:79]
	v_mfma_f32_16x16x32_bf16 v[72:75], v[184:187], v[236:239], v[72:75]
	v_mfma_f32_16x16x32_bf16 v[124:127], v[188:191], v[208:211], v[124:127]
	v_mfma_f32_16x16x32_bf16 v[120:123], v[200:203], v[208:211], v[120:123]
	v_mfma_f32_16x16x32_bf16 v[100:103], v[188:191], v[216:219], v[100:103]
	v_mfma_f32_16x16x32_bf16 v[96:99], v[200:203], v[216:219], v[96:99]
	v_mfma_f32_16x16x32_bf16 v[84:87], v[188:191], v[224:227], v[84:87]
	v_mfma_f32_16x16x32_bf16 v[80:83], v[200:203], v[224:227], v[80:83]
	v_mfma_f32_16x16x32_bf16 v[68:71], v[188:191], v[232:235], v[68:71]
	v_mfma_f32_16x16x32_bf16 v[64:67], v[200:203], v[232:235], v[64:67]
	v_mfma_f32_16x16x32_bf16 v[124:127], v[196:199], v[212:215], v[124:127]
	v_mfma_f32_16x16x32_bf16 v[120:123], v[204:207], v[212:215], v[120:123]
	v_mfma_f32_16x16x32_bf16 v[100:103], v[196:199], v[220:223], v[100:103]
	v_mfma_f32_16x16x32_bf16 v[96:99], v[204:207], v[220:223], v[96:99]
	v_mfma_f32_16x16x32_bf16 v[84:87], v[196:199], v[228:231], v[84:87]
	v_mfma_f32_16x16x32_bf16 v[80:83], v[204:207], v[228:231], v[80:83]
	v_mfma_f32_16x16x32_bf16 v[68:71], v[196:199], v[236:239], v[68:71]
	v_mfma_f32_16x16x32_bf16 v[64:67], v[204:207], v[236:239], v[64:67]
	s_barrier
	s_setprio 0
	s_add_i32 s22, s65, s37
	v_lshl_add_u64 v[168:169], v[168:169], 0, s[10:11]
	s_mov_b32 m0, s22
	ds_read_b128 v[208:211], v161 offset:49152
	ds_read_b128 v[212:215], v161 offset:50176
	ds_read_b128 v[216:219], v161 offset:51200
	ds_read_b128 v[220:223], v161 offset:52224
	ds_read_b128 v[224:227], v161 offset:53248
	ds_read_b128 v[228:231], v161 offset:54272
	ds_read_b128 v[232:235], v161 offset:55296
	ds_read_b128 v[236:239], v161 offset:56320
	global_load_lds_dwordx4 v[168:169], off
	s_add_i32 m0, s22, 0x2000
	s_add_u32 s2, s2, 0x40080
	v_lshl_add_u64 v[168:169], v[192:193], 0, s[10:11]
	s_addc_u32 s3, s3, 0
	s_add_i32 s22, s66, s37
	global_load_lds_dwordx4 v[168:169], off
	v_lshl_add_u64 v[168:169], s[2:3], 0, v[142:143]
	s_mov_b32 m0, s22
	s_nop 0
	global_load_lds_dwordx4 v[168:169], off
	v_lshl_add_u64 v[168:169], s[2:3], 0, v[146:147]
	s_add_i32 m0, s22, 0x2000
	s_nop 0
	global_load_lds_dwordx4 v[168:169], off
	v_lshl_add_u64 v[168:169], v[240:241], 0, s[10:11]
	s_mov_b32 m0, s43
	s_nop 0
	global_load_lds_dwordx4 v[168:169], off
	v_lshl_add_u64 v[168:169], v[242:243], 0, s[10:11]
	s_mov_b32 m0, s44
	s_nop 0
	global_load_lds_dwordx4 v[168:169], off
	s_waitcnt vmcnt(8)
	s_waitcnt lgkmcnt(0)
	s_setprio 1
	s_barrier
	v_mfma_f32_16x16x32_bf16 v[52:55], v[136:139], v[208:211], v[52:55]
	v_mfma_f32_16x16x32_bf16 v[48:51], v[180:183], v[208:211], v[48:51]
	v_mfma_f32_16x16x32_bf16 v[44:47], v[136:139], v[216:219], v[44:47]
	v_mfma_f32_16x16x32_bf16 v[40:43], v[180:183], v[216:219], v[40:43]
	v_mfma_f32_16x16x32_bf16 v[28:31], v[136:139], v[224:227], v[28:31]
	v_mfma_f32_16x16x32_bf16 v[24:27], v[180:183], v[224:227], v[24:27]
	v_mfma_f32_16x16x32_bf16 v[12:15], v[136:139], v[232:235], v[12:15]
	v_mfma_f32_16x16x32_bf16 v[8:11], v[180:183], v[232:235], v[8:11]
	v_mfma_f32_16x16x32_bf16 v[52:55], v[164:167], v[212:215], v[52:55]
	v_mfma_f32_16x16x32_bf16 v[48:51], v[184:187], v[212:215], v[48:51]
	v_mfma_f32_16x16x32_bf16 v[44:47], v[164:167], v[220:223], v[44:47]
	v_mfma_f32_16x16x32_bf16 v[40:43], v[184:187], v[220:223], v[40:43]
	v_mfma_f32_16x16x32_bf16 v[28:31], v[164:167], v[228:231], v[28:31]
	v_mfma_f32_16x16x32_bf16 v[24:27], v[184:187], v[228:231], v[24:27]
	v_mfma_f32_16x16x32_bf16 v[12:15], v[164:167], v[236:239], v[12:15]
	v_mfma_f32_16x16x32_bf16 v[8:11], v[184:187], v[236:239], v[8:11]
	v_mfma_f32_16x16x32_bf16 v[60:63], v[188:191], v[208:211], v[60:63]
	v_mfma_f32_16x16x32_bf16 v[56:59], v[200:203], v[208:211], v[56:59]
	v_mfma_f32_16x16x32_bf16 v[36:39], v[188:191], v[216:219], v[36:39]
	v_mfma_f32_16x16x32_bf16 v[32:35], v[200:203], v[216:219], v[32:35]
	v_mfma_f32_16x16x32_bf16 v[20:23], v[188:191], v[224:227], v[20:23]
	v_mfma_f32_16x16x32_bf16 v[16:19], v[200:203], v[224:227], v[16:19]
	v_mfma_f32_16x16x32_bf16 v[4:7], v[188:191], v[232:235], v[4:7]
	v_mfma_f32_16x16x32_bf16 v[0:3], v[200:203], v[232:235], v[0:3]
	v_mfma_f32_16x16x32_bf16 v[60:63], v[196:199], v[212:215], v[60:63]
	v_mfma_f32_16x16x32_bf16 v[56:59], v[204:207], v[212:215], v[56:59]
	v_mfma_f32_16x16x32_bf16 v[36:39], v[196:199], v[220:223], v[36:39]
	v_mfma_f32_16x16x32_bf16 v[32:35], v[204:207], v[220:223], v[32:35]
	v_mfma_f32_16x16x32_bf16 v[20:23], v[196:199], v[228:231], v[20:23]
	v_mfma_f32_16x16x32_bf16 v[16:19], v[204:207], v[228:231], v[16:19]
	v_mfma_f32_16x16x32_bf16 v[4:7], v[196:199], v[236:239], v[4:7]
	v_mfma_f32_16x16x32_bf16 v[0:3], v[204:207], v[236:239], v[0:3]
	s_barrier
	s_setprio 0
	s_add_i32 s64, s64, 2
	s_add_u32 s14, s14, 0x100
	s_addc_u32 s15, s15, 0
	s_add_u32 s58, s58, 0x100
	s_addc_u32 s59, s59, 0
	s_cmp_gt_u32 s64, 13
	s_cbranch_scc0 .LBB0_271

.LBB0_367:
	s_ashr_i32 s25, s24, 31
	s_lshl_b64 s[22:23], s[24:25], 19
	s_add_u32 s26, s84, s22
	s_addc_u32 s27, s85, s23
	s_and_b64 s[22:23], s[0:1], exec
	s_cselect_b32 s25, s27, s15
	s_cselect_b32 s50, s26, s14
	s_ashr_i32 s21, s20, 31
	s_lshl_b64 s[22:23], s[20:21], 19
	s_add_u32 s28, s30, s22
	s_addc_u32 s29, s31, s23
	s_and_b64 s[22:23], s[0:1], exec
	s_cselect_b32 s21, s29, s3
	s_cselect_b32 s51, s28, s2
	s_add_u32 s14, s14, 0x40080
	s_addc_u32 s15, s15, 0
	s_add_u32 s52, s2, 0x100
	s_addc_u32 s53, s3, 0
	s_mov_b32 s54, -2
	s_waitcnt vmcnt(0)
	ds_read_b128 v[158:161], v154
	ds_read_b128 v[162:165], v154 offset:1024
	ds_read_b128 v[166:169], v154 offset:2048
	ds_read_b128 v[182:185], v154 offset:3072
	ds_read_b128 v[186:189], v155
	ds_read_b128 v[190:193], v155 offset:1024
	ds_read_b128 v[196:199], v155 offset:2048
	ds_read_b128 v[200:203], v155 offset:3072
	s_add_u32 s2, s14, 0xfffc0080
	s_addc_u32 s3, s15, -1
	s_cmp_eq_u32 s54, 12
	s_cselect_b32 s23, s25, s3
	s_cselect_b32 s22, s50, s2
	s_cselect_b32 s3, s21, s53
	s_cselect_b32 s2, s51, s52
	v_lshl_add_u64 v[136:137], s[14:15], 0, v[128:129]
	s_add_i32 m0, s37, 0xc000
	ds_read_b128 v[204:207], v156
	ds_read_b128 v[208:211], v156 offset:1024
	ds_read_b128 v[212:215], v156 offset:2048
	ds_read_b128 v[216:219], v156 offset:3072
	ds_read_b128 v[220:223], v156 offset:4096
	ds_read_b128 v[224:227], v156 offset:5120
	ds_read_b128 v[228:231], v156 offset:6144
	ds_read_b128 v[232:235], v156 offset:7168
	global_load_lds_dwordx4 v[136:137], off
	v_lshl_add_u64 v[136:137], s[14:15], 0, v[130:131]
	s_add_i32 m0, s37, 0xe000
	s_nop 0
	global_load_lds_dwordx4 v[136:137], off
	s_waitcnt vmcnt(8)
	s_waitcnt lgkmcnt(0)
	s_setprio 1
	s_barrier
	v_mfma_f32_16x16x32_bf16 v[112:115], v[158:161], v[204:207], 0
	v_mfma_f32_16x16x32_bf16 v[108:111], v[166:169], v[204:207], 0
	v_mfma_f32_16x16x32_bf16 v[104:107], v[158:161], v[212:215], 0
	v_mfma_f32_16x16x32_bf16 v[100:103], v[166:169], v[212:215], 0
	v_mfma_f32_16x16x32_bf16 v[92:95], v[158:161], v[220:223], 0
	v_mfma_f32_16x16x32_bf16 v[84:87], v[166:169], v[220:223], 0
	v_mfma_f32_16x16x32_bf16 v[76:79], v[158:161], v[228:231], 0
	v_mfma_f32_16x16x32_bf16 v[68:71], v[166:169], v[228:231], 0
	v_mfma_f32_16x16x32_bf16 v[112:115], v[162:165], v[208:211], v[112:115]
	v_mfma_f32_16x16x32_bf16 v[108:111], v[182:185], v[208:211], v[108:111]
	v_mfma_f32_16x16x32_bf16 v[104:107], v[162:165], v[216:219], v[104:107]
	v_mfma_f32_16x16x32_bf16 v[100:103], v[182:185], v[216:219], v[100:103]
	v_mfma_f32_16x16x32_bf16 v[92:95], v[162:165], v[224:227], v[92:95]
	v_mfma_f32_16x16x32_bf16 v[84:87], v[182:185], v[224:227], v[84:87]
	v_mfma_f32_16x16x32_bf16 v[76:79], v[162:165], v[232:235], v[76:79]
	v_mfma_f32_16x16x32_bf16 v[68:71], v[182:185], v[232:235], v[68:71]
	v_mfma_f32_16x16x32_bf16 v[124:127], v[186:189], v[204:207], 0
	v_mfma_f32_16x16x32_bf16 v[120:123], v[196:199], v[204:207], 0
	v_mfma_f32_16x16x32_bf16 v[116:119], v[186:189], v[212:215], 0
	v_mfma_f32_16x16x32_bf16 v[96:99], v[196:199], v[212:215], 0
	v_mfma_f32_16x16x32_bf16 v[88:91], v[186:189], v[220:223], 0
	v_mfma_f32_16x16x32_bf16 v[80:83], v[196:199], v[220:223], 0
	v_mfma_f32_16x16x32_bf16 v[72:75], v[186:189], v[228:231], 0
	v_mfma_f32_16x16x32_bf16 v[64:67], v[196:199], v[228:231], 0
	v_mfma_f32_16x16x32_bf16 v[124:127], v[190:193], v[208:211], v[124:127]
	v_mfma_f32_16x16x32_bf16 v[120:123], v[200:203], v[208:211], v[120:123]
	v_mfma_f32_16x16x32_bf16 v[116:119], v[190:193], v[216:219], v[116:119]
	v_mfma_f32_16x16x32_bf16 v[96:99], v[200:203], v[216:219], v[96:99]
	v_mfma_f32_16x16x32_bf16 v[88:91], v[190:193], v[224:227], v[88:91]
	v_mfma_f32_16x16x32_bf16 v[80:83], v[200:203], v[224:227], v[80:83]
	v_mfma_f32_16x16x32_bf16 v[72:75], v[190:193], v[232:235], v[72:75]
	v_mfma_f32_16x16x32_bf16 v[64:67], v[200:203], v[232:235], v[64:67]
	s_barrier
	s_setprio 0
	s_add_i32 s55, s46, s34
	v_lshl_add_u64 v[136:137], s[2:3], 0, v[142:143]
	s_mov_b32 m0, s55
	ds_read_b128 v[204:207], v156 offset:16384
	ds_read_b128 v[208:211], v156 offset:17408
	ds_read_b128 v[212:215], v156 offset:18432
	ds_read_b128 v[216:219], v156 offset:19456
	ds_read_b128 v[220:223], v156 offset:20480
	ds_read_b128 v[224:227], v156 offset:21504
	ds_read_b128 v[228:231], v156 offset:22528
	ds_read_b128 v[232:235], v156 offset:23552
	global_load_lds_dwordx4 v[136:137], off
	s_add_i32 m0, s55, 0x2000
	s_add_u32 s56, s2, 0x40000
	v_lshl_add_u64 v[236:237], s[2:3], 0, v[146:147]
	s_addc_u32 s57, s3, 0
	s_add_i32 s55, s47, s34
	global_load_lds_dwordx4 v[236:237], off
	v_lshl_add_u64 v[238:239], s[56:57], 0, v[142:143]
	s_mov_b32 m0, s55
	v_lshl_add_u64 v[240:241], s[22:23], 0, v[144:145]
	global_load_lds_dwordx4 v[238:239], off
	v_lshl_add_u64 v[238:239], s[56:57], 0, v[146:147]
	s_add_i32 m0, s55, 0x2000
	s_nop 0
	global_load_lds_dwordx4 v[238:239], off
	v_lshl_add_u64 v[238:239], s[22:23], 0, v[140:141]
	s_mov_b32 m0, s37
	s_nop 0
	global_load_lds_dwordx4 v[238:239], off
	s_mov_b32 m0, s38
	s_nop 0
	global_load_lds_dwordx4 v[240:241], off
	s_waitcnt vmcnt(8)
	s_waitcnt lgkmcnt(0)
	s_setprio 1
	s_barrier
	v_mfma_f32_16x16x32_bf16 v[60:63], v[158:161], v[204:207], 0
	v_mfma_f32_16x16x32_bf16 v[52:55], v[166:169], v[204:207], 0
	v_mfma_f32_16x16x32_bf16 v[44:47], v[158:161], v[212:215], 0
	v_mfma_f32_16x16x32_bf16 v[36:39], v[166:169], v[212:215], 0
	v_mfma_f32_16x16x32_bf16 v[28:31], v[158:161], v[220:223], 0
	v_mfma_f32_16x16x32_bf16 v[20:23], v[166:169], v[220:223], 0
	v_mfma_f32_16x16x32_bf16 v[12:15], v[158:161], v[228:231], 0
	v_mfma_f32_16x16x32_bf16 v[4:7], v[166:169], v[228:231], 0
	v_mfma_f32_16x16x32_bf16 v[60:63], v[162:165], v[208:211], v[60:63]
	v_mfma_f32_16x16x32_bf16 v[52:55], v[182:185], v[208:211], v[52:55]
	v_mfma_f32_16x16x32_bf16 v[44:47], v[162:165], v[216:219], v[44:47]
	v_mfma_f32_16x16x32_bf16 v[36:39], v[182:185], v[216:219], v[36:39]
	v_mfma_f32_16x16x32_bf16 v[28:31], v[162:165], v[224:227], v[28:31]
	v_mfma_f32_16x16x32_bf16 v[20:23], v[182:185], v[224:227], v[20:23]
	v_mfma_f32_16x16x32_bf16 v[12:15], v[162:165], v[232:235], v[12:15]
	v_mfma_f32_16x16x32_bf16 v[4:7], v[182:185], v[232:235], v[4:7]
	v_mfma_f32_16x16x32_bf16 v[56:59], v[186:189], v[204:207], 0
	v_mfma_f32_16x16x32_bf16 v[48:51], v[196:199], v[204:207], 0
	v_mfma_f32_16x16x32_bf16 v[40:43], v[186:189], v[212:215], 0
	v_mfma_f32_16x16x32_bf16 v[32:35], v[196:199], v[212:215], 0
	v_mfma_f32_16x16x32_bf16 v[24:27], v[186:189], v[220:223], 0
	v_mfma_f32_16x16x32_bf16 v[16:19], v[196:199], v[220:223], 0
	v_mfma_f32_16x16x32_bf16 v[8:11], v[186:189], v[228:231], 0
	v_mfma_f32_16x16x32_bf16 v[0:3], v[196:199], v[228:231], 0
	v_mfma_f32_16x16x32_bf16 v[56:59], v[190:193], v[208:211], v[56:59]
	v_mfma_f32_16x16x32_bf16 v[48:51], v[200:203], v[208:211], v[48:51]
	v_mfma_f32_16x16x32_bf16 v[40:43], v[190:193], v[216:219], v[40:43]
	v_mfma_f32_16x16x32_bf16 v[32:35], v[200:203], v[216:219], v[32:35]
	v_mfma_f32_16x16x32_bf16 v[24:27], v[190:193], v[224:227], v[24:27]
	v_mfma_f32_16x16x32_bf16 v[16:19], v[200:203], v[224:227], v[16:19]
	v_mfma_f32_16x16x32_bf16 v[8:11], v[190:193], v[232:235], v[8:11]
	v_mfma_f32_16x16x32_bf16 v[0:3], v[200:203], v[232:235], v[0:3]
	s_barrier
	s_setprio 0
	s_add_i32 s55, 0, 0x18000
	s_add_i32 s56, 0, 0x1c000
	v_add_u32_e32 v182, s55, v139
	v_add_u32_e32 v200, s56, v139
	ds_read_b128 v[158:161], v182
	ds_read_b128 v[162:165], v182 offset:1024
	ds_read_b128 v[166:169], v182 offset:2048
	ds_read_b128 v[182:185], v182 offset:3072
	ds_read_b128 v[186:189], v200
	ds_read_b128 v[190:193], v200 offset:1024
	ds_read_b128 v[196:199], v200 offset:2048
	ds_read_b128 v[200:203], v200 offset:3072
	s_add_u32 s22, s22, 0x40000
	s_addc_u32 s23, s23, 0
	s_mov_b32 m0, s39
	v_lshl_add_u64 v[242:243], s[22:23], 0, v[140:141]
	ds_read_b128 v[204:207], v156 offset:32768
	ds_read_b128 v[208:211], v156 offset:33792
	ds_read_b128 v[212:215], v156 offset:34816
	ds_read_b128 v[216:219], v156 offset:35840
	ds_read_b128 v[220:223], v156 offset:36864
	ds_read_b128 v[224:227], v156 offset:37888
	ds_read_b128 v[228:231], v156 offset:38912
	ds_read_b128 v[232:235], v156 offset:39936
	global_load_lds_dwordx4 v[242:243], off
	v_lshl_add_u64 v[242:243], s[22:23], 0, v[144:145]
	s_mov_b32 m0, s40
	s_nop 0
	global_load_lds_dwordx4 v[242:243], off
	s_waitcnt vmcnt(8)
	s_waitcnt lgkmcnt(0)
	s_setprio 1
	s_barrier
	v_mfma_f32_16x16x32_bf16 v[112:115], v[158:161], v[204:207], v[112:115]
	v_mfma_f32_16x16x32_bf16 v[108:111], v[166:169], v[204:207], v[108:111]
	v_mfma_f32_16x16x32_bf16 v[104:107], v[158:161], v[212:215], v[104:107]
	v_mfma_f32_16x16x32_bf16 v[100:103], v[166:169], v[212:215], v[100:103]
	v_mfma_f32_16x16x32_bf16 v[92:95], v[158:161], v[220:223], v[92:95]
	v_mfma_f32_16x16x32_bf16 v[84:87], v[166:169], v[220:223], v[84:87]
	v_mfma_f32_16x16x32_bf16 v[76:79], v[158:161], v[228:231], v[76:79]
	v_mfma_f32_16x16x32_bf16 v[68:71], v[166:169], v[228:231], v[68:71]
	v_mfma_f32_16x16x32_bf16 v[112:115], v[162:165], v[208:211], v[112:115]
	v_mfma_f32_16x16x32_bf16 v[108:111], v[182:185], v[208:211], v[108:111]
	v_mfma_f32_16x16x32_bf16 v[104:107], v[162:165], v[216:219], v[104:107]
	v_mfma_f32_16x16x32_bf16 v[100:103], v[182:185], v[216:219], v[100:103]
	v_mfma_f32_16x16x32_bf16 v[92:95], v[162:165], v[224:227], v[92:95]
	v_mfma_f32_16x16x32_bf16 v[84:87], v[182:185], v[224:227], v[84:87]
	v_mfma_f32_16x16x32_bf16 v[76:79], v[162:165], v[232:235], v[76:79]
	v_mfma_f32_16x16x32_bf16 v[68:71], v[182:185], v[232:235], v[68:71]
	v_mfma_f32_16x16x32_bf16 v[124:127], v[186:189], v[204:207], v[124:127]
	v_mfma_f32_16x16x32_bf16 v[120:123], v[196:199], v[204:207], v[120:123]
	v_mfma_f32_16x16x32_bf16 v[116:119], v[186:189], v[212:215], v[116:119]
	v_mfma_f32_16x16x32_bf16 v[96:99], v[196:199], v[212:215], v[96:99]
	v_mfma_f32_16x16x32_bf16 v[88:91], v[186:189], v[220:223], v[88:91]
	v_mfma_f32_16x16x32_bf16 v[80:83], v[196:199], v[220:223], v[80:83]
	v_mfma_f32_16x16x32_bf16 v[72:75], v[186:189], v[228:231], v[72:75]
	v_mfma_f32_16x16x32_bf16 v[64:67], v[196:199], v[228:231], v[64:67]
	v_mfma_f32_16x16x32_bf16 v[124:127], v[190:193], v[208:211], v[124:127]
	v_mfma_f32_16x16x32_bf16 v[120:123], v[200:203], v[208:211], v[120:123]
	v_mfma_f32_16x16x32_bf16 v[116:119], v[190:193], v[216:219], v[116:119]
	v_mfma_f32_16x16x32_bf16 v[96:99], v[200:203], v[216:219], v[96:99]
	v_mfma_f32_16x16x32_bf16 v[88:91], v[190:193], v[224:227], v[88:91]
	v_mfma_f32_16x16x32_bf16 v[80:83], v[200:203], v[224:227], v[80:83]
	v_mfma_f32_16x16x32_bf16 v[72:75], v[190:193], v[232:235], v[72:75]
	v_mfma_f32_16x16x32_bf16 v[64:67], v[200:203], v[232:235], v[64:67]
	s_barrier
	s_setprio 0
	s_add_i32 s22, s55, s34
	v_lshl_add_u64 v[136:137], v[136:137], 0, s[8:9]
	s_mov_b32 m0, s22
	ds_read_b128 v[204:207], v156 offset:49152
	ds_read_b128 v[208:211], v156 offset:50176
	ds_read_b128 v[212:215], v156 offset:51200
	ds_read_b128 v[216:219], v156 offset:52224
	ds_read_b128 v[220:223], v156 offset:53248
	ds_read_b128 v[224:227], v156 offset:54272
	ds_read_b128 v[228:231], v156 offset:55296
	ds_read_b128 v[232:235], v156 offset:56320
	global_load_lds_dwordx4 v[136:137], off
	s_add_i32 m0, s22, 0x2000
	s_add_u32 s2, s2, 0x40080
	v_lshl_add_u64 v[136:137], v[236:237], 0, s[8:9]
	s_addc_u32 s3, s3, 0
	s_add_i32 s22, s56, s34
	global_load_lds_dwordx4 v[136:137], off
	v_lshl_add_u64 v[136:137], s[2:3], 0, v[142:143]
	s_mov_b32 m0, s22
	s_nop 0
	global_load_lds_dwordx4 v[136:137], off
	v_lshl_add_u64 v[136:137], s[2:3], 0, v[146:147]
	s_add_i32 m0, s22, 0x2000
	s_nop 0
	global_load_lds_dwordx4 v[136:137], off
	v_lshl_add_u64 v[136:137], v[238:239], 0, s[8:9]
	s_mov_b32 m0, s42
	s_nop 0
	global_load_lds_dwordx4 v[136:137], off
	v_lshl_add_u64 v[136:137], v[240:241], 0, s[8:9]
	s_mov_b32 m0, s43
	s_nop 0
	global_load_lds_dwordx4 v[136:137], off
	s_waitcnt vmcnt(8)
	s_waitcnt lgkmcnt(0)
	s_setprio 1
	s_barrier
	v_mfma_f32_16x16x32_bf16 v[60:63], v[158:161], v[204:207], v[60:63]
	v_mfma_f32_16x16x32_bf16 v[52:55], v[166:169], v[204:207], v[52:55]
	v_mfma_f32_16x16x32_bf16 v[44:47], v[158:161], v[212:215], v[44:47]
	v_mfma_f32_16x16x32_bf16 v[36:39], v[166:169], v[212:215], v[36:39]
	v_mfma_f32_16x16x32_bf16 v[28:31], v[158:161], v[220:223], v[28:31]
	v_mfma_f32_16x16x32_bf16 v[20:23], v[166:169], v[220:223], v[20:23]
	v_mfma_f32_16x16x32_bf16 v[12:15], v[158:161], v[228:231], v[12:15]
	v_mfma_f32_16x16x32_bf16 v[4:7], v[166:169], v[228:231], v[4:7]
	v_mfma_f32_16x16x32_bf16 v[60:63], v[162:165], v[208:211], v[60:63]
	v_mfma_f32_16x16x32_bf16 v[52:55], v[182:185], v[208:211], v[52:55]
	v_mfma_f32_16x16x32_bf16 v[44:47], v[162:165], v[216:219], v[44:47]
	v_mfma_f32_16x16x32_bf16 v[36:39], v[182:185], v[216:219], v[36:39]
	v_mfma_f32_16x16x32_bf16 v[28:31], v[162:165], v[224:227], v[28:31]
	v_mfma_f32_16x16x32_bf16 v[20:23], v[182:185], v[224:227], v[20:23]
	v_mfma_f32_16x16x32_bf16 v[12:15], v[162:165], v[232:235], v[12:15]
	v_mfma_f32_16x16x32_bf16 v[4:7], v[182:185], v[232:235], v[4:7]
	v_mfma_f32_16x16x32_bf16 v[56:59], v[186:189], v[204:207], v[56:59]
	v_mfma_f32_16x16x32_bf16 v[48:51], v[196:199], v[204:207], v[48:51]
	v_mfma_f32_16x16x32_bf16 v[40:43], v[186:189], v[212:215], v[40:43]
	v_mfma_f32_16x16x32_bf16 v[32:35], v[196:199], v[212:215], v[32:35]
	v_mfma_f32_16x16x32_bf16 v[24:27], v[186:189], v[220:223], v[24:27]
	v_mfma_f32_16x16x32_bf16 v[16:19], v[196:199], v[220:223], v[16:19]
	v_mfma_f32_16x16x32_bf16 v[8:11], v[186:189], v[228:231], v[8:11]
	v_mfma_f32_16x16x32_bf16 v[0:3], v[196:199], v[228:231], v[0:3]
	v_mfma_f32_16x16x32_bf16 v[56:59], v[190:193], v[208:211], v[56:59]
	v_mfma_f32_16x16x32_bf16 v[48:51], v[200:203], v[208:211], v[48:51]
	v_mfma_f32_16x16x32_bf16 v[40:43], v[190:193], v[216:219], v[40:43]
	v_mfma_f32_16x16x32_bf16 v[32:35], v[200:203], v[216:219], v[32:35]
	v_mfma_f32_16x16x32_bf16 v[24:27], v[190:193], v[224:227], v[24:27]
	v_mfma_f32_16x16x32_bf16 v[16:19], v[200:203], v[224:227], v[16:19]
	v_mfma_f32_16x16x32_bf16 v[8:11], v[190:193], v[232:235], v[8:11]
	v_mfma_f32_16x16x32_bf16 v[0:3], v[200:203], v[232:235], v[0:3]
	s_barrier
	s_setprio 0
	s_add_i32 s54, s54, 2
	s_add_u32 s14, s14, 0x100
	s_addc_u32 s15, s15, 0
	s_add_u32 s52, s52, 0x100
	s_addc_u32 s53, s53, 0
	s_cmp_gt_u32 s54, 13
	s_cbranch_scc1 .Lgemm_kdone_1
.LBB0_368:
	ds_read_b128 v[158:161], v154
	ds_read_b128 v[162:165], v154 offset:1024
	ds_read_b128 v[166:169], v154 offset:2048
	ds_read_b128 v[182:185], v154 offset:3072
	ds_read_b128 v[186:189], v155
	ds_read_b128 v[190:193], v155 offset:1024
	ds_read_b128 v[196:199], v155 offset:2048
	ds_read_b128 v[200:203], v155 offset:3072
	s_add_u32 s2, s14, 0xfffc0080
	s_addc_u32 s3, s15, -1
	s_cmp_eq_u32 s54, 12
	s_cselect_b32 s23, s25, s3
	s_cselect_b32 s22, s50, s2
	s_cselect_b32 s3, s21, s53
	s_cselect_b32 s2, s51, s52
	v_lshl_add_u64 v[136:137], s[14:15], 0, v[128:129]
	s_add_i32 m0, s37, 0xc000
	ds_read_b128 v[204:207], v156
	ds_read_b128 v[208:211], v156 offset:1024
	ds_read_b128 v[212:215], v156 offset:2048
	ds_read_b128 v[216:219], v156 offset:3072
	ds_read_b128 v[220:223], v156 offset:4096
	ds_read_b128 v[224:227], v156 offset:5120
	ds_read_b128 v[228:231], v156 offset:6144
	ds_read_b128 v[232:235], v156 offset:7168
	global_load_lds_dwordx4 v[136:137], off
	v_lshl_add_u64 v[136:137], s[14:15], 0, v[130:131]
	s_add_i32 m0, s37, 0xe000
	s_nop 0
	global_load_lds_dwordx4 v[136:137], off
	s_waitcnt vmcnt(8)
	s_waitcnt lgkmcnt(0)
	s_setprio 1
	s_barrier
	v_mfma_f32_16x16x32_bf16 v[112:115], v[158:161], v[204:207], v[112:115]
	v_mfma_f32_16x16x32_bf16 v[108:111], v[166:169], v[204:207], v[108:111]
	v_mfma_f32_16x16x32_bf16 v[104:107], v[158:161], v[212:215], v[104:107]
	v_mfma_f32_16x16x32_bf16 v[100:103], v[166:169], v[212:215], v[100:103]
	v_mfma_f32_16x16x32_bf16 v[92:95], v[158:161], v[220:223], v[92:95]
	v_mfma_f32_16x16x32_bf16 v[84:87], v[166:169], v[220:223], v[84:87]
	v_mfma_f32_16x16x32_bf16 v[76:79], v[158:161], v[228:231], v[76:79]
	v_mfma_f32_16x16x32_bf16 v[68:71], v[166:169], v[228:231], v[68:71]
	v_mfma_f32_16x16x32_bf16 v[112:115], v[162:165], v[208:211], v[112:115]
	v_mfma_f32_16x16x32_bf16 v[108:111], v[182:185], v[208:211], v[108:111]
	v_mfma_f32_16x16x32_bf16 v[104:107], v[162:165], v[216:219], v[104:107]
	v_mfma_f32_16x16x32_bf16 v[100:103], v[182:185], v[216:219], v[100:103]
	v_mfma_f32_16x16x32_bf16 v[92:95], v[162:165], v[224:227], v[92:95]
	v_mfma_f32_16x16x32_bf16 v[84:87], v[182:185], v[224:227], v[84:87]
	v_mfma_f32_16x16x32_bf16 v[76:79], v[162:165], v[232:235], v[76:79]
	v_mfma_f32_16x16x32_bf16 v[68:71], v[182:185], v[232:235], v[68:71]
	v_mfma_f32_16x16x32_bf16 v[124:127], v[186:189], v[204:207], v[124:127]
	v_mfma_f32_16x16x32_bf16 v[120:123], v[196:199], v[204:207], v[120:123]
	v_mfma_f32_16x16x32_bf16 v[116:119], v[186:189], v[212:215], v[116:119]
	v_mfma_f32_16x16x32_bf16 v[96:99], v[196:199], v[212:215], v[96:99]
	v_mfma_f32_16x16x32_bf16 v[88:91], v[186:189], v[220:223], v[88:91]
	v_mfma_f32_16x16x32_bf16 v[80:83], v[196:199], v[220:223], v[80:83]
	v_mfma_f32_16x16x32_bf16 v[72:75], v[186:189], v[228:231], v[72:75]
	v_mfma_f32_16x16x32_bf16 v[64:67], v[196:199], v[228:231], v[64:67]
	v_mfma_f32_16x16x32_bf16 v[124:127], v[190:193], v[208:211], v[124:127]
	v_mfma_f32_16x16x32_bf16 v[120:123], v[200:203], v[208:211], v[120:123]
	v_mfma_f32_16x16x32_bf16 v[116:119], v[190:193], v[216:219], v[116:119]
	v_mfma_f32_16x16x32_bf16 v[96:99], v[200:203], v[216:219], v[96:99]
	v_mfma_f32_16x16x32_bf16 v[88:91], v[190:193], v[224:227], v[88:91]
	v_mfma_f32_16x16x32_bf16 v[80:83], v[200:203], v[224:227], v[80:83]
	v_mfma_f32_16x16x32_bf16 v[72:75], v[190:193], v[232:235], v[72:75]
	v_mfma_f32_16x16x32_bf16 v[64:67], v[200:203], v[232:235], v[64:67]
	s_barrier
	s_setprio 0
	s_add_i32 s55, s46, s34
	v_lshl_add_u64 v[136:137], s[2:3], 0, v[142:143]
	s_mov_b32 m0, s55
	ds_read_b128 v[204:207], v156 offset:16384
	ds_read_b128 v[208:211], v156 offset:17408
	ds_read_b128 v[212:215], v156 offset:18432
	ds_read_b128 v[216:219], v156 offset:19456
	ds_read_b128 v[220:223], v156 offset:20480
	ds_read_b128 v[224:227], v156 offset:21504
	ds_read_b128 v[228:231], v156 offset:22528
	ds_read_b128 v[232:235], v156 offset:23552
	global_load_lds_dwordx4 v[136:137], off
	s_add_i32 m0, s55, 0x2000
	s_add_u32 s56, s2, 0x40000
	v_lshl_add_u64 v[236:237], s[2:3], 0, v[146:147]
	s_addc_u32 s57, s3, 0
	s_add_i32 s55, s47, s34
	global_load_lds_dwordx4 v[236:237], off
	v_lshl_add_u64 v[238:239], s[56:57], 0, v[142:143]
	s_mov_b32 m0, s55
	v_lshl_add_u64 v[240:241], s[22:23], 0, v[144:145]
	global_load_lds_dwordx4 v[238:239], off
	v_lshl_add_u64 v[238:239], s[56:57], 0, v[146:147]
	s_add_i32 m0, s55, 0x2000
	s_nop 0
	global_load_lds_dwordx4 v[238:239], off
	v_lshl_add_u64 v[238:239], s[22:23], 0, v[140:141]
	s_mov_b32 m0, s37
	s_nop 0
	global_load_lds_dwordx4 v[238:239], off
	s_mov_b32 m0, s38
	s_nop 0
	global_load_lds_dwordx4 v[240:241], off
	s_waitcnt vmcnt(8)
	s_waitcnt lgkmcnt(0)
	s_setprio 1
	s_barrier
	v_mfma_f32_16x16x32_bf16 v[60:63], v[158:161], v[204:207], v[60:63]
	v_mfma_f32_16x16x32_bf16 v[52:55], v[166:169], v[204:207], v[52:55]
	v_mfma_f32_16x16x32_bf16 v[44:47], v[158:161], v[212:215], v[44:47]
	v_mfma_f32_16x16x32_bf16 v[36:39], v[166:169], v[212:215], v[36:39]
	v_mfma_f32_16x16x32_bf16 v[28:31], v[158:161], v[220:223], v[28:31]
	v_mfma_f32_16x16x32_bf16 v[20:23], v[166:169], v[220:223], v[20:23]
	v_mfma_f32_16x16x32_bf16 v[12:15], v[158:161], v[228:231], v[12:15]
	v_mfma_f32_16x16x32_bf16 v[4:7], v[166:169], v[228:231], v[4:7]
	v_mfma_f32_16x16x32_bf16 v[60:63], v[162:165], v[208:211], v[60:63]
	v_mfma_f32_16x16x32_bf16 v[52:55], v[182:185], v[208:211], v[52:55]
	v_mfma_f32_16x16x32_bf16 v[44:47], v[162:165], v[216:219], v[44:47]
	v_mfma_f32_16x16x32_bf16 v[36:39], v[182:185], v[216:219], v[36:39]
	v_mfma_f32_16x16x32_bf16 v[28:31], v[162:165], v[224:227], v[28:31]
	v_mfma_f32_16x16x32_bf16 v[20:23], v[182:185], v[224:227], v[20:23]
	v_mfma_f32_16x16x32_bf16 v[12:15], v[162:165], v[232:235], v[12:15]
	v_mfma_f32_16x16x32_bf16 v[4:7], v[182:185], v[232:235], v[4:7]
	v_mfma_f32_16x16x32_bf16 v[56:59], v[186:189], v[204:207], v[56:59]
	v_mfma_f32_16x16x32_bf16 v[48:51], v[196:199], v[204:207], v[48:51]
	v_mfma_f32_16x16x32_bf16 v[40:43], v[186:189], v[212:215], v[40:43]
	v_mfma_f32_16x16x32_bf16 v[32:35], v[196:199], v[212:215], v[32:35]
	v_mfma_f32_16x16x32_bf16 v[24:27], v[186:189], v[220:223], v[24:27]
	v_mfma_f32_16x16x32_bf16 v[16:19], v[196:199], v[220:223], v[16:19]
	v_mfma_f32_16x16x32_bf16 v[8:11], v[186:189], v[228:231], v[8:11]
	v_mfma_f32_16x16x32_bf16 v[0:3], v[196:199], v[228:231], v[0:3]
	v_mfma_f32_16x16x32_bf16 v[56:59], v[190:193], v[208:211], v[56:59]
	v_mfma_f32_16x16x32_bf16 v[48:51], v[200:203], v[208:211], v[48:51]
	v_mfma_f32_16x16x32_bf16 v[40:43], v[190:193], v[216:219], v[40:43]
	v_mfma_f32_16x16x32_bf16 v[32:35], v[200:203], v[216:219], v[32:35]
	v_mfma_f32_16x16x32_bf16 v[24:27], v[190:193], v[224:227], v[24:27]
	v_mfma_f32_16x16x32_bf16 v[16:19], v[200:203], v[224:227], v[16:19]
	v_mfma_f32_16x16x32_bf16 v[8:11], v[190:193], v[232:235], v[8:11]
	v_mfma_f32_16x16x32_bf16 v[0:3], v[200:203], v[232:235], v[0:3]
	s_barrier
	s_setprio 0
	s_add_i32 s55, 0, 0x18000
	s_add_i32 s56, 0, 0x1c000
	v_add_u32_e32 v182, s55, v139
	v_add_u32_e32 v200, s56, v139
	ds_read_b128 v[158:161], v182
	ds_read_b128 v[162:165], v182 offset:1024
	ds_read_b128 v[166:169], v182 offset:2048
	ds_read_b128 v[182:185], v182 offset:3072
	ds_read_b128 v[186:189], v200
	ds_read_b128 v[190:193], v200 offset:1024
	ds_read_b128 v[196:199], v200 offset:2048
	ds_read_b128 v[200:203], v200 offset:3072
	s_add_u32 s22, s22, 0x40000
	s_addc_u32 s23, s23, 0
	s_mov_b32 m0, s39
	v_lshl_add_u64 v[242:243], s[22:23], 0, v[140:141]
	ds_read_b128 v[204:207], v156 offset:32768
	ds_read_b128 v[208:211], v156 offset:33792
	ds_read_b128 v[212:215], v156 offset:34816
	ds_read_b128 v[216:219], v156 offset:35840
	ds_read_b128 v[220:223], v156 offset:36864
	ds_read_b128 v[224:227], v156 offset:37888
	ds_read_b128 v[228:231], v156 offset:38912
	ds_read_b128 v[232:235], v156 offset:39936
	global_load_lds_dwordx4 v[242:243], off
	v_lshl_add_u64 v[242:243], s[22:23], 0, v[144:145]
	s_mov_b32 m0, s40
	s_nop 0
	global_load_lds_dwordx4 v[242:243], off
	s_waitcnt vmcnt(8)
	s_waitcnt lgkmcnt(0)
	s_setprio 1
	s_barrier
	v_mfma_f32_16x16x32_bf16 v[112:115], v[158:161], v[204:207], v[112:115]
	v_mfma_f32_16x16x32_bf16 v[108:111], v[166:169], v[204:207], v[108:111]
	v_mfma_f32_16x16x32_bf16 v[104:107], v[158:161], v[212:215], v[104:107]
	v_mfma_f32_16x16x32_bf16 v[100:103], v[166:169], v[212:215], v[100:103]
	v_mfma_f32_16x16x32_bf16 v[92:95], v[158:161], v[220:223], v[92:95]
	v_mfma_f32_16x16x32_bf16 v[84:87], v[166:169], v[220:223], v[84:87]
	v_mfma_f32_16x16x32_bf16 v[76:79], v[158:161], v[228:231], v[76:79]
	v_mfma_f32_16x16x32_bf16 v[68:71], v[166:169], v[228:231], v[68:71]
	v_mfma_f32_16x16x32_bf16 v[112:115], v[162:165], v[208:211], v[112:115]
	v_mfma_f32_16x16x32_bf16 v[108:111], v[182:185], v[208:211], v[108:111]
	v_mfma_f32_16x16x32_bf16 v[104:107], v[162:165], v[216:219], v[104:107]
	v_mfma_f32_16x16x32_bf16 v[100:103], v[182:185], v[216:219], v[100:103]
	v_mfma_f32_16x16x32_bf16 v[92:95], v[162:165], v[224:227], v[92:95]
	v_mfma_f32_16x16x32_bf16 v[84:87], v[182:185], v[224:227], v[84:87]
	v_mfma_f32_16x16x32_bf16 v[76:79], v[162:165], v[232:235], v[76:79]
	v_mfma_f32_16x16x32_bf16 v[68:71], v[182:185], v[232:235], v[68:71]
	v_mfma_f32_16x16x32_bf16 v[124:127], v[186:189], v[204:207], v[124:127]
	v_mfma_f32_16x16x32_bf16 v[120:123], v[196:199], v[204:207], v[120:123]
	v_mfma_f32_16x16x32_bf16 v[116:119], v[186:189], v[212:215], v[116:119]
	v_mfma_f32_16x16x32_bf16 v[96:99], v[196:199], v[212:215], v[96:99]
	v_mfma_f32_16x16x32_bf16 v[88:91], v[186:189], v[220:223], v[88:91]
	v_mfma_f32_16x16x32_bf16 v[80:83], v[196:199], v[220:223], v[80:83]
	v_mfma_f32_16x16x32_bf16 v[72:75], v[186:189], v[228:231], v[72:75]
	v_mfma_f32_16x16x32_bf16 v[64:67], v[196:199], v[228:231], v[64:67]
	v_mfma_f32_16x16x32_bf16 v[124:127], v[190:193], v[208:211], v[124:127]
	v_mfma_f32_16x16x32_bf16 v[120:123], v[200:203], v[208:211], v[120:123]
	v_mfma_f32_16x16x32_bf16 v[116:119], v[190:193], v[216:219], v[116:119]
	v_mfma_f32_16x16x32_bf16 v[96:99], v[200:203], v[216:219], v[96:99]
	v_mfma_f32_16x16x32_bf16 v[88:91], v[190:193], v[224:227], v[88:91]
	v_mfma_f32_16x16x32_bf16 v[80:83], v[200:203], v[224:227], v[80:83]
	v_mfma_f32_16x16x32_bf16 v[72:75], v[190:193], v[232:235], v[72:75]
	v_mfma_f32_16x16x32_bf16 v[64:67], v[200:203], v[232:235], v[64:67]
	s_barrier
	s_setprio 0
	s_add_i32 s22, s55, s34
	v_lshl_add_u64 v[136:137], v[136:137], 0, s[8:9]
	s_mov_b32 m0, s22
	ds_read_b128 v[204:207], v156 offset:49152
	ds_read_b128 v[208:211], v156 offset:50176
	ds_read_b128 v[212:215], v156 offset:51200
	ds_read_b128 v[216:219], v156 offset:52224
	ds_read_b128 v[220:223], v156 offset:53248
	ds_read_b128 v[224:227], v156 offset:54272
	ds_read_b128 v[228:231], v156 offset:55296
	ds_read_b128 v[232:235], v156 offset:56320
	global_load_lds_dwordx4 v[136:137], off
	s_add_i32 m0, s22, 0x2000
	s_add_u32 s2, s2, 0x40080
	v_lshl_add_u64 v[136:137], v[236:237], 0, s[8:9]
	s_addc_u32 s3, s3, 0
	s_add_i32 s22, s56, s34
	global_load_lds_dwordx4 v[136:137], off
	v_lshl_add_u64 v[136:137], s[2:3], 0, v[142:143]
	s_mov_b32 m0, s22
	s_nop 0
	global_load_lds_dwordx4 v[136:137], off
	v_lshl_add_u64 v[136:137], s[2:3], 0, v[146:147]
	s_add_i32 m0, s22, 0x2000
	s_nop 0
	global_load_lds_dwordx4 v[136:137], off
	v_lshl_add_u64 v[136:137], v[238:239], 0, s[8:9]
	s_mov_b32 m0, s42
	s_nop 0
	global_load_lds_dwordx4 v[136:137], off
	v_lshl_add_u64 v[136:137], v[240:241], 0, s[8:9]
	s_mov_b32 m0, s43
	s_nop 0
	global_load_lds_dwordx4 v[136:137], off
	s_waitcnt vmcnt(8)
	s_waitcnt lgkmcnt(0)
	s_setprio 1
	s_barrier
	v_mfma_f32_16x16x32_bf16 v[60:63], v[158:161], v[204:207], v[60:63]
	v_mfma_f32_16x16x32_bf16 v[52:55], v[166:169], v[204:207], v[52:55]
	v_mfma_f32_16x16x32_bf16 v[44:47], v[158:161], v[212:215], v[44:47]
	v_mfma_f32_16x16x32_bf16 v[36:39], v[166:169], v[212:215], v[36:39]
	v_mfma_f32_16x16x32_bf16 v[28:31], v[158:161], v[220:223], v[28:31]
	v_mfma_f32_16x16x32_bf16 v[20:23], v[166:169], v[220:223], v[20:23]
	v_mfma_f32_16x16x32_bf16 v[12:15], v[158:161], v[228:231], v[12:15]
	v_mfma_f32_16x16x32_bf16 v[4:7], v[166:169], v[228:231], v[4:7]
	v_mfma_f32_16x16x32_bf16 v[60:63], v[162:165], v[208:211], v[60:63]
	v_mfma_f32_16x16x32_bf16 v[52:55], v[182:185], v[208:211], v[52:55]
	v_mfma_f32_16x16x32_bf16 v[44:47], v[162:165], v[216:219], v[44:47]
	v_mfma_f32_16x16x32_bf16 v[36:39], v[182:185], v[216:219], v[36:39]
	v_mfma_f32_16x16x32_bf16 v[28:31], v[162:165], v[224:227], v[28:31]
	v_mfma_f32_16x16x32_bf16 v[20:23], v[182:185], v[224:227], v[20:23]
	v_mfma_f32_16x16x32_bf16 v[12:15], v[162:165], v[232:235], v[12:15]
	v_mfma_f32_16x16x32_bf16 v[4:7], v[182:185], v[232:235], v[4:7]
	v_mfma_f32_16x16x32_bf16 v[56:59], v[186:189], v[204:207], v[56:59]
	v_mfma_f32_16x16x32_bf16 v[48:51], v[196:199], v[204:207], v[48:51]
	v_mfma_f32_16x16x32_bf16 v[40:43], v[186:189], v[212:215], v[40:43]
	v_mfma_f32_16x16x32_bf16 v[32:35], v[196:199], v[212:215], v[32:35]
	v_mfma_f32_16x16x32_bf16 v[24:27], v[186:189], v[220:223], v[24:27]
	v_mfma_f32_16x16x32_bf16 v[16:19], v[196:199], v[220:223], v[16:19]
	v_mfma_f32_16x16x32_bf16 v[8:11], v[186:189], v[228:231], v[8:11]
	v_mfma_f32_16x16x32_bf16 v[0:3], v[196:199], v[228:231], v[0:3]
	v_mfma_f32_16x16x32_bf16 v[56:59], v[190:193], v[208:211], v[56:59]
	v_mfma_f32_16x16x32_bf16 v[48:51], v[200:203], v[208:211], v[48:51]
	v_mfma_f32_16x16x32_bf16 v[40:43], v[190:193], v[216:219], v[40:43]
	v_mfma_f32_16x16x32_bf16 v[32:35], v[200:203], v[216:219], v[32:35]
	v_mfma_f32_16x16x32_bf16 v[24:27], v[190:193], v[224:227], v[24:27]
	v_mfma_f32_16x16x32_bf16 v[16:19], v[200:203], v[224:227], v[16:19]
	v_mfma_f32_16x16x32_bf16 v[8:11], v[190:193], v[232:235], v[8:11]
	v_mfma_f32_16x16x32_bf16 v[0:3], v[200:203], v[232:235], v[0:3]
	s_barrier
	s_setprio 0
	s_add_i32 s54, s54, 2
	s_add_u32 s14, s14, 0x100
	s_addc_u32 s15, s15, 0
	s_add_u32 s52, s52, 0x100
	s_addc_u32 s53, s53, 0
	s_cmp_gt_u32 s54, 13
	s_cbranch_scc0 .LBB0_368

.LBB0_454:
	s_add_u32 s14, s14, 0xb0080
	s_addc_u32 s15, s15, 0
	s_add_u32 s65, s2, 0x100
	s_addc_u32 s66, s3, 0
	s_mov_b32 s67, -2
	s_waitcnt lgkmcnt(0)
	s_waitcnt vmcnt(0)
	ds_read_b128 v[128:131], v147
	ds_read_b128 v[132:135], v147 offset:1024
	ds_read_b128 v[136:139], v147 offset:2048
	ds_read_b128 v[164:167], v147 offset:3072
	ds_read_b128 v[188:191], v184
	ds_read_b128 v[196:199], v184 offset:1024
	ds_read_b128 v[200:203], v184 offset:2048
	ds_read_b128 v[204:207], v184 offset:3072
	s_add_u32 s2, s14, 0xfff50080
	s_addc_u32 s3, s15, -1
	s_cmp_eq_u32 s67, 40
	s_cselect_b32 s23, s1, s3
	s_cselect_b32 s22, s0, s2
	s_cselect_b32 s3, s31, s66
	s_cselect_b32 s2, s30, s65
	v_lshl_add_u64 v[168:169], s[14:15], 0, v[156:157]
	s_add_i32 m0, s37, 0xc000
	ds_read_b128 v[208:211], v185
	ds_read_b128 v[212:215], v185 offset:1024
	ds_read_b128 v[216:219], v185 offset:2048
	ds_read_b128 v[220:223], v185 offset:3072
	ds_read_b128 v[224:227], v185 offset:4096
	ds_read_b128 v[228:231], v185 offset:5120
	ds_read_b128 v[232:235], v185 offset:6144
	ds_read_b128 v[236:239], v185 offset:7168
	global_load_lds_dwordx4 v[168:169], off
	v_lshl_add_u64 v[168:169], s[14:15], 0, v[158:159]
	s_add_i32 m0, s37, 0xe000
	s_nop 0
	global_load_lds_dwordx4 v[168:169], off
	s_waitcnt vmcnt(8)
	s_waitcnt lgkmcnt(0)
	s_setprio 1
	s_barrier
	v_mfma_f32_16x16x32_bf16 v[124:127], v[128:131], v[208:211], 0
	v_mfma_f32_16x16x32_bf16 v[120:123], v[136:139], v[208:211], 0
	v_mfma_f32_16x16x32_bf16 v[108:111], v[128:131], v[216:219], 0
	v_mfma_f32_16x16x32_bf16 v[104:107], v[136:139], v[216:219], 0
	v_mfma_f32_16x16x32_bf16 v[92:95], v[128:131], v[224:227], 0
	v_mfma_f32_16x16x32_bf16 v[88:91], v[136:139], v[224:227], 0
	v_mfma_f32_16x16x32_bf16 v[76:79], v[128:131], v[232:235], 0
	v_mfma_f32_16x16x32_bf16 v[72:75], v[136:139], v[232:235], 0
	v_mfma_f32_16x16x32_bf16 v[124:127], v[132:135], v[212:215], v[124:127]
	v_mfma_f32_16x16x32_bf16 v[120:123], v[164:167], v[212:215], v[120:123]
	v_mfma_f32_16x16x32_bf16 v[108:111], v[132:135], v[220:223], v[108:111]
	v_mfma_f32_16x16x32_bf16 v[104:107], v[164:167], v[220:223], v[104:107]
	v_mfma_f32_16x16x32_bf16 v[92:95], v[132:135], v[228:231], v[92:95]
	v_mfma_f32_16x16x32_bf16 v[88:91], v[164:167], v[228:231], v[88:91]
	v_mfma_f32_16x16x32_bf16 v[76:79], v[132:135], v[236:239], v[76:79]
	v_mfma_f32_16x16x32_bf16 v[72:75], v[164:167], v[236:239], v[72:75]
	v_mfma_f32_16x16x32_bf16 v[116:119], v[188:191], v[208:211], 0
	v_mfma_f32_16x16x32_bf16 v[112:115], v[200:203], v[208:211], 0
	v_mfma_f32_16x16x32_bf16 v[100:103], v[188:191], v[216:219], 0
	v_mfma_f32_16x16x32_bf16 v[96:99], v[200:203], v[216:219], 0
	v_mfma_f32_16x16x32_bf16 v[84:87], v[188:191], v[224:227], 0
	v_mfma_f32_16x16x32_bf16 v[80:83], v[200:203], v[224:227], 0
	v_mfma_f32_16x16x32_bf16 v[68:71], v[188:191], v[232:235], 0
	v_mfma_f32_16x16x32_bf16 v[64:67], v[200:203], v[232:235], 0
	v_mfma_f32_16x16x32_bf16 v[116:119], v[196:199], v[212:215], v[116:119]
	v_mfma_f32_16x16x32_bf16 v[112:115], v[204:207], v[212:215], v[112:115]
	v_mfma_f32_16x16x32_bf16 v[100:103], v[196:199], v[220:223], v[100:103]
	v_mfma_f32_16x16x32_bf16 v[96:99], v[204:207], v[220:223], v[96:99]
	v_mfma_f32_16x16x32_bf16 v[84:87], v[196:199], v[228:231], v[84:87]
	v_mfma_f32_16x16x32_bf16 v[80:83], v[204:207], v[228:231], v[80:83]
	v_mfma_f32_16x16x32_bf16 v[68:71], v[196:199], v[236:239], v[68:71]
	v_mfma_f32_16x16x32_bf16 v[64:67], v[204:207], v[236:239], v[64:67]
	s_barrier
	s_setprio 0
	s_add_i32 s68, s51, s36
	v_lshl_add_u64 v[168:169], s[2:3], 0, v[150:151]
	s_mov_b32 m0, s68
	ds_read_b128 v[208:211], v185 offset:16384
	ds_read_b128 v[212:215], v185 offset:17408
	ds_read_b128 v[216:219], v185 offset:18432
	ds_read_b128 v[220:223], v185 offset:19456
	ds_read_b128 v[224:227], v185 offset:20480
	ds_read_b128 v[228:231], v185 offset:21504
	ds_read_b128 v[232:235], v185 offset:22528
	ds_read_b128 v[236:239], v185 offset:23552
	global_load_lds_dwordx4 v[168:169], off
	s_add_i32 m0, s68, 0x2000
	s_add_u32 s68, s2, 0xb0000
	v_lshl_add_u64 v[192:193], s[2:3], 0, v[154:155]
	s_addc_u32 s69, s3, 0
	s_add_i32 s70, s52, s36
	global_load_lds_dwordx4 v[192:193], off
	v_lshl_add_u64 v[240:241], s[68:69], 0, v[150:151]
	s_mov_b32 m0, s70
	v_lshl_add_u64 v[242:243], s[22:23], 0, v[152:153]
	global_load_lds_dwordx4 v[240:241], off
	v_lshl_add_u64 v[240:241], s[68:69], 0, v[154:155]
	s_add_i32 m0, s70, 0x2000
	s_nop 0
	global_load_lds_dwordx4 v[240:241], off
	v_lshl_add_u64 v[240:241], s[22:23], 0, v[148:149]
	s_mov_b32 m0, s37
	s_nop 0
	global_load_lds_dwordx4 v[240:241], off
	s_mov_b32 m0, s38
	s_nop 0
	global_load_lds_dwordx4 v[242:243], off
	s_waitcnt vmcnt(8)
	s_waitcnt lgkmcnt(0)
	s_setprio 1
	s_barrier
	v_mfma_f32_16x16x32_bf16 v[60:63], v[128:131], v[208:211], 0
	v_mfma_f32_16x16x32_bf16 v[56:59], v[136:139], v[208:211], 0
	v_mfma_f32_16x16x32_bf16 v[44:47], v[128:131], v[216:219], 0
	v_mfma_f32_16x16x32_bf16 v[40:43], v[136:139], v[216:219], 0
	v_mfma_f32_16x16x32_bf16 v[28:31], v[128:131], v[224:227], 0
	v_mfma_f32_16x16x32_bf16 v[24:27], v[136:139], v[224:227], 0
	v_mfma_f32_16x16x32_bf16 v[12:15], v[128:131], v[232:235], 0
	v_mfma_f32_16x16x32_bf16 v[8:11], v[136:139], v[232:235], 0
	v_mfma_f32_16x16x32_bf16 v[60:63], v[132:135], v[212:215], v[60:63]
	v_mfma_f32_16x16x32_bf16 v[56:59], v[164:167], v[212:215], v[56:59]
	v_mfma_f32_16x16x32_bf16 v[44:47], v[132:135], v[220:223], v[44:47]
	v_mfma_f32_16x16x32_bf16 v[40:43], v[164:167], v[220:223], v[40:43]
	v_mfma_f32_16x16x32_bf16 v[28:31], v[132:135], v[228:231], v[28:31]
	v_mfma_f32_16x16x32_bf16 v[24:27], v[164:167], v[228:231], v[24:27]
	v_mfma_f32_16x16x32_bf16 v[12:15], v[132:135], v[236:239], v[12:15]
	v_mfma_f32_16x16x32_bf16 v[8:11], v[164:167], v[236:239], v[8:11]
	v_mfma_f32_16x16x32_bf16 v[52:55], v[188:191], v[208:211], 0
	v_mfma_f32_16x16x32_bf16 v[48:51], v[200:203], v[208:211], 0
	v_mfma_f32_16x16x32_bf16 v[36:39], v[188:191], v[216:219], 0
	v_mfma_f32_16x16x32_bf16 v[32:35], v[200:203], v[216:219], 0
	v_mfma_f32_16x16x32_bf16 v[20:23], v[188:191], v[224:227], 0
	v_mfma_f32_16x16x32_bf16 v[16:19], v[200:203], v[224:227], 0
	v_mfma_f32_16x16x32_bf16 v[4:7], v[188:191], v[232:235], 0
	v_mfma_f32_16x16x32_bf16 v[0:3], v[200:203], v[232:235], 0
	v_mfma_f32_16x16x32_bf16 v[52:55], v[196:199], v[212:215], v[52:55]
	v_mfma_f32_16x16x32_bf16 v[48:51], v[204:207], v[212:215], v[48:51]
	v_mfma_f32_16x16x32_bf16 v[36:39], v[196:199], v[220:223], v[36:39]
	v_mfma_f32_16x16x32_bf16 v[32:35], v[204:207], v[220:223], v[32:35]
	v_mfma_f32_16x16x32_bf16 v[20:23], v[196:199], v[228:231], v[20:23]
	v_mfma_f32_16x16x32_bf16 v[16:19], v[204:207], v[228:231], v[16:19]
	v_mfma_f32_16x16x32_bf16 v[4:7], v[196:199], v[236:239], v[4:7]
	v_mfma_f32_16x16x32_bf16 v[0:3], v[204:207], v[236:239], v[0:3]
	s_barrier
	s_setprio 0
	s_add_i32 s68, 0, 0x18000
	s_add_i32 s69, 0, 0x1c000
	v_add_u32_e32 v164, s68, v141
	v_add_u32_e32 v187, s69, v141
	ds_read_b128 v[128:131], v164
	ds_read_b128 v[132:135], v164 offset:1024
	ds_read_b128 v[136:139], v164 offset:2048
	ds_read_b128 v[164:167], v164 offset:3072
	ds_read_b128 v[188:191], v187
	ds_read_b128 v[196:199], v187 offset:1024
	ds_read_b128 v[200:203], v187 offset:2048
	ds_read_b128 v[204:207], v187 offset:3072
	s_add_u32 s22, s22, 0xb0000
	s_addc_u32 s23, s23, 0
	s_mov_b32 m0, s39
	v_lshl_add_u64 v[244:245], s[22:23], 0, v[148:149]
	ds_read_b128 v[208:211], v185 offset:32768
	ds_read_b128 v[212:215], v185 offset:33792
	ds_read_b128 v[216:219], v185 offset:34816
	ds_read_b128 v[220:223], v185 offset:35840
	ds_read_b128 v[224:227], v185 offset:36864
	ds_read_b128 v[228:231], v185 offset:37888
	ds_read_b128 v[232:235], v185 offset:38912
	ds_read_b128 v[236:239], v185 offset:39936
	global_load_lds_dwordx4 v[244:245], off
	v_lshl_add_u64 v[244:245], s[22:23], 0, v[152:153]
	s_mov_b32 m0, s40
	s_nop 0
	global_load_lds_dwordx4 v[244:245], off
	s_waitcnt vmcnt(8)
	s_waitcnt lgkmcnt(0)
	s_setprio 1
	s_barrier
	v_mfma_f32_16x16x32_bf16 v[124:127], v[128:131], v[208:211], v[124:127]
	v_mfma_f32_16x16x32_bf16 v[120:123], v[136:139], v[208:211], v[120:123]
	v_mfma_f32_16x16x32_bf16 v[108:111], v[128:131], v[216:219], v[108:111]
	v_mfma_f32_16x16x32_bf16 v[104:107], v[136:139], v[216:219], v[104:107]
	v_mfma_f32_16x16x32_bf16 v[92:95], v[128:131], v[224:227], v[92:95]
	v_mfma_f32_16x16x32_bf16 v[88:91], v[136:139], v[224:227], v[88:91]
	v_mfma_f32_16x16x32_bf16 v[76:79], v[128:131], v[232:235], v[76:79]
	v_mfma_f32_16x16x32_bf16 v[72:75], v[136:139], v[232:235], v[72:75]
	v_mfma_f32_16x16x32_bf16 v[124:127], v[132:135], v[212:215], v[124:127]
	v_mfma_f32_16x16x32_bf16 v[120:123], v[164:167], v[212:215], v[120:123]
	v_mfma_f32_16x16x32_bf16 v[108:111], v[132:135], v[220:223], v[108:111]
	v_mfma_f32_16x16x32_bf16 v[104:107], v[164:167], v[220:223], v[104:107]
	v_mfma_f32_16x16x32_bf16 v[92:95], v[132:135], v[228:231], v[92:95]
	v_mfma_f32_16x16x32_bf16 v[88:91], v[164:167], v[228:231], v[88:91]
	v_mfma_f32_16x16x32_bf16 v[76:79], v[132:135], v[236:239], v[76:79]
	v_mfma_f32_16x16x32_bf16 v[72:75], v[164:167], v[236:239], v[72:75]
	v_mfma_f32_16x16x32_bf16 v[116:119], v[188:191], v[208:211], v[116:119]
	v_mfma_f32_16x16x32_bf16 v[112:115], v[200:203], v[208:211], v[112:115]
	v_mfma_f32_16x16x32_bf16 v[100:103], v[188:191], v[216:219], v[100:103]
	v_mfma_f32_16x16x32_bf16 v[96:99], v[200:203], v[216:219], v[96:99]
	v_mfma_f32_16x16x32_bf16 v[84:87], v[188:191], v[224:227], v[84:87]
	v_mfma_f32_16x16x32_bf16 v[80:83], v[200:203], v[224:227], v[80:83]
	v_mfma_f32_16x16x32_bf16 v[68:71], v[188:191], v[232:235], v[68:71]
	v_mfma_f32_16x16x32_bf16 v[64:67], v[200:203], v[232:235], v[64:67]
	v_mfma_f32_16x16x32_bf16 v[116:119], v[196:199], v[212:215], v[116:119]
	v_mfma_f32_16x16x32_bf16 v[112:115], v[204:207], v[212:215], v[112:115]
	v_mfma_f32_16x16x32_bf16 v[100:103], v[196:199], v[220:223], v[100:103]
	v_mfma_f32_16x16x32_bf16 v[96:99], v[204:207], v[220:223], v[96:99]
	v_mfma_f32_16x16x32_bf16 v[84:87], v[196:199], v[228:231], v[84:87]
	v_mfma_f32_16x16x32_bf16 v[80:83], v[204:207], v[228:231], v[80:83]
	v_mfma_f32_16x16x32_bf16 v[68:71], v[196:199], v[236:239], v[68:71]
	v_mfma_f32_16x16x32_bf16 v[64:67], v[204:207], v[236:239], v[64:67]
	s_barrier
	s_setprio 0
	s_add_i32 s22, s68, s36
	v_lshl_add_u64 v[168:169], v[168:169], 0, s[26:27]
	s_mov_b32 m0, s22
	ds_read_b128 v[208:211], v185 offset:49152
	ds_read_b128 v[212:215], v185 offset:50176
	ds_read_b128 v[216:219], v185 offset:51200
	ds_read_b128 v[220:223], v185 offset:52224
	ds_read_b128 v[224:227], v185 offset:53248
	ds_read_b128 v[228:231], v185 offset:54272
	ds_read_b128 v[232:235], v185 offset:55296
	ds_read_b128 v[236:239], v185 offset:56320
	global_load_lds_dwordx4 v[168:169], off
	s_add_i32 m0, s22, 0x2000
	s_add_u32 s2, s2, 0xb0080
	v_lshl_add_u64 v[168:169], v[192:193], 0, s[26:27]
	s_addc_u32 s3, s3, 0
	s_add_i32 s22, s69, s36
	global_load_lds_dwordx4 v[168:169], off
	v_lshl_add_u64 v[168:169], s[2:3], 0, v[150:151]
	s_mov_b32 m0, s22
	s_nop 0
	global_load_lds_dwordx4 v[168:169], off
	v_lshl_add_u64 v[168:169], s[2:3], 0, v[154:155]
	s_add_i32 m0, s22, 0x2000
	s_nop 0
	global_load_lds_dwordx4 v[168:169], off
	v_lshl_add_u64 v[168:169], v[240:241], 0, s[26:27]
	s_mov_b32 m0, s44
	s_nop 0
	global_load_lds_dwordx4 v[168:169], off
	v_lshl_add_u64 v[168:169], v[242:243], 0, s[26:27]
	s_mov_b32 m0, s45
	s_nop 0
	global_load_lds_dwordx4 v[168:169], off
	s_waitcnt vmcnt(8)
	s_waitcnt lgkmcnt(0)
	s_setprio 1
	s_barrier
	v_mfma_f32_16x16x32_bf16 v[60:63], v[128:131], v[208:211], v[60:63]
	v_mfma_f32_16x16x32_bf16 v[56:59], v[136:139], v[208:211], v[56:59]
	v_mfma_f32_16x16x32_bf16 v[44:47], v[128:131], v[216:219], v[44:47]
	v_mfma_f32_16x16x32_bf16 v[40:43], v[136:139], v[216:219], v[40:43]
	v_mfma_f32_16x16x32_bf16 v[28:31], v[128:131], v[224:227], v[28:31]
	v_mfma_f32_16x16x32_bf16 v[24:27], v[136:139], v[224:227], v[24:27]
	v_mfma_f32_16x16x32_bf16 v[12:15], v[128:131], v[232:235], v[12:15]
	v_mfma_f32_16x16x32_bf16 v[8:11], v[136:139], v[232:235], v[8:11]
	v_mfma_f32_16x16x32_bf16 v[60:63], v[132:135], v[212:215], v[60:63]
	v_mfma_f32_16x16x32_bf16 v[56:59], v[164:167], v[212:215], v[56:59]
	v_mfma_f32_16x16x32_bf16 v[44:47], v[132:135], v[220:223], v[44:47]
	v_mfma_f32_16x16x32_bf16 v[40:43], v[164:167], v[220:223], v[40:43]
	v_mfma_f32_16x16x32_bf16 v[28:31], v[132:135], v[228:231], v[28:31]
	v_mfma_f32_16x16x32_bf16 v[24:27], v[164:167], v[228:231], v[24:27]
	v_mfma_f32_16x16x32_bf16 v[12:15], v[132:135], v[236:239], v[12:15]
	v_mfma_f32_16x16x32_bf16 v[8:11], v[164:167], v[236:239], v[8:11]
	v_mfma_f32_16x16x32_bf16 v[52:55], v[188:191], v[208:211], v[52:55]
	v_mfma_f32_16x16x32_bf16 v[48:51], v[200:203], v[208:211], v[48:51]
	v_mfma_f32_16x16x32_bf16 v[36:39], v[188:191], v[216:219], v[36:39]
	v_mfma_f32_16x16x32_bf16 v[32:35], v[200:203], v[216:219], v[32:35]
	v_mfma_f32_16x16x32_bf16 v[20:23], v[188:191], v[224:227], v[20:23]
	v_mfma_f32_16x16x32_bf16 v[16:19], v[200:203], v[224:227], v[16:19]
	v_mfma_f32_16x16x32_bf16 v[4:7], v[188:191], v[232:235], v[4:7]
	v_mfma_f32_16x16x32_bf16 v[0:3], v[200:203], v[232:235], v[0:3]
	v_mfma_f32_16x16x32_bf16 v[52:55], v[196:199], v[212:215], v[52:55]
	v_mfma_f32_16x16x32_bf16 v[48:51], v[204:207], v[212:215], v[48:51]
	v_mfma_f32_16x16x32_bf16 v[36:39], v[196:199], v[220:223], v[36:39]
	v_mfma_f32_16x16x32_bf16 v[32:35], v[204:207], v[220:223], v[32:35]
	v_mfma_f32_16x16x32_bf16 v[20:23], v[196:199], v[228:231], v[20:23]
	v_mfma_f32_16x16x32_bf16 v[16:19], v[204:207], v[228:231], v[16:19]
	v_mfma_f32_16x16x32_bf16 v[4:7], v[196:199], v[236:239], v[4:7]
	v_mfma_f32_16x16x32_bf16 v[0:3], v[204:207], v[236:239], v[0:3]
	s_barrier
	s_setprio 0
	s_add_i32 s67, s67, 2
	s_add_u32 s14, s14, 0x100
	s_addc_u32 s15, s15, 0
	s_add_u32 s65, s65, 0x100
	s_addc_u32 s66, s66, 0
	s_cmp_gt_u32 s67, 41
	s_cbranch_scc1 .Lgemm_kdone_2
.LBB0_455:
	ds_read_b128 v[128:131], v147
	ds_read_b128 v[132:135], v147 offset:1024
	ds_read_b128 v[136:139], v147 offset:2048
	ds_read_b128 v[164:167], v147 offset:3072
	ds_read_b128 v[188:191], v184
	ds_read_b128 v[196:199], v184 offset:1024
	ds_read_b128 v[200:203], v184 offset:2048
	ds_read_b128 v[204:207], v184 offset:3072
	s_add_u32 s2, s14, 0xfff50080
	s_addc_u32 s3, s15, -1
	s_cmp_eq_u32 s67, 40
	s_cselect_b32 s23, s1, s3
	s_cselect_b32 s22, s0, s2
	s_cselect_b32 s3, s31, s66
	s_cselect_b32 s2, s30, s65
	v_lshl_add_u64 v[168:169], s[14:15], 0, v[156:157]
	s_add_i32 m0, s37, 0xc000
	ds_read_b128 v[208:211], v185
	ds_read_b128 v[212:215], v185 offset:1024
	ds_read_b128 v[216:219], v185 offset:2048
	ds_read_b128 v[220:223], v185 offset:3072
	ds_read_b128 v[224:227], v185 offset:4096
	ds_read_b128 v[228:231], v185 offset:5120
	ds_read_b128 v[232:235], v185 offset:6144
	ds_read_b128 v[236:239], v185 offset:7168
	global_load_lds_dwordx4 v[168:169], off
	v_lshl_add_u64 v[168:169], s[14:15], 0, v[158:159]
	s_add_i32 m0, s37, 0xe000
	s_nop 0
	global_load_lds_dwordx4 v[168:169], off
	s_waitcnt vmcnt(8)
	s_waitcnt lgkmcnt(0)
	s_setprio 1
	s_barrier
	v_mfma_f32_16x16x32_bf16 v[124:127], v[128:131], v[208:211], v[124:127]
	v_mfma_f32_16x16x32_bf16 v[120:123], v[136:139], v[208:211], v[120:123]
	v_mfma_f32_16x16x32_bf16 v[108:111], v[128:131], v[216:219], v[108:111]
	v_mfma_f32_16x16x32_bf16 v[104:107], v[136:139], v[216:219], v[104:107]
	v_mfma_f32_16x16x32_bf16 v[92:95], v[128:131], v[224:227], v[92:95]
	v_mfma_f32_16x16x32_bf16 v[88:91], v[136:139], v[224:227], v[88:91]
	v_mfma_f32_16x16x32_bf16 v[76:79], v[128:131], v[232:235], v[76:79]
	v_mfma_f32_16x16x32_bf16 v[72:75], v[136:139], v[232:235], v[72:75]
	v_mfma_f32_16x16x32_bf16 v[124:127], v[132:135], v[212:215], v[124:127]
	v_mfma_f32_16x16x32_bf16 v[120:123], v[164:167], v[212:215], v[120:123]
	v_mfma_f32_16x16x32_bf16 v[108:111], v[132:135], v[220:223], v[108:111]
	v_mfma_f32_16x16x32_bf16 v[104:107], v[164:167], v[220:223], v[104:107]
	v_mfma_f32_16x16x32_bf16 v[92:95], v[132:135], v[228:231], v[92:95]
	v_mfma_f32_16x16x32_bf16 v[88:91], v[164:167], v[228:231], v[88:91]
	v_mfma_f32_16x16x32_bf16 v[76:79], v[132:135], v[236:239], v[76:79]
	v_mfma_f32_16x16x32_bf16 v[72:75], v[164:167], v[236:239], v[72:75]
	v_mfma_f32_16x16x32_bf16 v[116:119], v[188:191], v[208:211], v[116:119]
	v_mfma_f32_16x16x32_bf16 v[112:115], v[200:203], v[208:211], v[112:115]
	v_mfma_f32_16x16x32_bf16 v[100:103], v[188:191], v[216:219], v[100:103]
	v_mfma_f32_16x16x32_bf16 v[96:99], v[200:203], v[216:219], v[96:99]
	v_mfma_f32_16x16x32_bf16 v[84:87], v[188:191], v[224:227], v[84:87]
	v_mfma_f32_16x16x32_bf16 v[80:83], v[200:203], v[224:227], v[80:83]
	v_mfma_f32_16x16x32_bf16 v[68:71], v[188:191], v[232:235], v[68:71]
	v_mfma_f32_16x16x32_bf16 v[64:67], v[200:203], v[232:235], v[64:67]
	v_mfma_f32_16x16x32_bf16 v[116:119], v[196:199], v[212:215], v[116:119]
	v_mfma_f32_16x16x32_bf16 v[112:115], v[204:207], v[212:215], v[112:115]
	v_mfma_f32_16x16x32_bf16 v[100:103], v[196:199], v[220:223], v[100:103]
	v_mfma_f32_16x16x32_bf16 v[96:99], v[204:207], v[220:223], v[96:99]
	v_mfma_f32_16x16x32_bf16 v[84:87], v[196:199], v[228:231], v[84:87]
	v_mfma_f32_16x16x32_bf16 v[80:83], v[204:207], v[228:231], v[80:83]
	v_mfma_f32_16x16x32_bf16 v[68:71], v[196:199], v[236:239], v[68:71]
	v_mfma_f32_16x16x32_bf16 v[64:67], v[204:207], v[236:239], v[64:67]
	s_barrier
	s_setprio 0
	s_add_i32 s68, s51, s36
	v_lshl_add_u64 v[168:169], s[2:3], 0, v[150:151]
	s_mov_b32 m0, s68
	ds_read_b128 v[208:211], v185 offset:16384
	ds_read_b128 v[212:215], v185 offset:17408
	ds_read_b128 v[216:219], v185 offset:18432
	ds_read_b128 v[220:223], v185 offset:19456
	ds_read_b128 v[224:227], v185 offset:20480
	ds_read_b128 v[228:231], v185 offset:21504
	ds_read_b128 v[232:235], v185 offset:22528
	ds_read_b128 v[236:239], v185 offset:23552
	global_load_lds_dwordx4 v[168:169], off
	s_add_i32 m0, s68, 0x2000
	s_add_u32 s68, s2, 0xb0000
	v_lshl_add_u64 v[192:193], s[2:3], 0, v[154:155]
	s_addc_u32 s69, s3, 0
	s_add_i32 s70, s52, s36
	global_load_lds_dwordx4 v[192:193], off
	v_lshl_add_u64 v[240:241], s[68:69], 0, v[150:151]
	s_mov_b32 m0, s70
	v_lshl_add_u64 v[242:243], s[22:23], 0, v[152:153]
	global_load_lds_dwordx4 v[240:241], off
	v_lshl_add_u64 v[240:241], s[68:69], 0, v[154:155]
	s_add_i32 m0, s70, 0x2000
	s_nop 0
	global_load_lds_dwordx4 v[240:241], off
	v_lshl_add_u64 v[240:241], s[22:23], 0, v[148:149]
	s_mov_b32 m0, s37
	s_nop 0
	global_load_lds_dwordx4 v[240:241], off
	s_mov_b32 m0, s38
	s_nop 0
	global_load_lds_dwordx4 v[242:243], off
	s_waitcnt vmcnt(8)
	s_waitcnt lgkmcnt(0)
	s_setprio 1
	s_barrier
	v_mfma_f32_16x16x32_bf16 v[60:63], v[128:131], v[208:211], v[60:63]
	v_mfma_f32_16x16x32_bf16 v[56:59], v[136:139], v[208:211], v[56:59]
	v_mfma_f32_16x16x32_bf16 v[44:47], v[128:131], v[216:219], v[44:47]
	v_mfma_f32_16x16x32_bf16 v[40:43], v[136:139], v[216:219], v[40:43]
	v_mfma_f32_16x16x32_bf16 v[28:31], v[128:131], v[224:227], v[28:31]
	v_mfma_f32_16x16x32_bf16 v[24:27], v[136:139], v[224:227], v[24:27]
	v_mfma_f32_16x16x32_bf16 v[12:15], v[128:131], v[232:235], v[12:15]
	v_mfma_f32_16x16x32_bf16 v[8:11], v[136:139], v[232:235], v[8:11]
	v_mfma_f32_16x16x32_bf16 v[60:63], v[132:135], v[212:215], v[60:63]
	v_mfma_f32_16x16x32_bf16 v[56:59], v[164:167], v[212:215], v[56:59]
	v_mfma_f32_16x16x32_bf16 v[44:47], v[132:135], v[220:223], v[44:47]
	v_mfma_f32_16x16x32_bf16 v[40:43], v[164:167], v[220:223], v[40:43]
	v_mfma_f32_16x16x32_bf16 v[28:31], v[132:135], v[228:231], v[28:31]
	v_mfma_f32_16x16x32_bf16 v[24:27], v[164:167], v[228:231], v[24:27]
	v_mfma_f32_16x16x32_bf16 v[12:15], v[132:135], v[236:239], v[12:15]
	v_mfma_f32_16x16x32_bf16 v[8:11], v[164:167], v[236:239], v[8:11]
	v_mfma_f32_16x16x32_bf16 v[52:55], v[188:191], v[208:211], v[52:55]
	v_mfma_f32_16x16x32_bf16 v[48:51], v[200:203], v[208:211], v[48:51]
	v_mfma_f32_16x16x32_bf16 v[36:39], v[188:191], v[216:219], v[36:39]
	v_mfma_f32_16x16x32_bf16 v[32:35], v[200:203], v[216:219], v[32:35]
	v_mfma_f32_16x16x32_bf16 v[20:23], v[188:191], v[224:227], v[20:23]
	v_mfma_f32_16x16x32_bf16 v[16:19], v[200:203], v[224:227], v[16:19]
	v_mfma_f32_16x16x32_bf16 v[4:7], v[188:191], v[232:235], v[4:7]
	v_mfma_f32_16x16x32_bf16 v[0:3], v[200:203], v[232:235], v[0:3]
	v_mfma_f32_16x16x32_bf16 v[52:55], v[196:199], v[212:215], v[52:55]
	v_mfma_f32_16x16x32_bf16 v[48:51], v[204:207], v[212:215], v[48:51]
	v_mfma_f32_16x16x32_bf16 v[36:39], v[196:199], v[220:223], v[36:39]
	v_mfma_f32_16x16x32_bf16 v[32:35], v[204:207], v[220:223], v[32:35]
	v_mfma_f32_16x16x32_bf16 v[20:23], v[196:199], v[228:231], v[20:23]
	v_mfma_f32_16x16x32_bf16 v[16:19], v[204:207], v[228:231], v[16:19]
	v_mfma_f32_16x16x32_bf16 v[4:7], v[196:199], v[236:239], v[4:7]
	v_mfma_f32_16x16x32_bf16 v[0:3], v[204:207], v[236:239], v[0:3]
	s_barrier
	s_setprio 0
	s_add_i32 s68, 0, 0x18000
	s_add_i32 s69, 0, 0x1c000
	v_add_u32_e32 v164, s68, v141
	v_add_u32_e32 v187, s69, v141
	ds_read_b128 v[128:131], v164
	ds_read_b128 v[132:135], v164 offset:1024
	ds_read_b128 v[136:139], v164 offset:2048
	ds_read_b128 v[164:167], v164 offset:3072
	ds_read_b128 v[188:191], v187
	ds_read_b128 v[196:199], v187 offset:1024
	ds_read_b128 v[200:203], v187 offset:2048
	ds_read_b128 v[204:207], v187 offset:3072
	s_add_u32 s22, s22, 0xb0000
	s_addc_u32 s23, s23, 0
	s_mov_b32 m0, s39
	v_lshl_add_u64 v[244:245], s[22:23], 0, v[148:149]
	ds_read_b128 v[208:211], v185 offset:32768
	ds_read_b128 v[212:215], v185 offset:33792
	ds_read_b128 v[216:219], v185 offset:34816
	ds_read_b128 v[220:223], v185 offset:35840
	ds_read_b128 v[224:227], v185 offset:36864
	ds_read_b128 v[228:231], v185 offset:37888
	ds_read_b128 v[232:235], v185 offset:38912
	ds_read_b128 v[236:239], v185 offset:39936
	global_load_lds_dwordx4 v[244:245], off
	v_lshl_add_u64 v[244:245], s[22:23], 0, v[152:153]
	s_mov_b32 m0, s40
	s_nop 0
	global_load_lds_dwordx4 v[244:245], off
	s_waitcnt vmcnt(8)
	s_waitcnt lgkmcnt(0)
	s_setprio 1
	s_barrier
	v_mfma_f32_16x16x32_bf16 v[124:127], v[128:131], v[208:211], v[124:127]
	v_mfma_f32_16x16x32_bf16 v[120:123], v[136:139], v[208:211], v[120:123]
	v_mfma_f32_16x16x32_bf16 v[108:111], v[128:131], v[216:219], v[108:111]
	v_mfma_f32_16x16x32_bf16 v[104:107], v[136:139], v[216:219], v[104:107]
	v_mfma_f32_16x16x32_bf16 v[92:95], v[128:131], v[224:227], v[92:95]
	v_mfma_f32_16x16x32_bf16 v[88:91], v[136:139], v[224:227], v[88:91]
	v_mfma_f32_16x16x32_bf16 v[76:79], v[128:131], v[232:235], v[76:79]
	v_mfma_f32_16x16x32_bf16 v[72:75], v[136:139], v[232:235], v[72:75]
	v_mfma_f32_16x16x32_bf16 v[124:127], v[132:135], v[212:215], v[124:127]
	v_mfma_f32_16x16x32_bf16 v[120:123], v[164:167], v[212:215], v[120:123]
	v_mfma_f32_16x16x32_bf16 v[108:111], v[132:135], v[220:223], v[108:111]
	v_mfma_f32_16x16x32_bf16 v[104:107], v[164:167], v[220:223], v[104:107]
	v_mfma_f32_16x16x32_bf16 v[92:95], v[132:135], v[228:231], v[92:95]
	v_mfma_f32_16x16x32_bf16 v[88:91], v[164:167], v[228:231], v[88:91]
	v_mfma_f32_16x16x32_bf16 v[76:79], v[132:135], v[236:239], v[76:79]
	v_mfma_f32_16x16x32_bf16 v[72:75], v[164:167], v[236:239], v[72:75]
	v_mfma_f32_16x16x32_bf16 v[116:119], v[188:191], v[208:211], v[116:119]
	v_mfma_f32_16x16x32_bf16 v[112:115], v[200:203], v[208:211], v[112:115]
	v_mfma_f32_16x16x32_bf16 v[100:103], v[188:191], v[216:219], v[100:103]
	v_mfma_f32_16x16x32_bf16 v[96:99], v[200:203], v[216:219], v[96:99]
	v_mfma_f32_16x16x32_bf16 v[84:87], v[188:191], v[224:227], v[84:87]
	v_mfma_f32_16x16x32_bf16 v[80:83], v[200:203], v[224:227], v[80:83]
	v_mfma_f32_16x16x32_bf16 v[68:71], v[188:191], v[232:235], v[68:71]
	v_mfma_f32_16x16x32_bf16 v[64:67], v[200:203], v[232:235], v[64:67]
	v_mfma_f32_16x16x32_bf16 v[116:119], v[196:199], v[212:215], v[116:119]
	v_mfma_f32_16x16x32_bf16 v[112:115], v[204:207], v[212:215], v[112:115]
	v_mfma_f32_16x16x32_bf16 v[100:103], v[196:199], v[220:223], v[100:103]
	v_mfma_f32_16x16x32_bf16 v[96:99], v[204:207], v[220:223], v[96:99]
	v_mfma_f32_16x16x32_bf16 v[84:87], v[196:199], v[228:231], v[84:87]
	v_mfma_f32_16x16x32_bf16 v[80:83], v[204:207], v[228:231], v[80:83]
	v_mfma_f32_16x16x32_bf16 v[68:71], v[196:199], v[236:239], v[68:71]
	v_mfma_f32_16x16x32_bf16 v[64:67], v[204:207], v[236:239], v[64:67]
	s_barrier
	s_setprio 0
	s_add_i32 s22, s68, s36
	v_lshl_add_u64 v[168:169], v[168:169], 0, s[26:27]
	s_mov_b32 m0, s22
	ds_read_b128 v[208:211], v185 offset:49152
	ds_read_b128 v[212:215], v185 offset:50176
	ds_read_b128 v[216:219], v185 offset:51200
	ds_read_b128 v[220:223], v185 offset:52224
	ds_read_b128 v[224:227], v185 offset:53248
	ds_read_b128 v[228:231], v185 offset:54272
	ds_read_b128 v[232:235], v185 offset:55296
	ds_read_b128 v[236:239], v185 offset:56320
	global_load_lds_dwordx4 v[168:169], off
	s_add_i32 m0, s22, 0x2000
	s_add_u32 s2, s2, 0xb0080
	v_lshl_add_u64 v[168:169], v[192:193], 0, s[26:27]
	s_addc_u32 s3, s3, 0
	s_add_i32 s22, s69, s36
	global_load_lds_dwordx4 v[168:169], off
	v_lshl_add_u64 v[168:169], s[2:3], 0, v[150:151]
	s_mov_b32 m0, s22
	s_nop 0
	global_load_lds_dwordx4 v[168:169], off
	v_lshl_add_u64 v[168:169], s[2:3], 0, v[154:155]
	s_add_i32 m0, s22, 0x2000
	s_nop 0
	global_load_lds_dwordx4 v[168:169], off
	v_lshl_add_u64 v[168:169], v[240:241], 0, s[26:27]
	s_mov_b32 m0, s44
	s_nop 0
	global_load_lds_dwordx4 v[168:169], off
	v_lshl_add_u64 v[168:169], v[242:243], 0, s[26:27]
	s_mov_b32 m0, s45
	s_nop 0
	global_load_lds_dwordx4 v[168:169], off
	s_waitcnt vmcnt(8)
	s_waitcnt lgkmcnt(0)
	s_setprio 1
	s_barrier
	v_mfma_f32_16x16x32_bf16 v[60:63], v[128:131], v[208:211], v[60:63]
	v_mfma_f32_16x16x32_bf16 v[56:59], v[136:139], v[208:211], v[56:59]
	v_mfma_f32_16x16x32_bf16 v[44:47], v[128:131], v[216:219], v[44:47]
	v_mfma_f32_16x16x32_bf16 v[40:43], v[136:139], v[216:219], v[40:43]
	v_mfma_f32_16x16x32_bf16 v[28:31], v[128:131], v[224:227], v[28:31]
	v_mfma_f32_16x16x32_bf16 v[24:27], v[136:139], v[224:227], v[24:27]
	v_mfma_f32_16x16x32_bf16 v[12:15], v[128:131], v[232:235], v[12:15]
	v_mfma_f32_16x16x32_bf16 v[8:11], v[136:139], v[232:235], v[8:11]
	v_mfma_f32_16x16x32_bf16 v[60:63], v[132:135], v[212:215], v[60:63]
	v_mfma_f32_16x16x32_bf16 v[56:59], v[164:167], v[212:215], v[56:59]
	v_mfma_f32_16x16x32_bf16 v[44:47], v[132:135], v[220:223], v[44:47]
	v_mfma_f32_16x16x32_bf16 v[40:43], v[164:167], v[220:223], v[40:43]
	v_mfma_f32_16x16x32_bf16 v[28:31], v[132:135], v[228:231], v[28:31]
	v_mfma_f32_16x16x32_bf16 v[24:27], v[164:167], v[228:231], v[24:27]
	v_mfma_f32_16x16x32_bf16 v[12:15], v[132:135], v[236:239], v[12:15]
	v_mfma_f32_16x16x32_bf16 v[8:11], v[164:167], v[236:239], v[8:11]
	v_mfma_f32_16x16x32_bf16 v[52:55], v[188:191], v[208:211], v[52:55]
	v_mfma_f32_16x16x32_bf16 v[48:51], v[200:203], v[208:211], v[48:51]
	v_mfma_f32_16x16x32_bf16 v[36:39], v[188:191], v[216:219], v[36:39]
	v_mfma_f32_16x16x32_bf16 v[32:35], v[200:203], v[216:219], v[32:35]
	v_mfma_f32_16x16x32_bf16 v[20:23], v[188:191], v[224:227], v[20:23]
	v_mfma_f32_16x16x32_bf16 v[16:19], v[200:203], v[224:227], v[16:19]
	v_mfma_f32_16x16x32_bf16 v[4:7], v[188:191], v[232:235], v[4:7]
	v_mfma_f32_16x16x32_bf16 v[0:3], v[200:203], v[232:235], v[0:3]
	v_mfma_f32_16x16x32_bf16 v[52:55], v[196:199], v[212:215], v[52:55]
	v_mfma_f32_16x16x32_bf16 v[48:51], v[204:207], v[212:215], v[48:51]
	v_mfma_f32_16x16x32_bf16 v[36:39], v[196:199], v[220:223], v[36:39]
	v_mfma_f32_16x16x32_bf16 v[32:35], v[204:207], v[220:223], v[32:35]
	v_mfma_f32_16x16x32_bf16 v[20:23], v[196:199], v[228:231], v[20:23]
	v_mfma_f32_16x16x32_bf16 v[16:19], v[204:207], v[228:231], v[16:19]
	v_mfma_f32_16x16x32_bf16 v[4:7], v[196:199], v[236:239], v[4:7]
	v_mfma_f32_16x16x32_bf16 v[0:3], v[204:207], v[236:239], v[0:3]
	s_barrier
	s_setprio 0
	s_add_i32 s67, s67, 2
	s_add_u32 s14, s14, 0x100
	s_addc_u32 s15, s15, 0
	s_add_u32 s65, s65, 0x100
	s_addc_u32 s66, s66, 0
	s_cmp_gt_u32 s67, 41
	s_cbranch_scc0 .LBB0_455

.LBB0_551:
	s_ashr_i32 s41, s40, 31
	s_lshl_b64 s[22:23], s[40:41], 19
	s_add_u32 s42, s84, s22
	s_addc_u32 s43, s85, s23
	s_and_b64 s[22:23], s[4:5], exec
	s_cselect_b32 s41, s43, s15
	s_cselect_b32 s69, s42, s14
	s_ashr_i32 s39, s38, 31
	s_lshl_b64 s[22:23], s[38:39], 19
	s_add_u32 s44, s34, s22
	s_addc_u32 s45, s35, s23
	s_and_b64 s[22:23], s[4:5], exec
	s_cselect_b32 s39, s45, s3
	s_cselect_b32 s70, s44, s2
	s_add_u32 s14, s14, 0x40080
	s_addc_u32 s15, s15, 0
	s_add_u32 s71, s2, 0x100
	s_addc_u32 s72, s3, 0
	s_mov_b32 s73, -2
	s_waitcnt vmcnt(0)
	ds_read_b128 v[156:159], v155
	ds_read_b128 v[160:163], v155 offset:1024
	ds_read_b128 v[184:187], v155 offset:2048
	ds_read_b128 v[188:191], v155 offset:3072
	ds_read_b128 v[196:199], v166
	ds_read_b128 v[200:203], v166 offset:1024
	ds_read_b128 v[204:207], v166 offset:2048
	ds_read_b128 v[208:211], v166 offset:3072
	s_add_u32 s2, s14, 0xfffc0080
	s_addc_u32 s3, s15, -1
	s_cmp_eq_u32 s73, 12
	s_cselect_b32 s23, s41, s3
	s_cselect_b32 s22, s69, s2
	s_cselect_b32 s3, s39, s72
	s_cselect_b32 s2, s70, s71
	v_lshl_add_u64 v[138:139], s[14:15], 0, v[130:131]
	s_add_i32 m0, s49, 0xc000
	ds_read_b128 v[212:215], v167
	ds_read_b128 v[216:219], v167 offset:1024
	ds_read_b128 v[220:223], v167 offset:2048
	ds_read_b128 v[224:227], v167 offset:3072
	ds_read_b128 v[228:231], v167 offset:4096
	ds_read_b128 v[232:235], v167 offset:5120
	ds_read_b128 v[236:239], v167 offset:6144
	ds_read_b128 v[240:243], v167 offset:7168
	global_load_lds_dwordx4 v[138:139], off
	v_lshl_add_u64 v[138:139], s[14:15], 0, v[132:133]
	s_add_i32 m0, s49, 0xe000
	s_nop 0
	global_load_lds_dwordx4 v[138:139], off
	s_waitcnt vmcnt(8)
	s_waitcnt lgkmcnt(0)
	s_setprio 1
	s_barrier
	v_mfma_f32_16x16x32_bf16 v[124:127], v[156:159], v[212:215], 0
	v_mfma_f32_16x16x32_bf16 v[120:123], v[184:187], v[212:215], 0
	v_mfma_f32_16x16x32_bf16 v[116:119], v[156:159], v[220:223], 0
	v_mfma_f32_16x16x32_bf16 v[112:115], v[184:187], v[220:223], 0
	v_mfma_f32_16x16x32_bf16 v[92:95], v[156:159], v[228:231], 0
	v_mfma_f32_16x16x32_bf16 v[88:91], v[184:187], v[228:231], 0
	v_mfma_f32_16x16x32_bf16 v[76:79], v[156:159], v[236:239], 0
	v_mfma_f32_16x16x32_bf16 v[72:75], v[184:187], v[236:239], 0
	v_mfma_f32_16x16x32_bf16 v[124:127], v[160:163], v[216:219], v[124:127]
	v_mfma_f32_16x16x32_bf16 v[120:123], v[188:191], v[216:219], v[120:123]
	v_mfma_f32_16x16x32_bf16 v[116:119], v[160:163], v[224:227], v[116:119]
	v_mfma_f32_16x16x32_bf16 v[112:115], v[188:191], v[224:227], v[112:115]
	v_mfma_f32_16x16x32_bf16 v[92:95], v[160:163], v[232:235], v[92:95]
	v_mfma_f32_16x16x32_bf16 v[88:91], v[188:191], v[232:235], v[88:91]
	v_mfma_f32_16x16x32_bf16 v[76:79], v[160:163], v[240:243], v[76:79]
	v_mfma_f32_16x16x32_bf16 v[72:75], v[188:191], v[240:243], v[72:75]
	v_mfma_f32_16x16x32_bf16 v[108:111], v[196:199], v[212:215], 0
	v_mfma_f32_16x16x32_bf16 v[104:107], v[204:207], v[212:215], 0
	v_mfma_f32_16x16x32_bf16 v[100:103], v[196:199], v[220:223], 0
	v_mfma_f32_16x16x32_bf16 v[96:99], v[204:207], v[220:223], 0
	v_mfma_f32_16x16x32_bf16 v[84:87], v[196:199], v[228:231], 0
	v_mfma_f32_16x16x32_bf16 v[80:83], v[204:207], v[228:231], 0
	v_mfma_f32_16x16x32_bf16 v[68:71], v[196:199], v[236:239], 0
	v_mfma_f32_16x16x32_bf16 v[64:67], v[204:207], v[236:239], 0
	v_mfma_f32_16x16x32_bf16 v[108:111], v[200:203], v[216:219], v[108:111]
	v_mfma_f32_16x16x32_bf16 v[104:107], v[208:211], v[216:219], v[104:107]
	v_mfma_f32_16x16x32_bf16 v[100:103], v[200:203], v[224:227], v[100:103]
	v_mfma_f32_16x16x32_bf16 v[96:99], v[208:211], v[224:227], v[96:99]
	v_mfma_f32_16x16x32_bf16 v[84:87], v[200:203], v[232:235], v[84:87]
	v_mfma_f32_16x16x32_bf16 v[80:83], v[208:211], v[232:235], v[80:83]
	v_mfma_f32_16x16x32_bf16 v[68:71], v[200:203], v[240:243], v[68:71]
	v_mfma_f32_16x16x32_bf16 v[64:67], v[208:211], v[240:243], v[64:67]
	s_barrier
	s_setprio 0
	s_add_i32 s74, s58, s46
	v_lshl_add_u64 v[138:139], s[2:3], 0, v[142:143]
	s_mov_b32 m0, s74
	ds_read_b128 v[212:215], v167 offset:16384
	ds_read_b128 v[216:219], v167 offset:17408
	ds_read_b128 v[220:223], v167 offset:18432
	ds_read_b128 v[224:227], v167 offset:19456
	ds_read_b128 v[228:231], v167 offset:20480
	ds_read_b128 v[232:235], v167 offset:21504
	ds_read_b128 v[236:239], v167 offset:22528
	ds_read_b128 v[240:243], v167 offset:23552
	global_load_lds_dwordx4 v[138:139], off
	s_add_i32 m0, s74, 0x2000
	s_add_u32 s74, s2, 0x40000
	v_lshl_add_u64 v[164:165], s[2:3], 0, v[146:147]
	s_addc_u32 s75, s3, 0
	s_add_i32 s76, s59, s46
	global_load_lds_dwordx4 v[164:165], off
	v_lshl_add_u64 v[192:193], s[74:75], 0, v[142:143]
	s_mov_b32 m0, s76
	v_lshl_add_u64 v[244:245], s[22:23], 0, v[144:145]
	global_load_lds_dwordx4 v[192:193], off
	v_lshl_add_u64 v[192:193], s[74:75], 0, v[146:147]
	s_add_i32 m0, s76, 0x2000
	s_nop 0
	global_load_lds_dwordx4 v[192:193], off
	v_lshl_add_u64 v[192:193], s[22:23], 0, v[140:141]
	s_mov_b32 m0, s49
	s_nop 0
	global_load_lds_dwordx4 v[192:193], off
	s_mov_b32 m0, s50
	s_nop 0
	global_load_lds_dwordx4 v[244:245], off
	s_waitcnt vmcnt(8)
	s_waitcnt lgkmcnt(0)
	s_setprio 1
	s_barrier
	v_mfma_f32_16x16x32_bf16 v[60:63], v[156:159], v[212:215], 0
	v_mfma_f32_16x16x32_bf16 v[56:59], v[184:187], v[212:215], 0
	v_mfma_f32_16x16x32_bf16 v[44:47], v[156:159], v[220:223], 0
	v_mfma_f32_16x16x32_bf16 v[40:43], v[184:187], v[220:223], 0
	v_mfma_f32_16x16x32_bf16 v[28:31], v[156:159], v[228:231], 0
	v_mfma_f32_16x16x32_bf16 v[24:27], v[184:187], v[228:231], 0
	v_mfma_f32_16x16x32_bf16 v[12:15], v[156:159], v[236:239], 0
	v_mfma_f32_16x16x32_bf16 v[8:11], v[184:187], v[236:239], 0
	v_mfma_f32_16x16x32_bf16 v[60:63], v[160:163], v[216:219], v[60:63]
	v_mfma_f32_16x16x32_bf16 v[56:59], v[188:191], v[216:219], v[56:59]
	v_mfma_f32_16x16x32_bf16 v[44:47], v[160:163], v[224:227], v[44:47]
	v_mfma_f32_16x16x32_bf16 v[40:43], v[188:191], v[224:227], v[40:43]
	v_mfma_f32_16x16x32_bf16 v[28:31], v[160:163], v[232:235], v[28:31]
	v_mfma_f32_16x16x32_bf16 v[24:27], v[188:191], v[232:235], v[24:27]
	v_mfma_f32_16x16x32_bf16 v[12:15], v[160:163], v[240:243], v[12:15]
	v_mfma_f32_16x16x32_bf16 v[8:11], v[188:191], v[240:243], v[8:11]
	v_mfma_f32_16x16x32_bf16 v[52:55], v[196:199], v[212:215], 0
	v_mfma_f32_16x16x32_bf16 v[48:51], v[204:207], v[212:215], 0
	v_mfma_f32_16x16x32_bf16 v[36:39], v[196:199], v[220:223], 0
	v_mfma_f32_16x16x32_bf16 v[32:35], v[204:207], v[220:223], 0
	v_mfma_f32_16x16x32_bf16 v[20:23], v[196:199], v[228:231], 0
	v_mfma_f32_16x16x32_bf16 v[16:19], v[204:207], v[228:231], 0
	v_mfma_f32_16x16x32_bf16 v[4:7], v[196:199], v[236:239], 0
	v_mfma_f32_16x16x32_bf16 v[0:3], v[204:207], v[236:239], 0
	v_mfma_f32_16x16x32_bf16 v[52:55], v[200:203], v[216:219], v[52:55]
	v_mfma_f32_16x16x32_bf16 v[48:51], v[208:211], v[216:219], v[48:51]
	v_mfma_f32_16x16x32_bf16 v[36:39], v[200:203], v[224:227], v[36:39]
	v_mfma_f32_16x16x32_bf16 v[32:35], v[208:211], v[224:227], v[32:35]
	v_mfma_f32_16x16x32_bf16 v[20:23], v[200:203], v[232:235], v[20:23]
	v_mfma_f32_16x16x32_bf16 v[16:19], v[208:211], v[232:235], v[16:19]
	v_mfma_f32_16x16x32_bf16 v[4:7], v[200:203], v[240:243], v[4:7]
	v_mfma_f32_16x16x32_bf16 v[0:3], v[208:211], v[240:243], v[0:3]
	s_barrier
	s_setprio 0
	s_add_i32 s74, 0, 0x18000
	v_add_u32_e32 v128, s74, v151
	s_add_i32 s75, 0, 0x1c000
	ds_read_b128 v[156:159], v128
	ds_read_b128 v[160:163], v128 offset:1024
	ds_read_b128 v[184:187], v128 offset:2048
	ds_read_b128 v[188:191], v128 offset:3072
	v_add_u32_e32 v128, s75, v151
	ds_read_b128 v[196:199], v128
	ds_read_b128 v[200:203], v128 offset:1024
	ds_read_b128 v[204:207], v128 offset:2048
	ds_read_b128 v[208:211], v128 offset:3072
	s_add_u32 s22, s22, 0x40000
	s_addc_u32 s23, s23, 0
	s_mov_b32 m0, s51
	v_lshl_add_u64 v[246:247], s[22:23], 0, v[140:141]
	ds_read_b128 v[212:215], v167 offset:32768
	ds_read_b128 v[216:219], v167 offset:33792
	ds_read_b128 v[220:223], v167 offset:34816
	ds_read_b128 v[224:227], v167 offset:35840
	ds_read_b128 v[228:231], v167 offset:36864
	ds_read_b128 v[232:235], v167 offset:37888
	ds_read_b128 v[236:239], v167 offset:38912
	ds_read_b128 v[240:243], v167 offset:39936
	global_load_lds_dwordx4 v[246:247], off
	v_lshl_add_u64 v[246:247], s[22:23], 0, v[144:145]
	s_mov_b32 m0, s52
	s_nop 0
	global_load_lds_dwordx4 v[246:247], off
	s_waitcnt vmcnt(8)
	s_waitcnt lgkmcnt(0)
	s_setprio 1
	s_barrier
	v_mfma_f32_16x16x32_bf16 v[124:127], v[156:159], v[212:215], v[124:127]
	v_mfma_f32_16x16x32_bf16 v[120:123], v[184:187], v[212:215], v[120:123]
	v_mfma_f32_16x16x32_bf16 v[116:119], v[156:159], v[220:223], v[116:119]
	v_mfma_f32_16x16x32_bf16 v[112:115], v[184:187], v[220:223], v[112:115]
	v_mfma_f32_16x16x32_bf16 v[92:95], v[156:159], v[228:231], v[92:95]
	v_mfma_f32_16x16x32_bf16 v[88:91], v[184:187], v[228:231], v[88:91]
	v_mfma_f32_16x16x32_bf16 v[76:79], v[156:159], v[236:239], v[76:79]
	v_mfma_f32_16x16x32_bf16 v[72:75], v[184:187], v[236:239], v[72:75]
	v_mfma_f32_16x16x32_bf16 v[124:127], v[160:163], v[216:219], v[124:127]
	v_mfma_f32_16x16x32_bf16 v[120:123], v[188:191], v[216:219], v[120:123]
	v_mfma_f32_16x16x32_bf16 v[116:119], v[160:163], v[224:227], v[116:119]
	v_mfma_f32_16x16x32_bf16 v[112:115], v[188:191], v[224:227], v[112:115]
	v_mfma_f32_16x16x32_bf16 v[92:95], v[160:163], v[232:235], v[92:95]
	v_mfma_f32_16x16x32_bf16 v[88:91], v[188:191], v[232:235], v[88:91]
	v_mfma_f32_16x16x32_bf16 v[76:79], v[160:163], v[240:243], v[76:79]
	v_mfma_f32_16x16x32_bf16 v[72:75], v[188:191], v[240:243], v[72:75]
	v_mfma_f32_16x16x32_bf16 v[108:111], v[196:199], v[212:215], v[108:111]
	v_mfma_f32_16x16x32_bf16 v[104:107], v[204:207], v[212:215], v[104:107]
	v_mfma_f32_16x16x32_bf16 v[100:103], v[196:199], v[220:223], v[100:103]
	v_mfma_f32_16x16x32_bf16 v[96:99], v[204:207], v[220:223], v[96:99]
	v_mfma_f32_16x16x32_bf16 v[84:87], v[196:199], v[228:231], v[84:87]
	v_mfma_f32_16x16x32_bf16 v[80:83], v[204:207], v[228:231], v[80:83]
	v_mfma_f32_16x16x32_bf16 v[68:71], v[196:199], v[236:239], v[68:71]
	v_mfma_f32_16x16x32_bf16 v[64:67], v[204:207], v[236:239], v[64:67]
	v_mfma_f32_16x16x32_bf16 v[108:111], v[200:203], v[216:219], v[108:111]
	v_mfma_f32_16x16x32_bf16 v[104:107], v[208:211], v[216:219], v[104:107]
	v_mfma_f32_16x16x32_bf16 v[100:103], v[200:203], v[224:227], v[100:103]
	v_mfma_f32_16x16x32_bf16 v[96:99], v[208:211], v[224:227], v[96:99]
	v_mfma_f32_16x16x32_bf16 v[84:87], v[200:203], v[232:235], v[84:87]
	v_mfma_f32_16x16x32_bf16 v[80:83], v[208:211], v[232:235], v[80:83]
	v_mfma_f32_16x16x32_bf16 v[68:71], v[200:203], v[240:243], v[68:71]
	v_mfma_f32_16x16x32_bf16 v[64:67], v[208:211], v[240:243], v[64:67]
	s_barrier
	s_setprio 0
	s_add_i32 s22, s74, s46
	v_lshl_add_u64 v[138:139], v[138:139], 0, s[24:25]
	s_mov_b32 m0, s22
	ds_read_b128 v[212:215], v167 offset:49152
	ds_read_b128 v[216:219], v167 offset:50176
	ds_read_b128 v[220:223], v167 offset:51200
	ds_read_b128 v[224:227], v167 offset:52224
	ds_read_b128 v[228:231], v167 offset:53248
	ds_read_b128 v[232:235], v167 offset:54272
	ds_read_b128 v[236:239], v167 offset:55296
	ds_read_b128 v[240:243], v167 offset:56320
	global_load_lds_dwordx4 v[138:139], off
	s_add_i32 m0, s22, 0x2000
	s_add_u32 s2, s2, 0x40080
	v_lshl_add_u64 v[138:139], v[164:165], 0, s[24:25]
	s_addc_u32 s3, s3, 0
	s_add_i32 s22, s75, s46
	global_load_lds_dwordx4 v[138:139], off
	v_lshl_add_u64 v[138:139], s[2:3], 0, v[142:143]
	s_mov_b32 m0, s22
	s_nop 0
	global_load_lds_dwordx4 v[138:139], off
	v_lshl_add_u64 v[138:139], s[2:3], 0, v[146:147]
	s_add_i32 m0, s22, 0x2000
	s_nop 0
	global_load_lds_dwordx4 v[138:139], off
	v_lshl_add_u64 v[138:139], v[192:193], 0, s[24:25]
	s_mov_b32 m0, s54
	s_nop 0
	global_load_lds_dwordx4 v[138:139], off
	v_lshl_add_u64 v[138:139], v[244:245], 0, s[24:25]
	s_mov_b32 m0, s55
	s_nop 0
	global_load_lds_dwordx4 v[138:139], off
	s_waitcnt vmcnt(8)
	s_waitcnt lgkmcnt(0)
	s_setprio 1
	s_barrier
	v_mfma_f32_16x16x32_bf16 v[60:63], v[156:159], v[212:215], v[60:63]
	v_mfma_f32_16x16x32_bf16 v[56:59], v[184:187], v[212:215], v[56:59]
	v_mfma_f32_16x16x32_bf16 v[44:47], v[156:159], v[220:223], v[44:47]
	v_mfma_f32_16x16x32_bf16 v[40:43], v[184:187], v[220:223], v[40:43]
	v_mfma_f32_16x16x32_bf16 v[28:31], v[156:159], v[228:231], v[28:31]
	v_mfma_f32_16x16x32_bf16 v[24:27], v[184:187], v[228:231], v[24:27]
	v_mfma_f32_16x16x32_bf16 v[12:15], v[156:159], v[236:239], v[12:15]
	v_mfma_f32_16x16x32_bf16 v[8:11], v[184:187], v[236:239], v[8:11]
	v_mfma_f32_16x16x32_bf16 v[60:63], v[160:163], v[216:219], v[60:63]
	v_mfma_f32_16x16x32_bf16 v[56:59], v[188:191], v[216:219], v[56:59]
	v_mfma_f32_16x16x32_bf16 v[44:47], v[160:163], v[224:227], v[44:47]
	v_mfma_f32_16x16x32_bf16 v[40:43], v[188:191], v[224:227], v[40:43]
	v_mfma_f32_16x16x32_bf16 v[28:31], v[160:163], v[232:235], v[28:31]
	v_mfma_f32_16x16x32_bf16 v[24:27], v[188:191], v[232:235], v[24:27]
	v_mfma_f32_16x16x32_bf16 v[12:15], v[160:163], v[240:243], v[12:15]
	v_mfma_f32_16x16x32_bf16 v[8:11], v[188:191], v[240:243], v[8:11]
	v_mfma_f32_16x16x32_bf16 v[52:55], v[196:199], v[212:215], v[52:55]
	v_mfma_f32_16x16x32_bf16 v[48:51], v[204:207], v[212:215], v[48:51]
	v_mfma_f32_16x16x32_bf16 v[36:39], v[196:199], v[220:223], v[36:39]
	v_mfma_f32_16x16x32_bf16 v[32:35], v[204:207], v[220:223], v[32:35]
	v_mfma_f32_16x16x32_bf16 v[20:23], v[196:199], v[228:231], v[20:23]
	v_mfma_f32_16x16x32_bf16 v[16:19], v[204:207], v[228:231], v[16:19]
	v_mfma_f32_16x16x32_bf16 v[4:7], v[196:199], v[236:239], v[4:7]
	v_mfma_f32_16x16x32_bf16 v[0:3], v[204:207], v[236:239], v[0:3]
	v_mfma_f32_16x16x32_bf16 v[52:55], v[200:203], v[216:219], v[52:55]
	v_mfma_f32_16x16x32_bf16 v[48:51], v[208:211], v[216:219], v[48:51]
	v_mfma_f32_16x16x32_bf16 v[36:39], v[200:203], v[224:227], v[36:39]
	v_mfma_f32_16x16x32_bf16 v[32:35], v[208:211], v[224:227], v[32:35]
	v_mfma_f32_16x16x32_bf16 v[20:23], v[200:203], v[232:235], v[20:23]
	v_mfma_f32_16x16x32_bf16 v[16:19], v[208:211], v[232:235], v[16:19]
	v_mfma_f32_16x16x32_bf16 v[4:7], v[200:203], v[240:243], v[4:7]
	v_mfma_f32_16x16x32_bf16 v[0:3], v[208:211], v[240:243], v[0:3]
	s_barrier
	s_setprio 0
	s_add_i32 s73, s73, 2
	s_add_u32 s14, s14, 0x100
	s_addc_u32 s15, s15, 0
	s_add_u32 s71, s71, 0x100
	s_addc_u32 s72, s72, 0
	s_cmp_gt_u32 s73, 13
	s_cbranch_scc1 .Lgemm_kdone_3
.LBB0_552:
	ds_read_b128 v[156:159], v155
	ds_read_b128 v[160:163], v155 offset:1024
	ds_read_b128 v[184:187], v155 offset:2048
	ds_read_b128 v[188:191], v155 offset:3072
	ds_read_b128 v[196:199], v166
	ds_read_b128 v[200:203], v166 offset:1024
	ds_read_b128 v[204:207], v166 offset:2048
	ds_read_b128 v[208:211], v166 offset:3072
	s_add_u32 s2, s14, 0xfffc0080
	s_addc_u32 s3, s15, -1
	s_cmp_eq_u32 s73, 12
	s_cselect_b32 s23, s41, s3
	s_cselect_b32 s22, s69, s2
	s_cselect_b32 s3, s39, s72
	s_cselect_b32 s2, s70, s71
	v_lshl_add_u64 v[138:139], s[14:15], 0, v[130:131]
	s_add_i32 m0, s49, 0xc000
	ds_read_b128 v[212:215], v167
	ds_read_b128 v[216:219], v167 offset:1024
	ds_read_b128 v[220:223], v167 offset:2048
	ds_read_b128 v[224:227], v167 offset:3072
	ds_read_b128 v[228:231], v167 offset:4096
	ds_read_b128 v[232:235], v167 offset:5120
	ds_read_b128 v[236:239], v167 offset:6144
	ds_read_b128 v[240:243], v167 offset:7168
	global_load_lds_dwordx4 v[138:139], off
	v_lshl_add_u64 v[138:139], s[14:15], 0, v[132:133]
	s_add_i32 m0, s49, 0xe000
	s_nop 0
	global_load_lds_dwordx4 v[138:139], off
	s_waitcnt vmcnt(8)
	s_waitcnt lgkmcnt(0)
	s_setprio 1
	s_barrier
	v_mfma_f32_16x16x32_bf16 v[124:127], v[156:159], v[212:215], v[124:127]
	v_mfma_f32_16x16x32_bf16 v[120:123], v[184:187], v[212:215], v[120:123]
	v_mfma_f32_16x16x32_bf16 v[116:119], v[156:159], v[220:223], v[116:119]
	v_mfma_f32_16x16x32_bf16 v[112:115], v[184:187], v[220:223], v[112:115]
	v_mfma_f32_16x16x32_bf16 v[92:95], v[156:159], v[228:231], v[92:95]
	v_mfma_f32_16x16x32_bf16 v[88:91], v[184:187], v[228:231], v[88:91]
	v_mfma_f32_16x16x32_bf16 v[76:79], v[156:159], v[236:239], v[76:79]
	v_mfma_f32_16x16x32_bf16 v[72:75], v[184:187], v[236:239], v[72:75]
	v_mfma_f32_16x16x32_bf16 v[124:127], v[160:163], v[216:219], v[124:127]
	v_mfma_f32_16x16x32_bf16 v[120:123], v[188:191], v[216:219], v[120:123]
	v_mfma_f32_16x16x32_bf16 v[116:119], v[160:163], v[224:227], v[116:119]
	v_mfma_f32_16x16x32_bf16 v[112:115], v[188:191], v[224:227], v[112:115]
	v_mfma_f32_16x16x32_bf16 v[92:95], v[160:163], v[232:235], v[92:95]
	v_mfma_f32_16x16x32_bf16 v[88:91], v[188:191], v[232:235], v[88:91]
	v_mfma_f32_16x16x32_bf16 v[76:79], v[160:163], v[240:243], v[76:79]
	v_mfma_f32_16x16x32_bf16 v[72:75], v[188:191], v[240:243], v[72:75]
	v_mfma_f32_16x16x32_bf16 v[108:111], v[196:199], v[212:215], v[108:111]
	v_mfma_f32_16x16x32_bf16 v[104:107], v[204:207], v[212:215], v[104:107]
	v_mfma_f32_16x16x32_bf16 v[100:103], v[196:199], v[220:223], v[100:103]
	v_mfma_f32_16x16x32_bf16 v[96:99], v[204:207], v[220:223], v[96:99]
	v_mfma_f32_16x16x32_bf16 v[84:87], v[196:199], v[228:231], v[84:87]
	v_mfma_f32_16x16x32_bf16 v[80:83], v[204:207], v[228:231], v[80:83]
	v_mfma_f32_16x16x32_bf16 v[68:71], v[196:199], v[236:239], v[68:71]
	v_mfma_f32_16x16x32_bf16 v[64:67], v[204:207], v[236:239], v[64:67]
	v_mfma_f32_16x16x32_bf16 v[108:111], v[200:203], v[216:219], v[108:111]
	v_mfma_f32_16x16x32_bf16 v[104:107], v[208:211], v[216:219], v[104:107]
	v_mfma_f32_16x16x32_bf16 v[100:103], v[200:203], v[224:227], v[100:103]
	v_mfma_f32_16x16x32_bf16 v[96:99], v[208:211], v[224:227], v[96:99]
	v_mfma_f32_16x16x32_bf16 v[84:87], v[200:203], v[232:235], v[84:87]
	v_mfma_f32_16x16x32_bf16 v[80:83], v[208:211], v[232:235], v[80:83]
	v_mfma_f32_16x16x32_bf16 v[68:71], v[200:203], v[240:243], v[68:71]
	v_mfma_f32_16x16x32_bf16 v[64:67], v[208:211], v[240:243], v[64:67]
	s_barrier
	s_setprio 0
	s_add_i32 s74, s58, s46
	v_lshl_add_u64 v[138:139], s[2:3], 0, v[142:143]
	s_mov_b32 m0, s74
	ds_read_b128 v[212:215], v167 offset:16384
	ds_read_b128 v[216:219], v167 offset:17408
	ds_read_b128 v[220:223], v167 offset:18432
	ds_read_b128 v[224:227], v167 offset:19456
	ds_read_b128 v[228:231], v167 offset:20480
	ds_read_b128 v[232:235], v167 offset:21504
	ds_read_b128 v[236:239], v167 offset:22528
	ds_read_b128 v[240:243], v167 offset:23552
	global_load_lds_dwordx4 v[138:139], off
	s_add_i32 m0, s74, 0x2000
	s_add_u32 s74, s2, 0x40000
	v_lshl_add_u64 v[164:165], s[2:3], 0, v[146:147]
	s_addc_u32 s75, s3, 0
	s_add_i32 s76, s59, s46
	global_load_lds_dwordx4 v[164:165], off
	v_lshl_add_u64 v[192:193], s[74:75], 0, v[142:143]
	s_mov_b32 m0, s76
	v_lshl_add_u64 v[244:245], s[22:23], 0, v[144:145]
	global_load_lds_dwordx4 v[192:193], off
	v_lshl_add_u64 v[192:193], s[74:75], 0, v[146:147]
	s_add_i32 m0, s76, 0x2000
	s_nop 0
	global_load_lds_dwordx4 v[192:193], off
	v_lshl_add_u64 v[192:193], s[22:23], 0, v[140:141]
	s_mov_b32 m0, s49
	s_nop 0
	global_load_lds_dwordx4 v[192:193], off
	s_mov_b32 m0, s50
	s_nop 0
	global_load_lds_dwordx4 v[244:245], off
	s_waitcnt vmcnt(8)
	s_waitcnt lgkmcnt(0)
	s_setprio 1
	s_barrier
	v_mfma_f32_16x16x32_bf16 v[60:63], v[156:159], v[212:215], v[60:63]
	v_mfma_f32_16x16x32_bf16 v[56:59], v[184:187], v[212:215], v[56:59]
	v_mfma_f32_16x16x32_bf16 v[44:47], v[156:159], v[220:223], v[44:47]
	v_mfma_f32_16x16x32_bf16 v[40:43], v[184:187], v[220:223], v[40:43]
	v_mfma_f32_16x16x32_bf16 v[28:31], v[156:159], v[228:231], v[28:31]
	v_mfma_f32_16x16x32_bf16 v[24:27], v[184:187], v[228:231], v[24:27]
	v_mfma_f32_16x16x32_bf16 v[12:15], v[156:159], v[236:239], v[12:15]
	v_mfma_f32_16x16x32_bf16 v[8:11], v[184:187], v[236:239], v[8:11]
	v_mfma_f32_16x16x32_bf16 v[60:63], v[160:163], v[216:219], v[60:63]
	v_mfma_f32_16x16x32_bf16 v[56:59], v[188:191], v[216:219], v[56:59]
	v_mfma_f32_16x16x32_bf16 v[44:47], v[160:163], v[224:227], v[44:47]
	v_mfma_f32_16x16x32_bf16 v[40:43], v[188:191], v[224:227], v[40:43]
	v_mfma_f32_16x16x32_bf16 v[28:31], v[160:163], v[232:235], v[28:31]
	v_mfma_f32_16x16x32_bf16 v[24:27], v[188:191], v[232:235], v[24:27]
	v_mfma_f32_16x16x32_bf16 v[12:15], v[160:163], v[240:243], v[12:15]
	v_mfma_f32_16x16x32_bf16 v[8:11], v[188:191], v[240:243], v[8:11]
	v_mfma_f32_16x16x32_bf16 v[52:55], v[196:199], v[212:215], v[52:55]
	v_mfma_f32_16x16x32_bf16 v[48:51], v[204:207], v[212:215], v[48:51]
	v_mfma_f32_16x16x32_bf16 v[36:39], v[196:199], v[220:223], v[36:39]
	v_mfma_f32_16x16x32_bf16 v[32:35], v[204:207], v[220:223], v[32:35]
	v_mfma_f32_16x16x32_bf16 v[20:23], v[196:199], v[228:231], v[20:23]
	v_mfma_f32_16x16x32_bf16 v[16:19], v[204:207], v[228:231], v[16:19]
	v_mfma_f32_16x16x32_bf16 v[4:7], v[196:199], v[236:239], v[4:7]
	v_mfma_f32_16x16x32_bf16 v[0:3], v[204:207], v[236:239], v[0:3]
	v_mfma_f32_16x16x32_bf16 v[52:55], v[200:203], v[216:219], v[52:55]
	v_mfma_f32_16x16x32_bf16 v[48:51], v[208:211], v[216:219], v[48:51]
	v_mfma_f32_16x16x32_bf16 v[36:39], v[200:203], v[224:227], v[36:39]
	v_mfma_f32_16x16x32_bf16 v[32:35], v[208:211], v[224:227], v[32:35]
	v_mfma_f32_16x16x32_bf16 v[20:23], v[200:203], v[232:235], v[20:23]
	v_mfma_f32_16x16x32_bf16 v[16:19], v[208:211], v[232:235], v[16:19]
	v_mfma_f32_16x16x32_bf16 v[4:7], v[200:203], v[240:243], v[4:7]
	v_mfma_f32_16x16x32_bf16 v[0:3], v[208:211], v[240:243], v[0:3]
	s_barrier
	s_setprio 0
	s_add_i32 s74, 0, 0x18000
	v_add_u32_e32 v128, s74, v151
	s_add_i32 s75, 0, 0x1c000
	ds_read_b128 v[156:159], v128
	ds_read_b128 v[160:163], v128 offset:1024
	ds_read_b128 v[184:187], v128 offset:2048
	ds_read_b128 v[188:191], v128 offset:3072
	v_add_u32_e32 v128, s75, v151
	ds_read_b128 v[196:199], v128
	ds_read_b128 v[200:203], v128 offset:1024
	ds_read_b128 v[204:207], v128 offset:2048
	ds_read_b128 v[208:211], v128 offset:3072
	s_add_u32 s22, s22, 0x40000
	s_addc_u32 s23, s23, 0
	s_mov_b32 m0, s51
	v_lshl_add_u64 v[246:247], s[22:23], 0, v[140:141]
	ds_read_b128 v[212:215], v167 offset:32768
	ds_read_b128 v[216:219], v167 offset:33792
	ds_read_b128 v[220:223], v167 offset:34816
	ds_read_b128 v[224:227], v167 offset:35840
	ds_read_b128 v[228:231], v167 offset:36864
	ds_read_b128 v[232:235], v167 offset:37888
	ds_read_b128 v[236:239], v167 offset:38912
	ds_read_b128 v[240:243], v167 offset:39936
	global_load_lds_dwordx4 v[246:247], off
	v_lshl_add_u64 v[246:247], s[22:23], 0, v[144:145]
	s_mov_b32 m0, s52
	s_nop 0
	global_load_lds_dwordx4 v[246:247], off
	s_waitcnt vmcnt(8)
	s_waitcnt lgkmcnt(0)
	s_setprio 1
	s_barrier
	v_mfma_f32_16x16x32_bf16 v[124:127], v[156:159], v[212:215], v[124:127]
	v_mfma_f32_16x16x32_bf16 v[120:123], v[184:187], v[212:215], v[120:123]
	v_mfma_f32_16x16x32_bf16 v[116:119], v[156:159], v[220:223], v[116:119]
	v_mfma_f32_16x16x32_bf16 v[112:115], v[184:187], v[220:223], v[112:115]
	v_mfma_f32_16x16x32_bf16 v[92:95], v[156:159], v[228:231], v[92:95]
	v_mfma_f32_16x16x32_bf16 v[88:91], v[184:187], v[228:231], v[88:91]
	v_mfma_f32_16x16x32_bf16 v[76:79], v[156:159], v[236:239], v[76:79]
	v_mfma_f32_16x16x32_bf16 v[72:75], v[184:187], v[236:239], v[72:75]
	v_mfma_f32_16x16x32_bf16 v[124:127], v[160:163], v[216:219], v[124:127]
	v_mfma_f32_16x16x32_bf16 v[120:123], v[188:191], v[216:219], v[120:123]
	v_mfma_f32_16x16x32_bf16 v[116:119], v[160:163], v[224:227], v[116:119]
	v_mfma_f32_16x16x32_bf16 v[112:115], v[188:191], v[224:227], v[112:115]
	v_mfma_f32_16x16x32_bf16 v[92:95], v[160:163], v[232:235], v[92:95]
	v_mfma_f32_16x16x32_bf16 v[88:91], v[188:191], v[232:235], v[88:91]
	v_mfma_f32_16x16x32_bf16 v[76:79], v[160:163], v[240:243], v[76:79]
	v_mfma_f32_16x16x32_bf16 v[72:75], v[188:191], v[240:243], v[72:75]
	v_mfma_f32_16x16x32_bf16 v[108:111], v[196:199], v[212:215], v[108:111]
	v_mfma_f32_16x16x32_bf16 v[104:107], v[204:207], v[212:215], v[104:107]
	v_mfma_f32_16x16x32_bf16 v[100:103], v[196:199], v[220:223], v[100:103]
	v_mfma_f32_16x16x32_bf16 v[96:99], v[204:207], v[220:223], v[96:99]
	v_mfma_f32_16x16x32_bf16 v[84:87], v[196:199], v[228:231], v[84:87]
	v_mfma_f32_16x16x32_bf16 v[80:83], v[204:207], v[228:231], v[80:83]
	v_mfma_f32_16x16x32_bf16 v[68:71], v[196:199], v[236:239], v[68:71]
	v_mfma_f32_16x16x32_bf16 v[64:67], v[204:207], v[236:239], v[64:67]
	v_mfma_f32_16x16x32_bf16 v[108:111], v[200:203], v[216:219], v[108:111]
	v_mfma_f32_16x16x32_bf16 v[104:107], v[208:211], v[216:219], v[104:107]
	v_mfma_f32_16x16x32_bf16 v[100:103], v[200:203], v[224:227], v[100:103]
	v_mfma_f32_16x16x32_bf16 v[96:99], v[208:211], v[224:227], v[96:99]
	v_mfma_f32_16x16x32_bf16 v[84:87], v[200:203], v[232:235], v[84:87]
	v_mfma_f32_16x16x32_bf16 v[80:83], v[208:211], v[232:235], v[80:83]
	v_mfma_f32_16x16x32_bf16 v[68:71], v[200:203], v[240:243], v[68:71]
	v_mfma_f32_16x16x32_bf16 v[64:67], v[208:211], v[240:243], v[64:67]
	s_barrier
	s_setprio 0
	s_add_i32 s22, s74, s46
	v_lshl_add_u64 v[138:139], v[138:139], 0, s[24:25]
	s_mov_b32 m0, s22
	ds_read_b128 v[212:215], v167 offset:49152
	ds_read_b128 v[216:219], v167 offset:50176
	ds_read_b128 v[220:223], v167 offset:51200
	ds_read_b128 v[224:227], v167 offset:52224
	ds_read_b128 v[228:231], v167 offset:53248
	ds_read_b128 v[232:235], v167 offset:54272
	ds_read_b128 v[236:239], v167 offset:55296
	ds_read_b128 v[240:243], v167 offset:56320
	global_load_lds_dwordx4 v[138:139], off
	s_add_i32 m0, s22, 0x2000
	s_add_u32 s2, s2, 0x40080
	v_lshl_add_u64 v[138:139], v[164:165], 0, s[24:25]
	s_addc_u32 s3, s3, 0
	s_add_i32 s22, s75, s46
	global_load_lds_dwordx4 v[138:139], off
	v_lshl_add_u64 v[138:139], s[2:3], 0, v[142:143]
	s_mov_b32 m0, s22
	s_nop 0
	global_load_lds_dwordx4 v[138:139], off
	v_lshl_add_u64 v[138:139], s[2:3], 0, v[146:147]
	s_add_i32 m0, s22, 0x2000
	s_nop 0
	global_load_lds_dwordx4 v[138:139], off
	v_lshl_add_u64 v[138:139], v[192:193], 0, s[24:25]
	s_mov_b32 m0, s54
	s_nop 0
	global_load_lds_dwordx4 v[138:139], off
	v_lshl_add_u64 v[138:139], v[244:245], 0, s[24:25]
	s_mov_b32 m0, s55
	s_nop 0
	global_load_lds_dwordx4 v[138:139], off
	s_waitcnt vmcnt(8)
	s_waitcnt lgkmcnt(0)
	s_setprio 1
	s_barrier
	v_mfma_f32_16x16x32_bf16 v[60:63], v[156:159], v[212:215], v[60:63]
	v_mfma_f32_16x16x32_bf16 v[56:59], v[184:187], v[212:215], v[56:59]
	v_mfma_f32_16x16x32_bf16 v[44:47], v[156:159], v[220:223], v[44:47]
	v_mfma_f32_16x16x32_bf16 v[40:43], v[184:187], v[220:223], v[40:43]
	v_mfma_f32_16x16x32_bf16 v[28:31], v[156:159], v[228:231], v[28:31]
	v_mfma_f32_16x16x32_bf16 v[24:27], v[184:187], v[228:231], v[24:27]
	v_mfma_f32_16x16x32_bf16 v[12:15], v[156:159], v[236:239], v[12:15]
	v_mfma_f32_16x16x32_bf16 v[8:11], v[184:187], v[236:239], v[8:11]
	v_mfma_f32_16x16x32_bf16 v[60:63], v[160:163], v[216:219], v[60:63]
	v_mfma_f32_16x16x32_bf16 v[56:59], v[188:191], v[216:219], v[56:59]
	v_mfma_f32_16x16x32_bf16 v[44:47], v[160:163], v[224:227], v[44:47]
	v_mfma_f32_16x16x32_bf16 v[40:43], v[188:191], v[224:227], v[40:43]
	v_mfma_f32_16x16x32_bf16 v[28:31], v[160:163], v[232:235], v[28:31]
	v_mfma_f32_16x16x32_bf16 v[24:27], v[188:191], v[232:235], v[24:27]
	v_mfma_f32_16x16x32_bf16 v[12:15], v[160:163], v[240:243], v[12:15]
	v_mfma_f32_16x16x32_bf16 v[8:11], v[188:191], v[240:243], v[8:11]
	v_mfma_f32_16x16x32_bf16 v[52:55], v[196:199], v[212:215], v[52:55]
	v_mfma_f32_16x16x32_bf16 v[48:51], v[204:207], v[212:215], v[48:51]
	v_mfma_f32_16x16x32_bf16 v[36:39], v[196:199], v[220:223], v[36:39]
	v_mfma_f32_16x16x32_bf16 v[32:35], v[204:207], v[220:223], v[32:35]
	v_mfma_f32_16x16x32_bf16 v[20:23], v[196:199], v[228:231], v[20:23]
	v_mfma_f32_16x16x32_bf16 v[16:19], v[204:207], v[228:231], v[16:19]
	v_mfma_f32_16x16x32_bf16 v[4:7], v[196:199], v[236:239], v[4:7]
	v_mfma_f32_16x16x32_bf16 v[0:3], v[204:207], v[236:239], v[0:3]
	v_mfma_f32_16x16x32_bf16 v[52:55], v[200:203], v[216:219], v[52:55]
	v_mfma_f32_16x16x32_bf16 v[48:51], v[208:211], v[216:219], v[48:51]
	v_mfma_f32_16x16x32_bf16 v[36:39], v[200:203], v[224:227], v[36:39]
	v_mfma_f32_16x16x32_bf16 v[32:35], v[208:211], v[224:227], v[32:35]
	v_mfma_f32_16x16x32_bf16 v[20:23], v[200:203], v[232:235], v[20:23]
	v_mfma_f32_16x16x32_bf16 v[16:19], v[208:211], v[232:235], v[16:19]
	v_mfma_f32_16x16x32_bf16 v[4:7], v[200:203], v[240:243], v[4:7]
	v_mfma_f32_16x16x32_bf16 v[0:3], v[208:211], v[240:243], v[0:3]
	s_barrier
	s_setprio 0
	s_add_i32 s73, s73, 2
	s_add_u32 s14, s14, 0x100
	s_addc_u32 s15, s15, 0
	s_add_u32 s71, s71, 0x100
	s_addc_u32 s72, s72, 0
	s_cmp_gt_u32 s73, 13
	s_cbranch_scc0 .LBB0_552

.LBB0_724:
	s_ashr_i32 s27, s26, 31
	s_lshl_b64 s[22:23], s[26:27], 19
	s_add_u32 s28, s16, s22
	s_addc_u32 s29, s17, s23
	s_and_b64 s[22:23], s[6:7], exec
	s_cselect_b32 s27, s29, s15
	s_cselect_b32 s59, s28, s14
	s_ashr_i32 s25, s24, 31
	s_lshl_b64 s[22:23], s[24:25], 19
	s_add_u32 s30, s35, s22
	s_addc_u32 s31, s38, s23
	s_and_b64 s[22:23], s[6:7], exec
	s_cselect_b32 s25, s31, s3
	s_cselect_b32 s64, s30, s2
	s_add_u32 s14, s14, 0x40080
	s_addc_u32 s15, s15, 0
	s_add_u32 s65, s2, 0x100
	s_addc_u32 s66, s3, 0
	s_mov_b32 s67, -2
	s_waitcnt lgkmcnt(0)
	s_waitcnt vmcnt(0)
	ds_read_b128 v[128:131], v155
	ds_read_b128 v[132:135], v155 offset:1024
	ds_read_b128 v[136:139], v155 offset:2048
	ds_read_b128 v[164:167], v155 offset:3072
	ds_read_b128 v[188:191], v184
	ds_read_b128 v[196:199], v184 offset:1024
	ds_read_b128 v[200:203], v184 offset:2048
	ds_read_b128 v[204:207], v184 offset:3072
	s_add_u32 s2, s14, 0xfffc0080
	s_addc_u32 s3, s15, -1
	s_cmp_eq_u32 s67, 12
	s_cselect_b32 s23, s27, s3
	s_cselect_b32 s22, s59, s2
	s_cselect_b32 s3, s25, s66
	s_cselect_b32 s2, s64, s65
	v_lshl_add_u64 v[168:169], s[14:15], 0, v[156:157]
	s_add_i32 m0, s37, 0xc000
	ds_read_b128 v[208:211], v185
	ds_read_b128 v[212:215], v185 offset:1024
	ds_read_b128 v[216:219], v185 offset:2048
	ds_read_b128 v[220:223], v185 offset:3072
	ds_read_b128 v[224:227], v185 offset:4096
	ds_read_b128 v[228:231], v185 offset:5120
	ds_read_b128 v[232:235], v185 offset:6144
	ds_read_b128 v[236:239], v185 offset:7168
	global_load_lds_dwordx4 v[168:169], off
	v_lshl_add_u64 v[168:169], s[14:15], 0, v[158:159]
	s_add_i32 m0, s37, 0xe000
	s_nop 0
	global_load_lds_dwordx4 v[168:169], off
	s_waitcnt vmcnt(8)
	s_waitcnt lgkmcnt(0)
	s_setprio 1
	s_barrier
	v_mfma_f32_16x16x32_bf16 v[124:127], v[128:131], v[208:211], 0
	v_mfma_f32_16x16x32_bf16 v[120:123], v[136:139], v[208:211], 0
	v_mfma_f32_16x16x32_bf16 v[108:111], v[128:131], v[216:219], 0
	v_mfma_f32_16x16x32_bf16 v[104:107], v[136:139], v[216:219], 0
	v_mfma_f32_16x16x32_bf16 v[92:95], v[128:131], v[224:227], 0
	v_mfma_f32_16x16x32_bf16 v[88:91], v[136:139], v[224:227], 0
	v_mfma_f32_16x16x32_bf16 v[76:79], v[128:131], v[232:235], 0
	v_mfma_f32_16x16x32_bf16 v[72:75], v[136:139], v[232:235], 0
	v_mfma_f32_16x16x32_bf16 v[124:127], v[132:135], v[212:215], v[124:127]
	v_mfma_f32_16x16x32_bf16 v[120:123], v[164:167], v[212:215], v[120:123]
	v_mfma_f32_16x16x32_bf16 v[108:111], v[132:135], v[220:223], v[108:111]
	v_mfma_f32_16x16x32_bf16 v[104:107], v[164:167], v[220:223], v[104:107]
	v_mfma_f32_16x16x32_bf16 v[92:95], v[132:135], v[228:231], v[92:95]
	v_mfma_f32_16x16x32_bf16 v[88:91], v[164:167], v[228:231], v[88:91]
	v_mfma_f32_16x16x32_bf16 v[76:79], v[132:135], v[236:239], v[76:79]
	v_mfma_f32_16x16x32_bf16 v[72:75], v[164:167], v[236:239], v[72:75]
	v_mfma_f32_16x16x32_bf16 v[116:119], v[188:191], v[208:211], 0
	v_mfma_f32_16x16x32_bf16 v[112:115], v[200:203], v[208:211], 0
	v_mfma_f32_16x16x32_bf16 v[100:103], v[188:191], v[216:219], 0
	v_mfma_f32_16x16x32_bf16 v[96:99], v[200:203], v[216:219], 0
	v_mfma_f32_16x16x32_bf16 v[84:87], v[188:191], v[224:227], 0
	v_mfma_f32_16x16x32_bf16 v[80:83], v[200:203], v[224:227], 0
	v_mfma_f32_16x16x32_bf16 v[68:71], v[188:191], v[232:235], 0
	v_mfma_f32_16x16x32_bf16 v[64:67], v[200:203], v[232:235], 0
	v_mfma_f32_16x16x32_bf16 v[116:119], v[196:199], v[212:215], v[116:119]
	v_mfma_f32_16x16x32_bf16 v[112:115], v[204:207], v[212:215], v[112:115]
	v_mfma_f32_16x16x32_bf16 v[100:103], v[196:199], v[220:223], v[100:103]
	v_mfma_f32_16x16x32_bf16 v[96:99], v[204:207], v[220:223], v[96:99]
	v_mfma_f32_16x16x32_bf16 v[84:87], v[196:199], v[228:231], v[84:87]
	v_mfma_f32_16x16x32_bf16 v[80:83], v[204:207], v[228:231], v[80:83]
	v_mfma_f32_16x16x32_bf16 v[68:71], v[196:199], v[236:239], v[68:71]
	v_mfma_f32_16x16x32_bf16 v[64:67], v[204:207], v[236:239], v[64:67]
	s_barrier
	s_setprio 0
	s_add_i32 s68, s52, s39
	v_lshl_add_u64 v[168:169], s[2:3], 0, v[142:143]
	s_mov_b32 m0, s68
	ds_read_b128 v[208:211], v185 offset:16384
	ds_read_b128 v[212:215], v185 offset:17408
	ds_read_b128 v[216:219], v185 offset:18432
	ds_read_b128 v[220:223], v185 offset:19456
	ds_read_b128 v[224:227], v185 offset:20480
	ds_read_b128 v[228:231], v185 offset:21504
	ds_read_b128 v[232:235], v185 offset:22528
	ds_read_b128 v[236:239], v185 offset:23552
	global_load_lds_dwordx4 v[168:169], off
	s_add_i32 m0, s68, 0x2000
	s_add_u32 s68, s2, 0x40000
	v_lshl_add_u64 v[192:193], s[2:3], 0, v[146:147]
	s_addc_u32 s69, s3, 0
	s_add_i32 s70, s53, s39
	global_load_lds_dwordx4 v[192:193], off
	v_lshl_add_u64 v[240:241], s[68:69], 0, v[142:143]
	s_mov_b32 m0, s70
	v_lshl_add_u64 v[242:243], s[22:23], 0, v[144:145]
	global_load_lds_dwordx4 v[240:241], off
	v_lshl_add_u64 v[240:241], s[68:69], 0, v[146:147]
	s_add_i32 m0, s70, 0x2000
	s_nop 0
	global_load_lds_dwordx4 v[240:241], off
	v_lshl_add_u64 v[240:241], s[22:23], 0, v[140:141]
	s_mov_b32 m0, s37
	s_nop 0
	global_load_lds_dwordx4 v[240:241], off
	s_mov_b32 m0, s40
	s_nop 0
	global_load_lds_dwordx4 v[242:243], off
	s_waitcnt vmcnt(8)
	s_waitcnt lgkmcnt(0)
	s_setprio 1
	s_barrier
	v_mfma_f32_16x16x32_bf16 v[60:63], v[128:131], v[208:211], 0
	v_mfma_f32_16x16x32_bf16 v[56:59], v[136:139], v[208:211], 0
	v_mfma_f32_16x16x32_bf16 v[44:47], v[128:131], v[216:219], 0
	v_mfma_f32_16x16x32_bf16 v[40:43], v[136:139], v[216:219], 0
	v_mfma_f32_16x16x32_bf16 v[28:31], v[128:131], v[224:227], 0
	v_mfma_f32_16x16x32_bf16 v[24:27], v[136:139], v[224:227], 0
	v_mfma_f32_16x16x32_bf16 v[12:15], v[128:131], v[232:235], 0
	v_mfma_f32_16x16x32_bf16 v[8:11], v[136:139], v[232:235], 0
	v_mfma_f32_16x16x32_bf16 v[60:63], v[132:135], v[212:215], v[60:63]
	v_mfma_f32_16x16x32_bf16 v[56:59], v[164:167], v[212:215], v[56:59]
	v_mfma_f32_16x16x32_bf16 v[44:47], v[132:135], v[220:223], v[44:47]
	v_mfma_f32_16x16x32_bf16 v[40:43], v[164:167], v[220:223], v[40:43]
	v_mfma_f32_16x16x32_bf16 v[28:31], v[132:135], v[228:231], v[28:31]
	v_mfma_f32_16x16x32_bf16 v[24:27], v[164:167], v[228:231], v[24:27]
	v_mfma_f32_16x16x32_bf16 v[12:15], v[132:135], v[236:239], v[12:15]
	v_mfma_f32_16x16x32_bf16 v[8:11], v[164:167], v[236:239], v[8:11]
	v_mfma_f32_16x16x32_bf16 v[52:55], v[188:191], v[208:211], 0
	v_mfma_f32_16x16x32_bf16 v[48:51], v[200:203], v[208:211], 0
	v_mfma_f32_16x16x32_bf16 v[36:39], v[188:191], v[216:219], 0
	v_mfma_f32_16x16x32_bf16 v[32:35], v[200:203], v[216:219], 0
	v_mfma_f32_16x16x32_bf16 v[20:23], v[188:191], v[224:227], 0
	v_mfma_f32_16x16x32_bf16 v[16:19], v[200:203], v[224:227], 0
	v_mfma_f32_16x16x32_bf16 v[4:7], v[188:191], v[232:235], 0
	v_mfma_f32_16x16x32_bf16 v[0:3], v[200:203], v[232:235], 0
	v_mfma_f32_16x16x32_bf16 v[52:55], v[196:199], v[212:215], v[52:55]
	v_mfma_f32_16x16x32_bf16 v[48:51], v[204:207], v[212:215], v[48:51]
	v_mfma_f32_16x16x32_bf16 v[36:39], v[196:199], v[220:223], v[36:39]
	v_mfma_f32_16x16x32_bf16 v[32:35], v[204:207], v[220:223], v[32:35]
	v_mfma_f32_16x16x32_bf16 v[20:23], v[196:199], v[228:231], v[20:23]
	v_mfma_f32_16x16x32_bf16 v[16:19], v[204:207], v[228:231], v[16:19]
	v_mfma_f32_16x16x32_bf16 v[4:7], v[196:199], v[236:239], v[4:7]
	v_mfma_f32_16x16x32_bf16 v[0:3], v[204:207], v[236:239], v[0:3]
	s_barrier
	s_setprio 0
	s_add_i32 s68, 0, 0x18000
	s_add_i32 s69, 0, 0x1c000
	v_add_u32_e32 v164, s68, v149
	v_add_u32_e32 v187, s69, v149
	ds_read_b128 v[128:131], v164
	ds_read_b128 v[132:135], v164 offset:1024
	ds_read_b128 v[136:139], v164 offset:2048
	ds_read_b128 v[164:167], v164 offset:3072
	ds_read_b128 v[188:191], v187
	ds_read_b128 v[196:199], v187 offset:1024
	ds_read_b128 v[200:203], v187 offset:2048
	ds_read_b128 v[204:207], v187 offset:3072
	s_add_u32 s22, s22, 0x40000
	s_addc_u32 s23, s23, 0
	s_mov_b32 m0, s41
	v_lshl_add_u64 v[244:245], s[22:23], 0, v[140:141]
	ds_read_b128 v[208:211], v185 offset:32768
	ds_read_b128 v[212:215], v185 offset:33792
	ds_read_b128 v[216:219], v185 offset:34816
	ds_read_b128 v[220:223], v185 offset:35840
	ds_read_b128 v[224:227], v185 offset:36864
	ds_read_b128 v[228:231], v185 offset:37888
	ds_read_b128 v[232:235], v185 offset:38912
	ds_read_b128 v[236:239], v185 offset:39936
	global_load_lds_dwordx4 v[244:245], off
	v_lshl_add_u64 v[244:245], s[22:23], 0, v[144:145]
	s_mov_b32 m0, s42
	s_nop 0
	global_load_lds_dwordx4 v[244:245], off
	s_waitcnt vmcnt(8)
	s_waitcnt lgkmcnt(0)
	s_setprio 1
	s_barrier
	v_mfma_f32_16x16x32_bf16 v[124:127], v[128:131], v[208:211], v[124:127]
	v_mfma_f32_16x16x32_bf16 v[120:123], v[136:139], v[208:211], v[120:123]
	v_mfma_f32_16x16x32_bf16 v[108:111], v[128:131], v[216:219], v[108:111]
	v_mfma_f32_16x16x32_bf16 v[104:107], v[136:139], v[216:219], v[104:107]
	v_mfma_f32_16x16x32_bf16 v[92:95], v[128:131], v[224:227], v[92:95]
	v_mfma_f32_16x16x32_bf16 v[88:91], v[136:139], v[224:227], v[88:91]
	v_mfma_f32_16x16x32_bf16 v[76:79], v[128:131], v[232:235], v[76:79]
	v_mfma_f32_16x16x32_bf16 v[72:75], v[136:139], v[232:235], v[72:75]
	v_mfma_f32_16x16x32_bf16 v[124:127], v[132:135], v[212:215], v[124:127]
	v_mfma_f32_16x16x32_bf16 v[120:123], v[164:167], v[212:215], v[120:123]
	v_mfma_f32_16x16x32_bf16 v[108:111], v[132:135], v[220:223], v[108:111]
	v_mfma_f32_16x16x32_bf16 v[104:107], v[164:167], v[220:223], v[104:107]
	v_mfma_f32_16x16x32_bf16 v[92:95], v[132:135], v[228:231], v[92:95]
	v_mfma_f32_16x16x32_bf16 v[88:91], v[164:167], v[228:231], v[88:91]
	v_mfma_f32_16x16x32_bf16 v[76:79], v[132:135], v[236:239], v[76:79]
	v_mfma_f32_16x16x32_bf16 v[72:75], v[164:167], v[236:239], v[72:75]
	v_mfma_f32_16x16x32_bf16 v[116:119], v[188:191], v[208:211], v[116:119]
	v_mfma_f32_16x16x32_bf16 v[112:115], v[200:203], v[208:211], v[112:115]
	v_mfma_f32_16x16x32_bf16 v[100:103], v[188:191], v[216:219], v[100:103]
	v_mfma_f32_16x16x32_bf16 v[96:99], v[200:203], v[216:219], v[96:99]
	v_mfma_f32_16x16x32_bf16 v[84:87], v[188:191], v[224:227], v[84:87]
	v_mfma_f32_16x16x32_bf16 v[80:83], v[200:203], v[224:227], v[80:83]
	v_mfma_f32_16x16x32_bf16 v[68:71], v[188:191], v[232:235], v[68:71]
	v_mfma_f32_16x16x32_bf16 v[64:67], v[200:203], v[232:235], v[64:67]
	v_mfma_f32_16x16x32_bf16 v[116:119], v[196:199], v[212:215], v[116:119]
	v_mfma_f32_16x16x32_bf16 v[112:115], v[204:207], v[212:215], v[112:115]
	v_mfma_f32_16x16x32_bf16 v[100:103], v[196:199], v[220:223], v[100:103]
	v_mfma_f32_16x16x32_bf16 v[96:99], v[204:207], v[220:223], v[96:99]
	v_mfma_f32_16x16x32_bf16 v[84:87], v[196:199], v[228:231], v[84:87]
	v_mfma_f32_16x16x32_bf16 v[80:83], v[204:207], v[228:231], v[80:83]
	v_mfma_f32_16x16x32_bf16 v[68:71], v[196:199], v[236:239], v[68:71]
	v_mfma_f32_16x16x32_bf16 v[64:67], v[204:207], v[236:239], v[64:67]
	s_barrier
	s_setprio 0
	s_add_i32 s22, s68, s39
	v_lshl_add_u64 v[168:169], v[168:169], 0, s[18:19]
	s_mov_b32 m0, s22
	ds_read_b128 v[208:211], v185 offset:49152
	ds_read_b128 v[212:215], v185 offset:50176
	ds_read_b128 v[216:219], v185 offset:51200
	ds_read_b128 v[220:223], v185 offset:52224
	ds_read_b128 v[224:227], v185 offset:53248
	ds_read_b128 v[228:231], v185 offset:54272
	ds_read_b128 v[232:235], v185 offset:55296
	ds_read_b128 v[236:239], v185 offset:56320
	global_load_lds_dwordx4 v[168:169], off
	s_add_i32 m0, s22, 0x2000
	s_add_u32 s2, s2, 0x40080
	v_lshl_add_u64 v[168:169], v[192:193], 0, s[18:19]
	s_addc_u32 s3, s3, 0
	s_add_i32 s22, s69, s39
	global_load_lds_dwordx4 v[168:169], off
	v_lshl_add_u64 v[168:169], s[2:3], 0, v[142:143]
	s_mov_b32 m0, s22
	s_nop 0
	global_load_lds_dwordx4 v[168:169], off
	v_lshl_add_u64 v[168:169], s[2:3], 0, v[146:147]
	s_add_i32 m0, s22, 0x2000
	s_nop 0
	global_load_lds_dwordx4 v[168:169], off
	v_lshl_add_u64 v[168:169], v[240:241], 0, s[18:19]
	s_mov_b32 m0, s46
	s_nop 0
	global_load_lds_dwordx4 v[168:169], off
	v_lshl_add_u64 v[168:169], v[242:243], 0, s[18:19]
	s_mov_b32 m0, s47
	s_nop 0
	global_load_lds_dwordx4 v[168:169], off
	s_waitcnt vmcnt(8)
	s_waitcnt lgkmcnt(0)
	s_setprio 1
	s_barrier
	v_mfma_f32_16x16x32_bf16 v[60:63], v[128:131], v[208:211], v[60:63]
	v_mfma_f32_16x16x32_bf16 v[56:59], v[136:139], v[208:211], v[56:59]
	v_mfma_f32_16x16x32_bf16 v[44:47], v[128:131], v[216:219], v[44:47]
	v_mfma_f32_16x16x32_bf16 v[40:43], v[136:139], v[216:219], v[40:43]
	v_mfma_f32_16x16x32_bf16 v[28:31], v[128:131], v[224:227], v[28:31]
	v_mfma_f32_16x16x32_bf16 v[24:27], v[136:139], v[224:227], v[24:27]
	v_mfma_f32_16x16x32_bf16 v[12:15], v[128:131], v[232:235], v[12:15]
	v_mfma_f32_16x16x32_bf16 v[8:11], v[136:139], v[232:235], v[8:11]
	v_mfma_f32_16x16x32_bf16 v[60:63], v[132:135], v[212:215], v[60:63]
	v_mfma_f32_16x16x32_bf16 v[56:59], v[164:167], v[212:215], v[56:59]
	v_mfma_f32_16x16x32_bf16 v[44:47], v[132:135], v[220:223], v[44:47]
	v_mfma_f32_16x16x32_bf16 v[40:43], v[164:167], v[220:223], v[40:43]
	v_mfma_f32_16x16x32_bf16 v[28:31], v[132:135], v[228:231], v[28:31]
	v_mfma_f32_16x16x32_bf16 v[24:27], v[164:167], v[228:231], v[24:27]
	v_mfma_f32_16x16x32_bf16 v[12:15], v[132:135], v[236:239], v[12:15]
	v_mfma_f32_16x16x32_bf16 v[8:11], v[164:167], v[236:239], v[8:11]
	v_mfma_f32_16x16x32_bf16 v[52:55], v[188:191], v[208:211], v[52:55]
	v_mfma_f32_16x16x32_bf16 v[48:51], v[200:203], v[208:211], v[48:51]
	v_mfma_f32_16x16x32_bf16 v[36:39], v[188:191], v[216:219], v[36:39]
	v_mfma_f32_16x16x32_bf16 v[32:35], v[200:203], v[216:219], v[32:35]
	v_mfma_f32_16x16x32_bf16 v[20:23], v[188:191], v[224:227], v[20:23]
	v_mfma_f32_16x16x32_bf16 v[16:19], v[200:203], v[224:227], v[16:19]
	v_mfma_f32_16x16x32_bf16 v[4:7], v[188:191], v[232:235], v[4:7]
	v_mfma_f32_16x16x32_bf16 v[0:3], v[200:203], v[232:235], v[0:3]
	v_mfma_f32_16x16x32_bf16 v[52:55], v[196:199], v[212:215], v[52:55]
	v_mfma_f32_16x16x32_bf16 v[48:51], v[204:207], v[212:215], v[48:51]
	v_mfma_f32_16x16x32_bf16 v[36:39], v[196:199], v[220:223], v[36:39]
	v_mfma_f32_16x16x32_bf16 v[32:35], v[204:207], v[220:223], v[32:35]
	v_mfma_f32_16x16x32_bf16 v[20:23], v[196:199], v[228:231], v[20:23]
	v_mfma_f32_16x16x32_bf16 v[16:19], v[204:207], v[228:231], v[16:19]
	v_mfma_f32_16x16x32_bf16 v[4:7], v[196:199], v[236:239], v[4:7]
	v_mfma_f32_16x16x32_bf16 v[0:3], v[204:207], v[236:239], v[0:3]
	s_barrier
	s_setprio 0
	s_add_i32 s67, s67, 2
	s_add_u32 s14, s14, 0x100
	s_addc_u32 s15, s15, 0
	s_add_u32 s65, s65, 0x100
	s_addc_u32 s66, s66, 0
	s_cmp_gt_u32 s67, 13
	s_cbranch_scc1 .Lgemm_kdone_4
.LBB0_725:
	ds_read_b128 v[128:131], v155
	ds_read_b128 v[132:135], v155 offset:1024
	ds_read_b128 v[136:139], v155 offset:2048
	ds_read_b128 v[164:167], v155 offset:3072
	ds_read_b128 v[188:191], v184
	ds_read_b128 v[196:199], v184 offset:1024
	ds_read_b128 v[200:203], v184 offset:2048
	ds_read_b128 v[204:207], v184 offset:3072
	s_add_u32 s2, s14, 0xfffc0080
	s_addc_u32 s3, s15, -1
	s_cmp_eq_u32 s67, 12
	s_cselect_b32 s23, s27, s3
	s_cselect_b32 s22, s59, s2
	s_cselect_b32 s3, s25, s66
	s_cselect_b32 s2, s64, s65
	v_lshl_add_u64 v[168:169], s[14:15], 0, v[156:157]
	s_add_i32 m0, s37, 0xc000
	ds_read_b128 v[208:211], v185
	ds_read_b128 v[212:215], v185 offset:1024
	ds_read_b128 v[216:219], v185 offset:2048
	ds_read_b128 v[220:223], v185 offset:3072
	ds_read_b128 v[224:227], v185 offset:4096
	ds_read_b128 v[228:231], v185 offset:5120
	ds_read_b128 v[232:235], v185 offset:6144
	ds_read_b128 v[236:239], v185 offset:7168
	global_load_lds_dwordx4 v[168:169], off
	v_lshl_add_u64 v[168:169], s[14:15], 0, v[158:159]
	s_add_i32 m0, s37, 0xe000
	s_nop 0
	global_load_lds_dwordx4 v[168:169], off
	s_waitcnt vmcnt(8)
	s_waitcnt lgkmcnt(0)
	s_setprio 1
	s_barrier
	v_mfma_f32_16x16x32_bf16 v[124:127], v[128:131], v[208:211], v[124:127]
	v_mfma_f32_16x16x32_bf16 v[120:123], v[136:139], v[208:211], v[120:123]
	v_mfma_f32_16x16x32_bf16 v[108:111], v[128:131], v[216:219], v[108:111]
	v_mfma_f32_16x16x32_bf16 v[104:107], v[136:139], v[216:219], v[104:107]
	v_mfma_f32_16x16x32_bf16 v[92:95], v[128:131], v[224:227], v[92:95]
	v_mfma_f32_16x16x32_bf16 v[88:91], v[136:139], v[224:227], v[88:91]
	v_mfma_f32_16x16x32_bf16 v[76:79], v[128:131], v[232:235], v[76:79]
	v_mfma_f32_16x16x32_bf16 v[72:75], v[136:139], v[232:235], v[72:75]
	v_mfma_f32_16x16x32_bf16 v[124:127], v[132:135], v[212:215], v[124:127]
	v_mfma_f32_16x16x32_bf16 v[120:123], v[164:167], v[212:215], v[120:123]
	v_mfma_f32_16x16x32_bf16 v[108:111], v[132:135], v[220:223], v[108:111]
	v_mfma_f32_16x16x32_bf16 v[104:107], v[164:167], v[220:223], v[104:107]
	v_mfma_f32_16x16x32_bf16 v[92:95], v[132:135], v[228:231], v[92:95]
	v_mfma_f32_16x16x32_bf16 v[88:91], v[164:167], v[228:231], v[88:91]
	v_mfma_f32_16x16x32_bf16 v[76:79], v[132:135], v[236:239], v[76:79]
	v_mfma_f32_16x16x32_bf16 v[72:75], v[164:167], v[236:239], v[72:75]
	v_mfma_f32_16x16x32_bf16 v[116:119], v[188:191], v[208:211], v[116:119]
	v_mfma_f32_16x16x32_bf16 v[112:115], v[200:203], v[208:211], v[112:115]
	v_mfma_f32_16x16x32_bf16 v[100:103], v[188:191], v[216:219], v[100:103]
	v_mfma_f32_16x16x32_bf16 v[96:99], v[200:203], v[216:219], v[96:99]
	v_mfma_f32_16x16x32_bf16 v[84:87], v[188:191], v[224:227], v[84:87]
	v_mfma_f32_16x16x32_bf16 v[80:83], v[200:203], v[224:227], v[80:83]
	v_mfma_f32_16x16x32_bf16 v[68:71], v[188:191], v[232:235], v[68:71]
	v_mfma_f32_16x16x32_bf16 v[64:67], v[200:203], v[232:235], v[64:67]
	v_mfma_f32_16x16x32_bf16 v[116:119], v[196:199], v[212:215], v[116:119]
	v_mfma_f32_16x16x32_bf16 v[112:115], v[204:207], v[212:215], v[112:115]
	v_mfma_f32_16x16x32_bf16 v[100:103], v[196:199], v[220:223], v[100:103]
	v_mfma_f32_16x16x32_bf16 v[96:99], v[204:207], v[220:223], v[96:99]
	v_mfma_f32_16x16x32_bf16 v[84:87], v[196:199], v[228:231], v[84:87]
	v_mfma_f32_16x16x32_bf16 v[80:83], v[204:207], v[228:231], v[80:83]
	v_mfma_f32_16x16x32_bf16 v[68:71], v[196:199], v[236:239], v[68:71]
	v_mfma_f32_16x16x32_bf16 v[64:67], v[204:207], v[236:239], v[64:67]
	s_barrier
	s_setprio 0
	s_add_i32 s68, s52, s39
	v_lshl_add_u64 v[168:169], s[2:3], 0, v[142:143]
	s_mov_b32 m0, s68
	ds_read_b128 v[208:211], v185 offset:16384
	ds_read_b128 v[212:215], v185 offset:17408
	ds_read_b128 v[216:219], v185 offset:18432
	ds_read_b128 v[220:223], v185 offset:19456
	ds_read_b128 v[224:227], v185 offset:20480
	ds_read_b128 v[228:231], v185 offset:21504
	ds_read_b128 v[232:235], v185 offset:22528
	ds_read_b128 v[236:239], v185 offset:23552
	global_load_lds_dwordx4 v[168:169], off
	s_add_i32 m0, s68, 0x2000
	s_add_u32 s68, s2, 0x40000
	v_lshl_add_u64 v[192:193], s[2:3], 0, v[146:147]
	s_addc_u32 s69, s3, 0
	s_add_i32 s70, s53, s39
	global_load_lds_dwordx4 v[192:193], off
	v_lshl_add_u64 v[240:241], s[68:69], 0, v[142:143]
	s_mov_b32 m0, s70
	v_lshl_add_u64 v[242:243], s[22:23], 0, v[144:145]
	global_load_lds_dwordx4 v[240:241], off
	v_lshl_add_u64 v[240:241], s[68:69], 0, v[146:147]
	s_add_i32 m0, s70, 0x2000
	s_nop 0
	global_load_lds_dwordx4 v[240:241], off
	v_lshl_add_u64 v[240:241], s[22:23], 0, v[140:141]
	s_mov_b32 m0, s37
	s_nop 0
	global_load_lds_dwordx4 v[240:241], off
	s_mov_b32 m0, s40
	s_nop 0
	global_load_lds_dwordx4 v[242:243], off
	s_waitcnt vmcnt(8)
	s_waitcnt lgkmcnt(0)
	s_setprio 1
	s_barrier
	v_mfma_f32_16x16x32_bf16 v[60:63], v[128:131], v[208:211], v[60:63]
	v_mfma_f32_16x16x32_bf16 v[56:59], v[136:139], v[208:211], v[56:59]
	v_mfma_f32_16x16x32_bf16 v[44:47], v[128:131], v[216:219], v[44:47]
	v_mfma_f32_16x16x32_bf16 v[40:43], v[136:139], v[216:219], v[40:43]
	v_mfma_f32_16x16x32_bf16 v[28:31], v[128:131], v[224:227], v[28:31]
	v_mfma_f32_16x16x32_bf16 v[24:27], v[136:139], v[224:227], v[24:27]
	v_mfma_f32_16x16x32_bf16 v[12:15], v[128:131], v[232:235], v[12:15]
	v_mfma_f32_16x16x32_bf16 v[8:11], v[136:139], v[232:235], v[8:11]
	v_mfma_f32_16x16x32_bf16 v[60:63], v[132:135], v[212:215], v[60:63]
	v_mfma_f32_16x16x32_bf16 v[56:59], v[164:167], v[212:215], v[56:59]
	v_mfma_f32_16x16x32_bf16 v[44:47], v[132:135], v[220:223], v[44:47]
	v_mfma_f32_16x16x32_bf16 v[40:43], v[164:167], v[220:223], v[40:43]
	v_mfma_f32_16x16x32_bf16 v[28:31], v[132:135], v[228:231], v[28:31]
	v_mfma_f32_16x16x32_bf16 v[24:27], v[164:167], v[228:231], v[24:27]
	v_mfma_f32_16x16x32_bf16 v[12:15], v[132:135], v[236:239], v[12:15]
	v_mfma_f32_16x16x32_bf16 v[8:11], v[164:167], v[236:239], v[8:11]
	v_mfma_f32_16x16x32_bf16 v[52:55], v[188:191], v[208:211], v[52:55]
	v_mfma_f32_16x16x32_bf16 v[48:51], v[200:203], v[208:211], v[48:51]
	v_mfma_f32_16x16x32_bf16 v[36:39], v[188:191], v[216:219], v[36:39]
	v_mfma_f32_16x16x32_bf16 v[32:35], v[200:203], v[216:219], v[32:35]
	v_mfma_f32_16x16x32_bf16 v[20:23], v[188:191], v[224:227], v[20:23]
	v_mfma_f32_16x16x32_bf16 v[16:19], v[200:203], v[224:227], v[16:19]
	v_mfma_f32_16x16x32_bf16 v[4:7], v[188:191], v[232:235], v[4:7]
	v_mfma_f32_16x16x32_bf16 v[0:3], v[200:203], v[232:235], v[0:3]
	v_mfma_f32_16x16x32_bf16 v[52:55], v[196:199], v[212:215], v[52:55]
	v_mfma_f32_16x16x32_bf16 v[48:51], v[204:207], v[212:215], v[48:51]
	v_mfma_f32_16x16x32_bf16 v[36:39], v[196:199], v[220:223], v[36:39]
	v_mfma_f32_16x16x32_bf16 v[32:35], v[204:207], v[220:223], v[32:35]
	v_mfma_f32_16x16x32_bf16 v[20:23], v[196:199], v[228:231], v[20:23]
	v_mfma_f32_16x16x32_bf16 v[16:19], v[204:207], v[228:231], v[16:19]
	v_mfma_f32_16x16x32_bf16 v[4:7], v[196:199], v[236:239], v[4:7]
	v_mfma_f32_16x16x32_bf16 v[0:3], v[204:207], v[236:239], v[0:3]
	s_barrier
	s_setprio 0
	s_add_i32 s68, 0, 0x18000
	s_add_i32 s69, 0, 0x1c000
	v_add_u32_e32 v164, s68, v149
	v_add_u32_e32 v187, s69, v149
	ds_read_b128 v[128:131], v164
	ds_read_b128 v[132:135], v164 offset:1024
	ds_read_b128 v[136:139], v164 offset:2048
	ds_read_b128 v[164:167], v164 offset:3072
	ds_read_b128 v[188:191], v187
	ds_read_b128 v[196:199], v187 offset:1024
	ds_read_b128 v[200:203], v187 offset:2048
	ds_read_b128 v[204:207], v187 offset:3072
	s_add_u32 s22, s22, 0x40000
	s_addc_u32 s23, s23, 0
	s_mov_b32 m0, s41
	v_lshl_add_u64 v[244:245], s[22:23], 0, v[140:141]
	ds_read_b128 v[208:211], v185 offset:32768
	ds_read_b128 v[212:215], v185 offset:33792
	ds_read_b128 v[216:219], v185 offset:34816
	ds_read_b128 v[220:223], v185 offset:35840
	ds_read_b128 v[224:227], v185 offset:36864
	ds_read_b128 v[228:231], v185 offset:37888
	ds_read_b128 v[232:235], v185 offset:38912
	ds_read_b128 v[236:239], v185 offset:39936
	global_load_lds_dwordx4 v[244:245], off
	v_lshl_add_u64 v[244:245], s[22:23], 0, v[144:145]
	s_mov_b32 m0, s42
	s_nop 0
	global_load_lds_dwordx4 v[244:245], off
	s_waitcnt vmcnt(8)
	s_waitcnt lgkmcnt(0)
	s_setprio 1
	s_barrier
	v_mfma_f32_16x16x32_bf16 v[124:127], v[128:131], v[208:211], v[124:127]
	v_mfma_f32_16x16x32_bf16 v[120:123], v[136:139], v[208:211], v[120:123]
	v_mfma_f32_16x16x32_bf16 v[108:111], v[128:131], v[216:219], v[108:111]
	v_mfma_f32_16x16x32_bf16 v[104:107], v[136:139], v[216:219], v[104:107]
	v_mfma_f32_16x16x32_bf16 v[92:95], v[128:131], v[224:227], v[92:95]
	v_mfma_f32_16x16x32_bf16 v[88:91], v[136:139], v[224:227], v[88:91]
	v_mfma_f32_16x16x32_bf16 v[76:79], v[128:131], v[232:235], v[76:79]
	v_mfma_f32_16x16x32_bf16 v[72:75], v[136:139], v[232:235], v[72:75]
	v_mfma_f32_16x16x32_bf16 v[124:127], v[132:135], v[212:215], v[124:127]
	v_mfma_f32_16x16x32_bf16 v[120:123], v[164:167], v[212:215], v[120:123]
	v_mfma_f32_16x16x32_bf16 v[108:111], v[132:135], v[220:223], v[108:111]
	v_mfma_f32_16x16x32_bf16 v[104:107], v[164:167], v[220:223], v[104:107]
	v_mfma_f32_16x16x32_bf16 v[92:95], v[132:135], v[228:231], v[92:95]
	v_mfma_f32_16x16x32_bf16 v[88:91], v[164:167], v[228:231], v[88:91]
	v_mfma_f32_16x16x32_bf16 v[76:79], v[132:135], v[236:239], v[76:79]
	v_mfma_f32_16x16x32_bf16 v[72:75], v[164:167], v[236:239], v[72:75]
	v_mfma_f32_16x16x32_bf16 v[116:119], v[188:191], v[208:211], v[116:119]
	v_mfma_f32_16x16x32_bf16 v[112:115], v[200:203], v[208:211], v[112:115]
	v_mfma_f32_16x16x32_bf16 v[100:103], v[188:191], v[216:219], v[100:103]
	v_mfma_f32_16x16x32_bf16 v[96:99], v[200:203], v[216:219], v[96:99]
	v_mfma_f32_16x16x32_bf16 v[84:87], v[188:191], v[224:227], v[84:87]
	v_mfma_f32_16x16x32_bf16 v[80:83], v[200:203], v[224:227], v[80:83]
	v_mfma_f32_16x16x32_bf16 v[68:71], v[188:191], v[232:235], v[68:71]
	v_mfma_f32_16x16x32_bf16 v[64:67], v[200:203], v[232:235], v[64:67]
	v_mfma_f32_16x16x32_bf16 v[116:119], v[196:199], v[212:215], v[116:119]
	v_mfma_f32_16x16x32_bf16 v[112:115], v[204:207], v[212:215], v[112:115]
	v_mfma_f32_16x16x32_bf16 v[100:103], v[196:199], v[220:223], v[100:103]
	v_mfma_f32_16x16x32_bf16 v[96:99], v[204:207], v[220:223], v[96:99]
	v_mfma_f32_16x16x32_bf16 v[84:87], v[196:199], v[228:231], v[84:87]
	v_mfma_f32_16x16x32_bf16 v[80:83], v[204:207], v[228:231], v[80:83]
	v_mfma_f32_16x16x32_bf16 v[68:71], v[196:199], v[236:239], v[68:71]
	v_mfma_f32_16x16x32_bf16 v[64:67], v[204:207], v[236:239], v[64:67]
	s_barrier
	s_setprio 0
	s_add_i32 s22, s68, s39
	v_lshl_add_u64 v[168:169], v[168:169], 0, s[18:19]
	s_mov_b32 m0, s22
	ds_read_b128 v[208:211], v185 offset:49152
	ds_read_b128 v[212:215], v185 offset:50176
	ds_read_b128 v[216:219], v185 offset:51200
	ds_read_b128 v[220:223], v185 offset:52224
	ds_read_b128 v[224:227], v185 offset:53248
	ds_read_b128 v[228:231], v185 offset:54272
	ds_read_b128 v[232:235], v185 offset:55296
	ds_read_b128 v[236:239], v185 offset:56320
	global_load_lds_dwordx4 v[168:169], off
	s_add_i32 m0, s22, 0x2000
	s_add_u32 s2, s2, 0x40080
	v_lshl_add_u64 v[168:169], v[192:193], 0, s[18:19]
	s_addc_u32 s3, s3, 0
	s_add_i32 s22, s69, s39
	global_load_lds_dwordx4 v[168:169], off
	v_lshl_add_u64 v[168:169], s[2:3], 0, v[142:143]
	s_mov_b32 m0, s22
	s_nop 0
	global_load_lds_dwordx4 v[168:169], off
	v_lshl_add_u64 v[168:169], s[2:3], 0, v[146:147]
	s_add_i32 m0, s22, 0x2000
	s_nop 0
	global_load_lds_dwordx4 v[168:169], off
	v_lshl_add_u64 v[168:169], v[240:241], 0, s[18:19]
	s_mov_b32 m0, s46
	s_nop 0
	global_load_lds_dwordx4 v[168:169], off
	v_lshl_add_u64 v[168:169], v[242:243], 0, s[18:19]
	s_mov_b32 m0, s47
	s_nop 0
	global_load_lds_dwordx4 v[168:169], off
	s_waitcnt vmcnt(8)
	s_waitcnt lgkmcnt(0)
	s_setprio 1
	s_barrier
	v_mfma_f32_16x16x32_bf16 v[60:63], v[128:131], v[208:211], v[60:63]
	v_mfma_f32_16x16x32_bf16 v[56:59], v[136:139], v[208:211], v[56:59]
	v_mfma_f32_16x16x32_bf16 v[44:47], v[128:131], v[216:219], v[44:47]
	v_mfma_f32_16x16x32_bf16 v[40:43], v[136:139], v[216:219], v[40:43]
	v_mfma_f32_16x16x32_bf16 v[28:31], v[128:131], v[224:227], v[28:31]
	v_mfma_f32_16x16x32_bf16 v[24:27], v[136:139], v[224:227], v[24:27]
	v_mfma_f32_16x16x32_bf16 v[12:15], v[128:131], v[232:235], v[12:15]
	v_mfma_f32_16x16x32_bf16 v[8:11], v[136:139], v[232:235], v[8:11]
	v_mfma_f32_16x16x32_bf16 v[60:63], v[132:135], v[212:215], v[60:63]
	v_mfma_f32_16x16x32_bf16 v[56:59], v[164:167], v[212:215], v[56:59]
	v_mfma_f32_16x16x32_bf16 v[44:47], v[132:135], v[220:223], v[44:47]
	v_mfma_f32_16x16x32_bf16 v[40:43], v[164:167], v[220:223], v[40:43]
	v_mfma_f32_16x16x32_bf16 v[28:31], v[132:135], v[228:231], v[28:31]
	v_mfma_f32_16x16x32_bf16 v[24:27], v[164:167], v[228:231], v[24:27]
	v_mfma_f32_16x16x32_bf16 v[12:15], v[132:135], v[236:239], v[12:15]
	v_mfma_f32_16x16x32_bf16 v[8:11], v[164:167], v[236:239], v[8:11]
	v_mfma_f32_16x16x32_bf16 v[52:55], v[188:191], v[208:211], v[52:55]
	v_mfma_f32_16x16x32_bf16 v[48:51], v[200:203], v[208:211], v[48:51]
	v_mfma_f32_16x16x32_bf16 v[36:39], v[188:191], v[216:219], v[36:39]
	v_mfma_f32_16x16x32_bf16 v[32:35], v[200:203], v[216:219], v[32:35]
	v_mfma_f32_16x16x32_bf16 v[20:23], v[188:191], v[224:227], v[20:23]
	v_mfma_f32_16x16x32_bf16 v[16:19], v[200:203], v[224:227], v[16:19]
	v_mfma_f32_16x16x32_bf16 v[4:7], v[188:191], v[232:235], v[4:7]
	v_mfma_f32_16x16x32_bf16 v[0:3], v[200:203], v[232:235], v[0:3]
	v_mfma_f32_16x16x32_bf16 v[52:55], v[196:199], v[212:215], v[52:55]
	v_mfma_f32_16x16x32_bf16 v[48:51], v[204:207], v[212:215], v[48:51]
	v_mfma_f32_16x16x32_bf16 v[36:39], v[196:199], v[220:223], v[36:39]
	v_mfma_f32_16x16x32_bf16 v[32:35], v[204:207], v[220:223], v[32:35]
	v_mfma_f32_16x16x32_bf16 v[20:23], v[196:199], v[228:231], v[20:23]
	v_mfma_f32_16x16x32_bf16 v[16:19], v[204:207], v[228:231], v[16:19]
	v_mfma_f32_16x16x32_bf16 v[4:7], v[196:199], v[236:239], v[4:7]
	v_mfma_f32_16x16x32_bf16 v[0:3], v[204:207], v[236:239], v[0:3]
	s_barrier
	s_setprio 0
	s_add_i32 s67, s67, 2
	s_add_u32 s14, s14, 0x100
	s_addc_u32 s15, s15, 0
	s_add_u32 s65, s65, 0x100
	s_addc_u32 s66, s66, 0
	s_cmp_gt_u32 s67, 13
	s_cbranch_scc0 .LBB0_725

.LBB0_808:
	s_ashr_i32 s25, s24, 31
	s_lshl_b64 s[22:23], s[24:25], 19
	s_add_u32 s26, s84, s22
	s_addc_u32 s27, s85, s23
	s_and_b64 s[22:23], s[4:5], exec
	s_cselect_b32 s25, s27, s15
	s_cselect_b32 s50, s26, s14
	s_ashr_i32 s21, s20, 31
	s_lshl_b64 s[22:23], s[20:21], 19
	s_add_u32 s28, s30, s22
	s_addc_u32 s29, s31, s23
	s_and_b64 s[22:23], s[4:5], exec
	s_cselect_b32 s21, s29, s3
	s_cselect_b32 s51, s28, s2
	s_add_u32 s14, s14, 0x40080
	s_addc_u32 s15, s15, 0
	s_add_u32 s52, s2, 0x100
	s_addc_u32 s53, s3, 0
	s_mov_b32 s54, -2
	s_waitcnt vmcnt(0)
	ds_read_b128 v[136:139], v155
	ds_read_b128 v[162:165], v155 offset:1024
	ds_read_b128 v[166:169], v155 offset:2048
	ds_read_b128 v[178:181], v155 offset:3072
	ds_read_b128 v[184:187], v158
	ds_read_b128 v[188:191], v158 offset:1024
	ds_read_b128 v[196:199], v158 offset:2048
	ds_read_b128 v[200:203], v158 offset:3072
	s_add_u32 s2, s14, 0xfffc0080
	s_addc_u32 s3, s15, -1
	s_cmp_eq_u32 s54, 12
	s_cselect_b32 s23, s25, s3
	s_cselect_b32 s22, s50, s2
	s_cselect_b32 s3, s21, s53
	s_cselect_b32 s2, s51, s52
	v_lshl_add_u64 v[156:157], s[14:15], 0, v[128:129]
	s_add_i32 m0, s37, 0xc000
	ds_read_b128 v[204:207], v159
	ds_read_b128 v[208:211], v159 offset:1024
	ds_read_b128 v[212:215], v159 offset:2048
	ds_read_b128 v[216:219], v159 offset:3072
	ds_read_b128 v[220:223], v159 offset:4096
	ds_read_b128 v[224:227], v159 offset:5120
	ds_read_b128 v[228:231], v159 offset:6144
	ds_read_b128 v[232:235], v159 offset:7168
	global_load_lds_dwordx4 v[156:157], off
	v_lshl_add_u64 v[156:157], s[14:15], 0, v[130:131]
	s_add_i32 m0, s37, 0xe000
	s_nop 0
	global_load_lds_dwordx4 v[156:157], off
	s_waitcnt vmcnt(8)
	s_waitcnt lgkmcnt(0)
	s_setprio 1
	s_barrier
	v_mfma_f32_16x16x32_bf16 v[112:115], v[136:139], v[204:207], 0
	v_mfma_f32_16x16x32_bf16 v[108:111], v[166:169], v[204:207], 0
	v_mfma_f32_16x16x32_bf16 v[104:107], v[136:139], v[212:215], 0
	v_mfma_f32_16x16x32_bf16 v[100:103], v[166:169], v[212:215], 0
	v_mfma_f32_16x16x32_bf16 v[92:95], v[136:139], v[220:223], 0
	v_mfma_f32_16x16x32_bf16 v[84:87], v[166:169], v[220:223], 0
	v_mfma_f32_16x16x32_bf16 v[76:79], v[136:139], v[228:231], 0
	v_mfma_f32_16x16x32_bf16 v[68:71], v[166:169], v[228:231], 0
	v_mfma_f32_16x16x32_bf16 v[112:115], v[162:165], v[208:211], v[112:115]
	v_mfma_f32_16x16x32_bf16 v[108:111], v[178:181], v[208:211], v[108:111]
	v_mfma_f32_16x16x32_bf16 v[104:107], v[162:165], v[216:219], v[104:107]
	v_mfma_f32_16x16x32_bf16 v[100:103], v[178:181], v[216:219], v[100:103]
	v_mfma_f32_16x16x32_bf16 v[92:95], v[162:165], v[224:227], v[92:95]
	v_mfma_f32_16x16x32_bf16 v[84:87], v[178:181], v[224:227], v[84:87]
	v_mfma_f32_16x16x32_bf16 v[76:79], v[162:165], v[232:235], v[76:79]
	v_mfma_f32_16x16x32_bf16 v[68:71], v[178:181], v[232:235], v[68:71]
	v_mfma_f32_16x16x32_bf16 v[124:127], v[184:187], v[204:207], 0
	v_mfma_f32_16x16x32_bf16 v[120:123], v[196:199], v[204:207], 0
	v_mfma_f32_16x16x32_bf16 v[116:119], v[184:187], v[212:215], 0
	v_mfma_f32_16x16x32_bf16 v[96:99], v[196:199], v[212:215], 0
	v_mfma_f32_16x16x32_bf16 v[88:91], v[184:187], v[220:223], 0
	v_mfma_f32_16x16x32_bf16 v[80:83], v[196:199], v[220:223], 0
	v_mfma_f32_16x16x32_bf16 v[72:75], v[184:187], v[228:231], 0
	v_mfma_f32_16x16x32_bf16 v[64:67], v[196:199], v[228:231], 0
	v_mfma_f32_16x16x32_bf16 v[124:127], v[188:191], v[208:211], v[124:127]
	v_mfma_f32_16x16x32_bf16 v[120:123], v[200:203], v[208:211], v[120:123]
	v_mfma_f32_16x16x32_bf16 v[116:119], v[188:191], v[216:219], v[116:119]
	v_mfma_f32_16x16x32_bf16 v[96:99], v[200:203], v[216:219], v[96:99]
	v_mfma_f32_16x16x32_bf16 v[88:91], v[188:191], v[224:227], v[88:91]
	v_mfma_f32_16x16x32_bf16 v[80:83], v[200:203], v[224:227], v[80:83]
	v_mfma_f32_16x16x32_bf16 v[72:75], v[188:191], v[232:235], v[72:75]
	v_mfma_f32_16x16x32_bf16 v[64:67], v[200:203], v[232:235], v[64:67]
	s_barrier
	s_setprio 0
	s_add_i32 s55, s46, s34
	v_lshl_add_u64 v[156:157], s[2:3], 0, v[142:143]
	s_mov_b32 m0, s55
	ds_read_b128 v[204:207], v159 offset:16384
	ds_read_b128 v[208:211], v159 offset:17408
	ds_read_b128 v[212:215], v159 offset:18432
	ds_read_b128 v[216:219], v159 offset:19456
	ds_read_b128 v[220:223], v159 offset:20480
	ds_read_b128 v[224:227], v159 offset:21504
	ds_read_b128 v[228:231], v159 offset:22528
	ds_read_b128 v[232:235], v159 offset:23552
	global_load_lds_dwordx4 v[156:157], off
	s_add_i32 m0, s55, 0x2000
	s_add_u32 s56, s2, 0x40000
	v_lshl_add_u64 v[192:193], s[2:3], 0, v[146:147]
	s_addc_u32 s57, s3, 0
	s_add_i32 s55, s47, s34
	global_load_lds_dwordx4 v[192:193], off
	v_lshl_add_u64 v[236:237], s[56:57], 0, v[142:143]
	s_mov_b32 m0, s55
	v_lshl_add_u64 v[238:239], s[22:23], 0, v[144:145]
	global_load_lds_dwordx4 v[236:237], off
	v_lshl_add_u64 v[236:237], s[56:57], 0, v[146:147]
	s_add_i32 m0, s55, 0x2000
	s_nop 0
	global_load_lds_dwordx4 v[236:237], off
	v_lshl_add_u64 v[236:237], s[22:23], 0, v[140:141]
	s_mov_b32 m0, s37
	s_nop 0
	global_load_lds_dwordx4 v[236:237], off
	s_mov_b32 m0, s38
	s_nop 0
	global_load_lds_dwordx4 v[238:239], off
	s_waitcnt vmcnt(8)
	s_waitcnt lgkmcnt(0)
	s_setprio 1
	s_barrier
	v_mfma_f32_16x16x32_bf16 v[60:63], v[136:139], v[204:207], 0
	v_mfma_f32_16x16x32_bf16 v[52:55], v[166:169], v[204:207], 0
	v_mfma_f32_16x16x32_bf16 v[44:47], v[136:139], v[212:215], 0
	v_mfma_f32_16x16x32_bf16 v[36:39], v[166:169], v[212:215], 0
	v_mfma_f32_16x16x32_bf16 v[28:31], v[136:139], v[220:223], 0
	v_mfma_f32_16x16x32_bf16 v[20:23], v[166:169], v[220:223], 0
	v_mfma_f32_16x16x32_bf16 v[12:15], v[136:139], v[228:231], 0
	v_mfma_f32_16x16x32_bf16 v[4:7], v[166:169], v[228:231], 0
	v_mfma_f32_16x16x32_bf16 v[60:63], v[162:165], v[208:211], v[60:63]
	v_mfma_f32_16x16x32_bf16 v[52:55], v[178:181], v[208:211], v[52:55]
	v_mfma_f32_16x16x32_bf16 v[44:47], v[162:165], v[216:219], v[44:47]
	v_mfma_f32_16x16x32_bf16 v[36:39], v[178:181], v[216:219], v[36:39]
	v_mfma_f32_16x16x32_bf16 v[28:31], v[162:165], v[224:227], v[28:31]
	v_mfma_f32_16x16x32_bf16 v[20:23], v[178:181], v[224:227], v[20:23]
	v_mfma_f32_16x16x32_bf16 v[12:15], v[162:165], v[232:235], v[12:15]
	v_mfma_f32_16x16x32_bf16 v[4:7], v[178:181], v[232:235], v[4:7]
	v_mfma_f32_16x16x32_bf16 v[56:59], v[184:187], v[204:207], 0
	v_mfma_f32_16x16x32_bf16 v[48:51], v[196:199], v[204:207], 0
	v_mfma_f32_16x16x32_bf16 v[40:43], v[184:187], v[212:215], 0
	v_mfma_f32_16x16x32_bf16 v[32:35], v[196:199], v[212:215], 0
	v_mfma_f32_16x16x32_bf16 v[24:27], v[184:187], v[220:223], 0
	v_mfma_f32_16x16x32_bf16 v[16:19], v[196:199], v[220:223], 0
	v_mfma_f32_16x16x32_bf16 v[8:11], v[184:187], v[228:231], 0
	v_mfma_f32_16x16x32_bf16 v[0:3], v[196:199], v[228:231], 0
	v_mfma_f32_16x16x32_bf16 v[56:59], v[188:191], v[208:211], v[56:59]
	v_mfma_f32_16x16x32_bf16 v[48:51], v[200:203], v[208:211], v[48:51]
	v_mfma_f32_16x16x32_bf16 v[40:43], v[188:191], v[216:219], v[40:43]
	v_mfma_f32_16x16x32_bf16 v[32:35], v[200:203], v[216:219], v[32:35]
	v_mfma_f32_16x16x32_bf16 v[24:27], v[188:191], v[224:227], v[24:27]
	v_mfma_f32_16x16x32_bf16 v[16:19], v[200:203], v[224:227], v[16:19]
	v_mfma_f32_16x16x32_bf16 v[8:11], v[188:191], v[232:235], v[8:11]
	v_mfma_f32_16x16x32_bf16 v[0:3], v[200:203], v[232:235], v[0:3]
	s_barrier
	s_setprio 0
	s_add_i32 s55, 0, 0x18000
	v_add_u32_e32 v161, s55, v151
	s_add_i32 s56, 0, 0x1c000
	ds_read_b128 v[136:139], v161
	ds_read_b128 v[162:165], v161 offset:1024
	ds_read_b128 v[166:169], v161 offset:2048
	ds_read_b128 v[178:181], v161 offset:3072
	v_add_u32_e32 v161, s56, v151
	ds_read_b128 v[184:187], v161
	ds_read_b128 v[188:191], v161 offset:1024
	ds_read_b128 v[196:199], v161 offset:2048
	ds_read_b128 v[200:203], v161 offset:3072
	s_add_u32 s22, s22, 0x40000
	s_addc_u32 s23, s23, 0
	s_mov_b32 m0, s39
	v_lshl_add_u64 v[240:241], s[22:23], 0, v[140:141]
	ds_read_b128 v[204:207], v159 offset:32768
	ds_read_b128 v[208:211], v159 offset:33792
	ds_read_b128 v[212:215], v159 offset:34816
	ds_read_b128 v[216:219], v159 offset:35840
	ds_read_b128 v[220:223], v159 offset:36864
	ds_read_b128 v[224:227], v159 offset:37888
	ds_read_b128 v[228:231], v159 offset:38912
	ds_read_b128 v[232:235], v159 offset:39936
	global_load_lds_dwordx4 v[240:241], off
	v_lshl_add_u64 v[240:241], s[22:23], 0, v[144:145]
	s_mov_b32 m0, s40
	s_nop 0
	global_load_lds_dwordx4 v[240:241], off
	s_waitcnt vmcnt(8)
	s_waitcnt lgkmcnt(0)
	s_setprio 1
	s_barrier
	v_mfma_f32_16x16x32_bf16 v[112:115], v[136:139], v[204:207], v[112:115]
	v_mfma_f32_16x16x32_bf16 v[108:111], v[166:169], v[204:207], v[108:111]
	v_mfma_f32_16x16x32_bf16 v[104:107], v[136:139], v[212:215], v[104:107]
	v_mfma_f32_16x16x32_bf16 v[100:103], v[166:169], v[212:215], v[100:103]
	v_mfma_f32_16x16x32_bf16 v[92:95], v[136:139], v[220:223], v[92:95]
	v_mfma_f32_16x16x32_bf16 v[84:87], v[166:169], v[220:223], v[84:87]
	v_mfma_f32_16x16x32_bf16 v[76:79], v[136:139], v[228:231], v[76:79]
	v_mfma_f32_16x16x32_bf16 v[68:71], v[166:169], v[228:231], v[68:71]
	v_mfma_f32_16x16x32_bf16 v[112:115], v[162:165], v[208:211], v[112:115]
	v_mfma_f32_16x16x32_bf16 v[108:111], v[178:181], v[208:211], v[108:111]
	v_mfma_f32_16x16x32_bf16 v[104:107], v[162:165], v[216:219], v[104:107]
	v_mfma_f32_16x16x32_bf16 v[100:103], v[178:181], v[216:219], v[100:103]
	v_mfma_f32_16x16x32_bf16 v[92:95], v[162:165], v[224:227], v[92:95]
	v_mfma_f32_16x16x32_bf16 v[84:87], v[178:181], v[224:227], v[84:87]
	v_mfma_f32_16x16x32_bf16 v[76:79], v[162:165], v[232:235], v[76:79]
	v_mfma_f32_16x16x32_bf16 v[68:71], v[178:181], v[232:235], v[68:71]
	v_mfma_f32_16x16x32_bf16 v[124:127], v[184:187], v[204:207], v[124:127]
	v_mfma_f32_16x16x32_bf16 v[120:123], v[196:199], v[204:207], v[120:123]
	v_mfma_f32_16x16x32_bf16 v[116:119], v[184:187], v[212:215], v[116:119]
	v_mfma_f32_16x16x32_bf16 v[96:99], v[196:199], v[212:215], v[96:99]
	v_mfma_f32_16x16x32_bf16 v[88:91], v[184:187], v[220:223], v[88:91]
	v_mfma_f32_16x16x32_bf16 v[80:83], v[196:199], v[220:223], v[80:83]
	v_mfma_f32_16x16x32_bf16 v[72:75], v[184:187], v[228:231], v[72:75]
	v_mfma_f32_16x16x32_bf16 v[64:67], v[196:199], v[228:231], v[64:67]
	v_mfma_f32_16x16x32_bf16 v[124:127], v[188:191], v[208:211], v[124:127]
	v_mfma_f32_16x16x32_bf16 v[120:123], v[200:203], v[208:211], v[120:123]
	v_mfma_f32_16x16x32_bf16 v[116:119], v[188:191], v[216:219], v[116:119]
	v_mfma_f32_16x16x32_bf16 v[96:99], v[200:203], v[216:219], v[96:99]
	v_mfma_f32_16x16x32_bf16 v[88:91], v[188:191], v[224:227], v[88:91]
	v_mfma_f32_16x16x32_bf16 v[80:83], v[200:203], v[224:227], v[80:83]
	v_mfma_f32_16x16x32_bf16 v[72:75], v[188:191], v[232:235], v[72:75]
	v_mfma_f32_16x16x32_bf16 v[64:67], v[200:203], v[232:235], v[64:67]
	s_barrier
	s_setprio 0
	s_add_i32 s22, s55, s34
	v_lshl_add_u64 v[156:157], v[156:157], 0, s[12:13]
	s_mov_b32 m0, s22
	ds_read_b128 v[204:207], v159 offset:49152
	ds_read_b128 v[208:211], v159 offset:50176
	ds_read_b128 v[212:215], v159 offset:51200
	ds_read_b128 v[216:219], v159 offset:52224
	ds_read_b128 v[220:223], v159 offset:53248
	ds_read_b128 v[224:227], v159 offset:54272
	ds_read_b128 v[228:231], v159 offset:55296
	ds_read_b128 v[232:235], v159 offset:56320
	global_load_lds_dwordx4 v[156:157], off
	s_add_i32 m0, s22, 0x2000
	s_add_u32 s2, s2, 0x40080
	v_lshl_add_u64 v[156:157], v[192:193], 0, s[12:13]
	s_addc_u32 s3, s3, 0
	s_add_i32 s22, s56, s34
	global_load_lds_dwordx4 v[156:157], off
	v_lshl_add_u64 v[156:157], s[2:3], 0, v[142:143]
	s_mov_b32 m0, s22
	s_nop 0
	global_load_lds_dwordx4 v[156:157], off
	v_lshl_add_u64 v[156:157], s[2:3], 0, v[146:147]
	s_add_i32 m0, s22, 0x2000
	s_nop 0
	global_load_lds_dwordx4 v[156:157], off
	v_lshl_add_u64 v[156:157], v[236:237], 0, s[12:13]
	s_mov_b32 m0, s42
	s_nop 0
	global_load_lds_dwordx4 v[156:157], off
	v_lshl_add_u64 v[156:157], v[238:239], 0, s[12:13]
	s_mov_b32 m0, s43
	s_nop 0
	global_load_lds_dwordx4 v[156:157], off
	s_waitcnt vmcnt(8)
	s_waitcnt lgkmcnt(0)
	s_setprio 1
	s_barrier
	v_mfma_f32_16x16x32_bf16 v[60:63], v[136:139], v[204:207], v[60:63]
	v_mfma_f32_16x16x32_bf16 v[52:55], v[166:169], v[204:207], v[52:55]
	v_mfma_f32_16x16x32_bf16 v[44:47], v[136:139], v[212:215], v[44:47]
	v_mfma_f32_16x16x32_bf16 v[36:39], v[166:169], v[212:215], v[36:39]
	v_mfma_f32_16x16x32_bf16 v[28:31], v[136:139], v[220:223], v[28:31]
	v_mfma_f32_16x16x32_bf16 v[20:23], v[166:169], v[220:223], v[20:23]
	v_mfma_f32_16x16x32_bf16 v[12:15], v[136:139], v[228:231], v[12:15]
	v_mfma_f32_16x16x32_bf16 v[4:7], v[166:169], v[228:231], v[4:7]
	v_mfma_f32_16x16x32_bf16 v[60:63], v[162:165], v[208:211], v[60:63]
	v_mfma_f32_16x16x32_bf16 v[52:55], v[178:181], v[208:211], v[52:55]
	v_mfma_f32_16x16x32_bf16 v[44:47], v[162:165], v[216:219], v[44:47]
	v_mfma_f32_16x16x32_bf16 v[36:39], v[178:181], v[216:219], v[36:39]
	v_mfma_f32_16x16x32_bf16 v[28:31], v[162:165], v[224:227], v[28:31]
	v_mfma_f32_16x16x32_bf16 v[20:23], v[178:181], v[224:227], v[20:23]
	v_mfma_f32_16x16x32_bf16 v[12:15], v[162:165], v[232:235], v[12:15]
	v_mfma_f32_16x16x32_bf16 v[4:7], v[178:181], v[232:235], v[4:7]
	v_mfma_f32_16x16x32_bf16 v[56:59], v[184:187], v[204:207], v[56:59]
	v_mfma_f32_16x16x32_bf16 v[48:51], v[196:199], v[204:207], v[48:51]
	v_mfma_f32_16x16x32_bf16 v[40:43], v[184:187], v[212:215], v[40:43]
	v_mfma_f32_16x16x32_bf16 v[32:35], v[196:199], v[212:215], v[32:35]
	v_mfma_f32_16x16x32_bf16 v[24:27], v[184:187], v[220:223], v[24:27]
	v_mfma_f32_16x16x32_bf16 v[16:19], v[196:199], v[220:223], v[16:19]
	v_mfma_f32_16x16x32_bf16 v[8:11], v[184:187], v[228:231], v[8:11]
	v_mfma_f32_16x16x32_bf16 v[0:3], v[196:199], v[228:231], v[0:3]
	v_mfma_f32_16x16x32_bf16 v[56:59], v[188:191], v[208:211], v[56:59]
	v_mfma_f32_16x16x32_bf16 v[48:51], v[200:203], v[208:211], v[48:51]
	v_mfma_f32_16x16x32_bf16 v[40:43], v[188:191], v[216:219], v[40:43]
	v_mfma_f32_16x16x32_bf16 v[32:35], v[200:203], v[216:219], v[32:35]
	v_mfma_f32_16x16x32_bf16 v[24:27], v[188:191], v[224:227], v[24:27]
	v_mfma_f32_16x16x32_bf16 v[16:19], v[200:203], v[224:227], v[16:19]
	v_mfma_f32_16x16x32_bf16 v[8:11], v[188:191], v[232:235], v[8:11]
	v_mfma_f32_16x16x32_bf16 v[0:3], v[200:203], v[232:235], v[0:3]
	s_barrier
	s_setprio 0
	s_add_i32 s54, s54, 2
	s_add_u32 s14, s14, 0x100
	s_addc_u32 s15, s15, 0
	s_add_u32 s52, s52, 0x100
	s_addc_u32 s53, s53, 0
	s_cmp_gt_u32 s54, 13
	s_cbranch_scc1 .Lgemm_kdone_5
.LBB0_809:
	ds_read_b128 v[136:139], v155
	ds_read_b128 v[162:165], v155 offset:1024
	ds_read_b128 v[166:169], v155 offset:2048
	ds_read_b128 v[178:181], v155 offset:3072
	ds_read_b128 v[184:187], v158
	ds_read_b128 v[188:191], v158 offset:1024
	ds_read_b128 v[196:199], v158 offset:2048
	ds_read_b128 v[200:203], v158 offset:3072
	s_add_u32 s2, s14, 0xfffc0080
	s_addc_u32 s3, s15, -1
	s_cmp_eq_u32 s54, 12
	s_cselect_b32 s23, s25, s3
	s_cselect_b32 s22, s50, s2
	s_cselect_b32 s3, s21, s53
	s_cselect_b32 s2, s51, s52
	v_lshl_add_u64 v[156:157], s[14:15], 0, v[128:129]
	s_add_i32 m0, s37, 0xc000
	ds_read_b128 v[204:207], v159
	ds_read_b128 v[208:211], v159 offset:1024
	ds_read_b128 v[212:215], v159 offset:2048
	ds_read_b128 v[216:219], v159 offset:3072
	ds_read_b128 v[220:223], v159 offset:4096
	ds_read_b128 v[224:227], v159 offset:5120
	ds_read_b128 v[228:231], v159 offset:6144
	ds_read_b128 v[232:235], v159 offset:7168
	global_load_lds_dwordx4 v[156:157], off
	v_lshl_add_u64 v[156:157], s[14:15], 0, v[130:131]
	s_add_i32 m0, s37, 0xe000
	s_nop 0
	global_load_lds_dwordx4 v[156:157], off
	s_waitcnt vmcnt(8)
	s_waitcnt lgkmcnt(0)
	s_setprio 1
	s_barrier
	v_mfma_f32_16x16x32_bf16 v[112:115], v[136:139], v[204:207], v[112:115]
	v_mfma_f32_16x16x32_bf16 v[108:111], v[166:169], v[204:207], v[108:111]
	v_mfma_f32_16x16x32_bf16 v[104:107], v[136:139], v[212:215], v[104:107]
	v_mfma_f32_16x16x32_bf16 v[100:103], v[166:169], v[212:215], v[100:103]
	v_mfma_f32_16x16x32_bf16 v[92:95], v[136:139], v[220:223], v[92:95]
	v_mfma_f32_16x16x32_bf16 v[84:87], v[166:169], v[220:223], v[84:87]
	v_mfma_f32_16x16x32_bf16 v[76:79], v[136:139], v[228:231], v[76:79]
	v_mfma_f32_16x16x32_bf16 v[68:71], v[166:169], v[228:231], v[68:71]
	v_mfma_f32_16x16x32_bf16 v[112:115], v[162:165], v[208:211], v[112:115]
	v_mfma_f32_16x16x32_bf16 v[108:111], v[178:181], v[208:211], v[108:111]
	v_mfma_f32_16x16x32_bf16 v[104:107], v[162:165], v[216:219], v[104:107]
	v_mfma_f32_16x16x32_bf16 v[100:103], v[178:181], v[216:219], v[100:103]
	v_mfma_f32_16x16x32_bf16 v[92:95], v[162:165], v[224:227], v[92:95]
	v_mfma_f32_16x16x32_bf16 v[84:87], v[178:181], v[224:227], v[84:87]
	v_mfma_f32_16x16x32_bf16 v[76:79], v[162:165], v[232:235], v[76:79]
	v_mfma_f32_16x16x32_bf16 v[68:71], v[178:181], v[232:235], v[68:71]
	v_mfma_f32_16x16x32_bf16 v[124:127], v[184:187], v[204:207], v[124:127]
	v_mfma_f32_16x16x32_bf16 v[120:123], v[196:199], v[204:207], v[120:123]
	v_mfma_f32_16x16x32_bf16 v[116:119], v[184:187], v[212:215], v[116:119]
	v_mfma_f32_16x16x32_bf16 v[96:99], v[196:199], v[212:215], v[96:99]
	v_mfma_f32_16x16x32_bf16 v[88:91], v[184:187], v[220:223], v[88:91]
	v_mfma_f32_16x16x32_bf16 v[80:83], v[196:199], v[220:223], v[80:83]
	v_mfma_f32_16x16x32_bf16 v[72:75], v[184:187], v[228:231], v[72:75]
	v_mfma_f32_16x16x32_bf16 v[64:67], v[196:199], v[228:231], v[64:67]
	v_mfma_f32_16x16x32_bf16 v[124:127], v[188:191], v[208:211], v[124:127]
	v_mfma_f32_16x16x32_bf16 v[120:123], v[200:203], v[208:211], v[120:123]
	v_mfma_f32_16x16x32_bf16 v[116:119], v[188:191], v[216:219], v[116:119]
	v_mfma_f32_16x16x32_bf16 v[96:99], v[200:203], v[216:219], v[96:99]
	v_mfma_f32_16x16x32_bf16 v[88:91], v[188:191], v[224:227], v[88:91]
	v_mfma_f32_16x16x32_bf16 v[80:83], v[200:203], v[224:227], v[80:83]
	v_mfma_f32_16x16x32_bf16 v[72:75], v[188:191], v[232:235], v[72:75]
	v_mfma_f32_16x16x32_bf16 v[64:67], v[200:203], v[232:235], v[64:67]
	s_barrier
	s_setprio 0
	s_add_i32 s55, s46, s34
	v_lshl_add_u64 v[156:157], s[2:3], 0, v[142:143]
	s_mov_b32 m0, s55
	ds_read_b128 v[204:207], v159 offset:16384
	ds_read_b128 v[208:211], v159 offset:17408
	ds_read_b128 v[212:215], v159 offset:18432
	ds_read_b128 v[216:219], v159 offset:19456
	ds_read_b128 v[220:223], v159 offset:20480
	ds_read_b128 v[224:227], v159 offset:21504
	ds_read_b128 v[228:231], v159 offset:22528
	ds_read_b128 v[232:235], v159 offset:23552
	global_load_lds_dwordx4 v[156:157], off
	s_add_i32 m0, s55, 0x2000
	s_add_u32 s56, s2, 0x40000
	v_lshl_add_u64 v[192:193], s[2:3], 0, v[146:147]
	s_addc_u32 s57, s3, 0
	s_add_i32 s55, s47, s34
	global_load_lds_dwordx4 v[192:193], off
	v_lshl_add_u64 v[236:237], s[56:57], 0, v[142:143]
	s_mov_b32 m0, s55
	v_lshl_add_u64 v[238:239], s[22:23], 0, v[144:145]
	global_load_lds_dwordx4 v[236:237], off
	v_lshl_add_u64 v[236:237], s[56:57], 0, v[146:147]
	s_add_i32 m0, s55, 0x2000
	s_nop 0
	global_load_lds_dwordx4 v[236:237], off
	v_lshl_add_u64 v[236:237], s[22:23], 0, v[140:141]
	s_mov_b32 m0, s37
	s_nop 0
	global_load_lds_dwordx4 v[236:237], off
	s_mov_b32 m0, s38
	s_nop 0
	global_load_lds_dwordx4 v[238:239], off
	s_waitcnt vmcnt(8)
	s_waitcnt lgkmcnt(0)
	s_setprio 1
	s_barrier
	v_mfma_f32_16x16x32_bf16 v[60:63], v[136:139], v[204:207], v[60:63]
	v_mfma_f32_16x16x32_bf16 v[52:55], v[166:169], v[204:207], v[52:55]
	v_mfma_f32_16x16x32_bf16 v[44:47], v[136:139], v[212:215], v[44:47]
	v_mfma_f32_16x16x32_bf16 v[36:39], v[166:169], v[212:215], v[36:39]
	v_mfma_f32_16x16x32_bf16 v[28:31], v[136:139], v[220:223], v[28:31]
	v_mfma_f32_16x16x32_bf16 v[20:23], v[166:169], v[220:223], v[20:23]
	v_mfma_f32_16x16x32_bf16 v[12:15], v[136:139], v[228:231], v[12:15]
	v_mfma_f32_16x16x32_bf16 v[4:7], v[166:169], v[228:231], v[4:7]
	v_mfma_f32_16x16x32_bf16 v[60:63], v[162:165], v[208:211], v[60:63]
	v_mfma_f32_16x16x32_bf16 v[52:55], v[178:181], v[208:211], v[52:55]
	v_mfma_f32_16x16x32_bf16 v[44:47], v[162:165], v[216:219], v[44:47]
	v_mfma_f32_16x16x32_bf16 v[36:39], v[178:181], v[216:219], v[36:39]
	v_mfma_f32_16x16x32_bf16 v[28:31], v[162:165], v[224:227], v[28:31]
	v_mfma_f32_16x16x32_bf16 v[20:23], v[178:181], v[224:227], v[20:23]
	v_mfma_f32_16x16x32_bf16 v[12:15], v[162:165], v[232:235], v[12:15]
	v_mfma_f32_16x16x32_bf16 v[4:7], v[178:181], v[232:235], v[4:7]
	v_mfma_f32_16x16x32_bf16 v[56:59], v[184:187], v[204:207], v[56:59]
	v_mfma_f32_16x16x32_bf16 v[48:51], v[196:199], v[204:207], v[48:51]
	v_mfma_f32_16x16x32_bf16 v[40:43], v[184:187], v[212:215], v[40:43]
	v_mfma_f32_16x16x32_bf16 v[32:35], v[196:199], v[212:215], v[32:35]
	v_mfma_f32_16x16x32_bf16 v[24:27], v[184:187], v[220:223], v[24:27]
	v_mfma_f32_16x16x32_bf16 v[16:19], v[196:199], v[220:223], v[16:19]
	v_mfma_f32_16x16x32_bf16 v[8:11], v[184:187], v[228:231], v[8:11]
	v_mfma_f32_16x16x32_bf16 v[0:3], v[196:199], v[228:231], v[0:3]
	v_mfma_f32_16x16x32_bf16 v[56:59], v[188:191], v[208:211], v[56:59]
	v_mfma_f32_16x16x32_bf16 v[48:51], v[200:203], v[208:211], v[48:51]
	v_mfma_f32_16x16x32_bf16 v[40:43], v[188:191], v[216:219], v[40:43]
	v_mfma_f32_16x16x32_bf16 v[32:35], v[200:203], v[216:219], v[32:35]
	v_mfma_f32_16x16x32_bf16 v[24:27], v[188:191], v[224:227], v[24:27]
	v_mfma_f32_16x16x32_bf16 v[16:19], v[200:203], v[224:227], v[16:19]
	v_mfma_f32_16x16x32_bf16 v[8:11], v[188:191], v[232:235], v[8:11]
	v_mfma_f32_16x16x32_bf16 v[0:3], v[200:203], v[232:235], v[0:3]
	s_barrier
	s_setprio 0
	s_add_i32 s55, 0, 0x18000
	v_add_u32_e32 v161, s55, v151
	s_add_i32 s56, 0, 0x1c000
	ds_read_b128 v[136:139], v161
	ds_read_b128 v[162:165], v161 offset:1024
	ds_read_b128 v[166:169], v161 offset:2048
	ds_read_b128 v[178:181], v161 offset:3072
	v_add_u32_e32 v161, s56, v151
	ds_read_b128 v[184:187], v161
	ds_read_b128 v[188:191], v161 offset:1024
	ds_read_b128 v[196:199], v161 offset:2048
	ds_read_b128 v[200:203], v161 offset:3072
	s_add_u32 s22, s22, 0x40000
	s_addc_u32 s23, s23, 0
	s_mov_b32 m0, s39
	v_lshl_add_u64 v[240:241], s[22:23], 0, v[140:141]
	ds_read_b128 v[204:207], v159 offset:32768
	ds_read_b128 v[208:211], v159 offset:33792
	ds_read_b128 v[212:215], v159 offset:34816
	ds_read_b128 v[216:219], v159 offset:35840
	ds_read_b128 v[220:223], v159 offset:36864
	ds_read_b128 v[224:227], v159 offset:37888
	ds_read_b128 v[228:231], v159 offset:38912
	ds_read_b128 v[232:235], v159 offset:39936
	global_load_lds_dwordx4 v[240:241], off
	v_lshl_add_u64 v[240:241], s[22:23], 0, v[144:145]
	s_mov_b32 m0, s40
	s_nop 0
	global_load_lds_dwordx4 v[240:241], off
	s_waitcnt vmcnt(8)
	s_waitcnt lgkmcnt(0)
	s_setprio 1
	s_barrier
	v_mfma_f32_16x16x32_bf16 v[112:115], v[136:139], v[204:207], v[112:115]
	v_mfma_f32_16x16x32_bf16 v[108:111], v[166:169], v[204:207], v[108:111]
	v_mfma_f32_16x16x32_bf16 v[104:107], v[136:139], v[212:215], v[104:107]
	v_mfma_f32_16x16x32_bf16 v[100:103], v[166:169], v[212:215], v[100:103]
	v_mfma_f32_16x16x32_bf16 v[92:95], v[136:139], v[220:223], v[92:95]
	v_mfma_f32_16x16x32_bf16 v[84:87], v[166:169], v[220:223], v[84:87]
	v_mfma_f32_16x16x32_bf16 v[76:79], v[136:139], v[228:231], v[76:79]
	v_mfma_f32_16x16x32_bf16 v[68:71], v[166:169], v[228:231], v[68:71]
	v_mfma_f32_16x16x32_bf16 v[112:115], v[162:165], v[208:211], v[112:115]
	v_mfma_f32_16x16x32_bf16 v[108:111], v[178:181], v[208:211], v[108:111]
	v_mfma_f32_16x16x32_bf16 v[104:107], v[162:165], v[216:219], v[104:107]
	v_mfma_f32_16x16x32_bf16 v[100:103], v[178:181], v[216:219], v[100:103]
	v_mfma_f32_16x16x32_bf16 v[92:95], v[162:165], v[224:227], v[92:95]
	v_mfma_f32_16x16x32_bf16 v[84:87], v[178:181], v[224:227], v[84:87]
	v_mfma_f32_16x16x32_bf16 v[76:79], v[162:165], v[232:235], v[76:79]
	v_mfma_f32_16x16x32_bf16 v[68:71], v[178:181], v[232:235], v[68:71]
	v_mfma_f32_16x16x32_bf16 v[124:127], v[184:187], v[204:207], v[124:127]
	v_mfma_f32_16x16x32_bf16 v[120:123], v[196:199], v[204:207], v[120:123]
	v_mfma_f32_16x16x32_bf16 v[116:119], v[184:187], v[212:215], v[116:119]
	v_mfma_f32_16x16x32_bf16 v[96:99], v[196:199], v[212:215], v[96:99]
	v_mfma_f32_16x16x32_bf16 v[88:91], v[184:187], v[220:223], v[88:91]
	v_mfma_f32_16x16x32_bf16 v[80:83], v[196:199], v[220:223], v[80:83]
	v_mfma_f32_16x16x32_bf16 v[72:75], v[184:187], v[228:231], v[72:75]
	v_mfma_f32_16x16x32_bf16 v[64:67], v[196:199], v[228:231], v[64:67]
	v_mfma_f32_16x16x32_bf16 v[124:127], v[188:191], v[208:211], v[124:127]
	v_mfma_f32_16x16x32_bf16 v[120:123], v[200:203], v[208:211], v[120:123]
	v_mfma_f32_16x16x32_bf16 v[116:119], v[188:191], v[216:219], v[116:119]
	v_mfma_f32_16x16x32_bf16 v[96:99], v[200:203], v[216:219], v[96:99]
	v_mfma_f32_16x16x32_bf16 v[88:91], v[188:191], v[224:227], v[88:91]
	v_mfma_f32_16x16x32_bf16 v[80:83], v[200:203], v[224:227], v[80:83]
	v_mfma_f32_16x16x32_bf16 v[72:75], v[188:191], v[232:235], v[72:75]
	v_mfma_f32_16x16x32_bf16 v[64:67], v[200:203], v[232:235], v[64:67]
	s_barrier
	s_setprio 0
	s_add_i32 s22, s55, s34
	v_lshl_add_u64 v[156:157], v[156:157], 0, s[12:13]
	s_mov_b32 m0, s22
	ds_read_b128 v[204:207], v159 offset:49152
	ds_read_b128 v[208:211], v159 offset:50176
	ds_read_b128 v[212:215], v159 offset:51200
	ds_read_b128 v[216:219], v159 offset:52224
	ds_read_b128 v[220:223], v159 offset:53248
	ds_read_b128 v[224:227], v159 offset:54272
	ds_read_b128 v[228:231], v159 offset:55296
	ds_read_b128 v[232:235], v159 offset:56320
	global_load_lds_dwordx4 v[156:157], off
	s_add_i32 m0, s22, 0x2000
	s_add_u32 s2, s2, 0x40080
	v_lshl_add_u64 v[156:157], v[192:193], 0, s[12:13]
	s_addc_u32 s3, s3, 0
	s_add_i32 s22, s56, s34
	global_load_lds_dwordx4 v[156:157], off
	v_lshl_add_u64 v[156:157], s[2:3], 0, v[142:143]
	s_mov_b32 m0, s22
	s_nop 0
	global_load_lds_dwordx4 v[156:157], off
	v_lshl_add_u64 v[156:157], s[2:3], 0, v[146:147]
	s_add_i32 m0, s22, 0x2000
	s_nop 0
	global_load_lds_dwordx4 v[156:157], off
	v_lshl_add_u64 v[156:157], v[236:237], 0, s[12:13]
	s_mov_b32 m0, s42
	s_nop 0
	global_load_lds_dwordx4 v[156:157], off
	v_lshl_add_u64 v[156:157], v[238:239], 0, s[12:13]
	s_mov_b32 m0, s43
	s_nop 0
	global_load_lds_dwordx4 v[156:157], off
	s_waitcnt vmcnt(8)
	s_waitcnt lgkmcnt(0)
	s_setprio 1
	s_barrier
	v_mfma_f32_16x16x32_bf16 v[60:63], v[136:139], v[204:207], v[60:63]
	v_mfma_f32_16x16x32_bf16 v[52:55], v[166:169], v[204:207], v[52:55]
	v_mfma_f32_16x16x32_bf16 v[44:47], v[136:139], v[212:215], v[44:47]
	v_mfma_f32_16x16x32_bf16 v[36:39], v[166:169], v[212:215], v[36:39]
	v_mfma_f32_16x16x32_bf16 v[28:31], v[136:139], v[220:223], v[28:31]
	v_mfma_f32_16x16x32_bf16 v[20:23], v[166:169], v[220:223], v[20:23]
	v_mfma_f32_16x16x32_bf16 v[12:15], v[136:139], v[228:231], v[12:15]
	v_mfma_f32_16x16x32_bf16 v[4:7], v[166:169], v[228:231], v[4:7]
	v_mfma_f32_16x16x32_bf16 v[60:63], v[162:165], v[208:211], v[60:63]
	v_mfma_f32_16x16x32_bf16 v[52:55], v[178:181], v[208:211], v[52:55]
	v_mfma_f32_16x16x32_bf16 v[44:47], v[162:165], v[216:219], v[44:47]
	v_mfma_f32_16x16x32_bf16 v[36:39], v[178:181], v[216:219], v[36:39]
	v_mfma_f32_16x16x32_bf16 v[28:31], v[162:165], v[224:227], v[28:31]
	v_mfma_f32_16x16x32_bf16 v[20:23], v[178:181], v[224:227], v[20:23]
	v_mfma_f32_16x16x32_bf16 v[12:15], v[162:165], v[232:235], v[12:15]
	v_mfma_f32_16x16x32_bf16 v[4:7], v[178:181], v[232:235], v[4:7]
	v_mfma_f32_16x16x32_bf16 v[56:59], v[184:187], v[204:207], v[56:59]
	v_mfma_f32_16x16x32_bf16 v[48:51], v[196:199], v[204:207], v[48:51]
	v_mfma_f32_16x16x32_bf16 v[40:43], v[184:187], v[212:215], v[40:43]
	v_mfma_f32_16x16x32_bf16 v[32:35], v[196:199], v[212:215], v[32:35]
	v_mfma_f32_16x16x32_bf16 v[24:27], v[184:187], v[220:223], v[24:27]
	v_mfma_f32_16x16x32_bf16 v[16:19], v[196:199], v[220:223], v[16:19]
	v_mfma_f32_16x16x32_bf16 v[8:11], v[184:187], v[228:231], v[8:11]
	v_mfma_f32_16x16x32_bf16 v[0:3], v[196:199], v[228:231], v[0:3]
	v_mfma_f32_16x16x32_bf16 v[56:59], v[188:191], v[208:211], v[56:59]
	v_mfma_f32_16x16x32_bf16 v[48:51], v[200:203], v[208:211], v[48:51]
	v_mfma_f32_16x16x32_bf16 v[40:43], v[188:191], v[216:219], v[40:43]
	v_mfma_f32_16x16x32_bf16 v[32:35], v[200:203], v[216:219], v[32:35]
	v_mfma_f32_16x16x32_bf16 v[24:27], v[188:191], v[224:227], v[24:27]
	v_mfma_f32_16x16x32_bf16 v[16:19], v[200:203], v[224:227], v[16:19]
	v_mfma_f32_16x16x32_bf16 v[8:11], v[188:191], v[232:235], v[8:11]
	v_mfma_f32_16x16x32_bf16 v[0:3], v[200:203], v[232:235], v[0:3]
	s_barrier
	s_setprio 0
	s_add_i32 s54, s54, 2
	s_add_u32 s14, s14, 0x100
	s_addc_u32 s15, s15, 0
	s_add_u32 s52, s52, 0x100
	s_addc_u32 s53, s53, 0
	s_cmp_gt_u32 s54, 13
	s_cbranch_scc0 .LBB0_809

.LBB0_890:
	s_add_u32 s14, s14, 0xb0080
	s_addc_u32 s15, s15, 0
	s_add_u32 s53, s2, 0x100
	s_addc_u32 s54, s3, 0
	s_mov_b32 s55, -2
	s_waitcnt lgkmcnt(0)
	s_waitcnt vmcnt(0)
	ds_read_b128 v[128:131], v165
	ds_read_b128 v[132:135], v165 offset:1024
	ds_read_b128 v[136:139], v165 offset:2048
	ds_read_b128 v[156:159], v165 offset:3072
	ds_read_b128 v[172:175], v166
	ds_read_b128 v[176:179], v166 offset:1024
	ds_read_b128 v[180:183], v166 offset:2048
	ds_read_b128 v[184:187], v166 offset:3072
	s_add_u32 s2, s14, 0xfff50080
	s_addc_u32 s3, s15, -1
	s_cmp_eq_u32 s55, 40
	s_cselect_b32 s23, s1, s3
	s_cselect_b32 s22, s0, s2
	s_cselect_b32 s3, s21, s54
	s_cselect_b32 s2, s20, s53
	v_lshl_add_u64 v[160:161], s[14:15], 0, v[140:141]
	s_add_i32 m0, s27, 0xc000
	ds_read_b128 v[188:191], v167
	ds_read_b128 v[196:199], v167 offset:1024
	ds_read_b128 v[200:203], v167 offset:2048
	ds_read_b128 v[204:207], v167 offset:3072
	ds_read_b128 v[208:211], v167 offset:4096
	ds_read_b128 v[212:215], v167 offset:5120
	ds_read_b128 v[216:219], v167 offset:6144
	ds_read_b128 v[220:223], v167 offset:7168
	global_load_lds_dwordx4 v[160:161], off
	v_lshl_add_u64 v[160:161], s[14:15], 0, v[142:143]
	s_add_i32 m0, s27, 0xe000
	s_nop 0
	global_load_lds_dwordx4 v[160:161], off
	s_waitcnt vmcnt(8)
	s_waitcnt lgkmcnt(0)
	s_setprio 1
	s_barrier
	v_mfma_f32_16x16x32_bf16 v[124:127], v[128:131], v[188:191], 0
	v_mfma_f32_16x16x32_bf16 v[120:123], v[136:139], v[188:191], 0
	v_mfma_f32_16x16x32_bf16 v[108:111], v[128:131], v[200:203], 0
	v_mfma_f32_16x16x32_bf16 v[104:107], v[136:139], v[200:203], 0
	v_mfma_f32_16x16x32_bf16 v[92:95], v[128:131], v[208:211], 0
	v_mfma_f32_16x16x32_bf16 v[88:91], v[136:139], v[208:211], 0
	v_mfma_f32_16x16x32_bf16 v[76:79], v[128:131], v[216:219], 0
	v_mfma_f32_16x16x32_bf16 v[72:75], v[136:139], v[216:219], 0
	v_mfma_f32_16x16x32_bf16 v[124:127], v[132:135], v[196:199], v[124:127]
	v_mfma_f32_16x16x32_bf16 v[120:123], v[156:159], v[196:199], v[120:123]
	v_mfma_f32_16x16x32_bf16 v[108:111], v[132:135], v[204:207], v[108:111]
	v_mfma_f32_16x16x32_bf16 v[104:107], v[156:159], v[204:207], v[104:107]
	v_mfma_f32_16x16x32_bf16 v[92:95], v[132:135], v[212:215], v[92:95]
	v_mfma_f32_16x16x32_bf16 v[88:91], v[156:159], v[212:215], v[88:91]
	v_mfma_f32_16x16x32_bf16 v[76:79], v[132:135], v[220:223], v[76:79]
	v_mfma_f32_16x16x32_bf16 v[72:75], v[156:159], v[220:223], v[72:75]
	v_mfma_f32_16x16x32_bf16 v[116:119], v[172:175], v[188:191], 0
	v_mfma_f32_16x16x32_bf16 v[112:115], v[180:183], v[188:191], 0
	v_mfma_f32_16x16x32_bf16 v[100:103], v[172:175], v[200:203], 0
	v_mfma_f32_16x16x32_bf16 v[96:99], v[180:183], v[200:203], 0
	v_mfma_f32_16x16x32_bf16 v[84:87], v[172:175], v[208:211], 0
	v_mfma_f32_16x16x32_bf16 v[80:83], v[180:183], v[208:211], 0
	v_mfma_f32_16x16x32_bf16 v[68:71], v[172:175], v[216:219], 0
	v_mfma_f32_16x16x32_bf16 v[64:67], v[180:183], v[216:219], 0
	v_mfma_f32_16x16x32_bf16 v[116:119], v[176:179], v[196:199], v[116:119]
	v_mfma_f32_16x16x32_bf16 v[112:115], v[184:187], v[196:199], v[112:115]
	v_mfma_f32_16x16x32_bf16 v[100:103], v[176:179], v[204:207], v[100:103]
	v_mfma_f32_16x16x32_bf16 v[96:99], v[184:187], v[204:207], v[96:99]
	v_mfma_f32_16x16x32_bf16 v[84:87], v[176:179], v[212:215], v[84:87]
	v_mfma_f32_16x16x32_bf16 v[80:83], v[184:187], v[212:215], v[80:83]
	v_mfma_f32_16x16x32_bf16 v[68:71], v[176:179], v[220:223], v[68:71]
	v_mfma_f32_16x16x32_bf16 v[64:67], v[184:187], v[220:223], v[64:67]
	s_barrier
	s_setprio 0
	s_add_i32 s56, s43, s26
	v_lshl_add_u64 v[160:161], s[2:3], 0, v[150:151]
	s_mov_b32 m0, s56
	ds_read_b128 v[188:191], v167 offset:16384
	ds_read_b128 v[196:199], v167 offset:17408
	ds_read_b128 v[200:203], v167 offset:18432
	ds_read_b128 v[204:207], v167 offset:19456
	ds_read_b128 v[208:211], v167 offset:20480
	ds_read_b128 v[212:215], v167 offset:21504
	ds_read_b128 v[216:219], v167 offset:22528
	ds_read_b128 v[220:223], v167 offset:23552
	global_load_lds_dwordx4 v[160:161], off
	s_add_i32 m0, s56, 0x2000
	s_add_u32 s56, s2, 0xb0000
	v_lshl_add_u64 v[192:193], s[2:3], 0, v[154:155]
	s_addc_u32 s57, s3, 0
	s_add_i32 s58, s44, s26
	global_load_lds_dwordx4 v[192:193], off
	v_lshl_add_u64 v[224:225], s[56:57], 0, v[150:151]
	s_mov_b32 m0, s58
	v_lshl_add_u64 v[226:227], s[22:23], 0, v[152:153]
	global_load_lds_dwordx4 v[224:225], off
	v_lshl_add_u64 v[224:225], s[56:57], 0, v[154:155]
	s_add_i32 m0, s58, 0x2000
	s_nop 0
	global_load_lds_dwordx4 v[224:225], off
	v_lshl_add_u64 v[224:225], s[22:23], 0, v[148:149]
	s_mov_b32 m0, s27
	s_nop 0
	global_load_lds_dwordx4 v[224:225], off
	s_mov_b32 m0, s28
	s_nop 0
	global_load_lds_dwordx4 v[226:227], off
	s_waitcnt vmcnt(8)
	s_waitcnt lgkmcnt(0)
	s_setprio 1
	s_barrier
	v_mfma_f32_16x16x32_bf16 v[60:63], v[128:131], v[188:191], 0
	v_mfma_f32_16x16x32_bf16 v[56:59], v[136:139], v[188:191], 0
	v_mfma_f32_16x16x32_bf16 v[44:47], v[128:131], v[200:203], 0
	v_mfma_f32_16x16x32_bf16 v[40:43], v[136:139], v[200:203], 0
	v_mfma_f32_16x16x32_bf16 v[28:31], v[128:131], v[208:211], 0
	v_mfma_f32_16x16x32_bf16 v[24:27], v[136:139], v[208:211], 0
	v_mfma_f32_16x16x32_bf16 v[12:15], v[128:131], v[216:219], 0
	v_mfma_f32_16x16x32_bf16 v[8:11], v[136:139], v[216:219], 0
	v_mfma_f32_16x16x32_bf16 v[60:63], v[132:135], v[196:199], v[60:63]
	v_mfma_f32_16x16x32_bf16 v[56:59], v[156:159], v[196:199], v[56:59]
	v_mfma_f32_16x16x32_bf16 v[44:47], v[132:135], v[204:207], v[44:47]
	v_mfma_f32_16x16x32_bf16 v[40:43], v[156:159], v[204:207], v[40:43]
	v_mfma_f32_16x16x32_bf16 v[28:31], v[132:135], v[212:215], v[28:31]
	v_mfma_f32_16x16x32_bf16 v[24:27], v[156:159], v[212:215], v[24:27]
	v_mfma_f32_16x16x32_bf16 v[12:15], v[132:135], v[220:223], v[12:15]
	v_mfma_f32_16x16x32_bf16 v[8:11], v[156:159], v[220:223], v[8:11]
	v_mfma_f32_16x16x32_bf16 v[52:55], v[172:175], v[188:191], 0
	v_mfma_f32_16x16x32_bf16 v[48:51], v[180:183], v[188:191], 0
	v_mfma_f32_16x16x32_bf16 v[36:39], v[172:175], v[200:203], 0
	v_mfma_f32_16x16x32_bf16 v[32:35], v[180:183], v[200:203], 0
	v_mfma_f32_16x16x32_bf16 v[20:23], v[172:175], v[208:211], 0
	v_mfma_f32_16x16x32_bf16 v[16:19], v[180:183], v[208:211], 0
	v_mfma_f32_16x16x32_bf16 v[4:7], v[172:175], v[216:219], 0
	v_mfma_f32_16x16x32_bf16 v[0:3], v[180:183], v[216:219], 0
	v_mfma_f32_16x16x32_bf16 v[52:55], v[176:179], v[196:199], v[52:55]
	v_mfma_f32_16x16x32_bf16 v[48:51], v[184:187], v[196:199], v[48:51]
	v_mfma_f32_16x16x32_bf16 v[36:39], v[176:179], v[204:207], v[36:39]
	v_mfma_f32_16x16x32_bf16 v[32:35], v[184:187], v[204:207], v[32:35]
	v_mfma_f32_16x16x32_bf16 v[20:23], v[176:179], v[212:215], v[20:23]
	v_mfma_f32_16x16x32_bf16 v[16:19], v[184:187], v[212:215], v[16:19]
	v_mfma_f32_16x16x32_bf16 v[4:7], v[176:179], v[220:223], v[4:7]
	v_mfma_f32_16x16x32_bf16 v[0:3], v[184:187], v[220:223], v[0:3]
	s_barrier
	s_setprio 0
	s_add_i32 s56, 0, 0x18000
	s_add_i32 s57, 0, 0x1c000
	v_add_u32_e32 v156, s56, v162
	v_add_u32_e32 v169, s57, v162
	ds_read_b128 v[128:131], v156
	ds_read_b128 v[132:135], v156 offset:1024
	ds_read_b128 v[136:139], v156 offset:2048
	ds_read_b128 v[156:159], v156 offset:3072
	ds_read_b128 v[172:175], v169
	ds_read_b128 v[176:179], v169 offset:1024
	ds_read_b128 v[180:183], v169 offset:2048
	ds_read_b128 v[184:187], v169 offset:3072
	s_add_u32 s22, s22, 0xb0000
	s_addc_u32 s23, s23, 0
	s_mov_b32 m0, s29
	v_lshl_add_u64 v[228:229], s[22:23], 0, v[148:149]
	ds_read_b128 v[188:191], v167 offset:32768
	ds_read_b128 v[196:199], v167 offset:33792
	ds_read_b128 v[200:203], v167 offset:34816
	ds_read_b128 v[204:207], v167 offset:35840
	ds_read_b128 v[208:211], v167 offset:36864
	ds_read_b128 v[212:215], v167 offset:37888
	ds_read_b128 v[216:219], v167 offset:38912
	ds_read_b128 v[220:223], v167 offset:39936
	global_load_lds_dwordx4 v[228:229], off
	v_lshl_add_u64 v[228:229], s[22:23], 0, v[152:153]
	s_mov_b32 m0, s30
	s_nop 0
	global_load_lds_dwordx4 v[228:229], off
	s_waitcnt vmcnt(8)
	s_waitcnt lgkmcnt(0)
	s_setprio 1
	s_barrier
	v_mfma_f32_16x16x32_bf16 v[124:127], v[128:131], v[188:191], v[124:127]
	v_mfma_f32_16x16x32_bf16 v[120:123], v[136:139], v[188:191], v[120:123]
	v_mfma_f32_16x16x32_bf16 v[108:111], v[128:131], v[200:203], v[108:111]
	v_mfma_f32_16x16x32_bf16 v[104:107], v[136:139], v[200:203], v[104:107]
	v_mfma_f32_16x16x32_bf16 v[92:95], v[128:131], v[208:211], v[92:95]
	v_mfma_f32_16x16x32_bf16 v[88:91], v[136:139], v[208:211], v[88:91]
	v_mfma_f32_16x16x32_bf16 v[76:79], v[128:131], v[216:219], v[76:79]
	v_mfma_f32_16x16x32_bf16 v[72:75], v[136:139], v[216:219], v[72:75]
	v_mfma_f32_16x16x32_bf16 v[124:127], v[132:135], v[196:199], v[124:127]
	v_mfma_f32_16x16x32_bf16 v[120:123], v[156:159], v[196:199], v[120:123]
	v_mfma_f32_16x16x32_bf16 v[108:111], v[132:135], v[204:207], v[108:111]
	v_mfma_f32_16x16x32_bf16 v[104:107], v[156:159], v[204:207], v[104:107]
	v_mfma_f32_16x16x32_bf16 v[92:95], v[132:135], v[212:215], v[92:95]
	v_mfma_f32_16x16x32_bf16 v[88:91], v[156:159], v[212:215], v[88:91]
	v_mfma_f32_16x16x32_bf16 v[76:79], v[132:135], v[220:223], v[76:79]
	v_mfma_f32_16x16x32_bf16 v[72:75], v[156:159], v[220:223], v[72:75]
	v_mfma_f32_16x16x32_bf16 v[116:119], v[172:175], v[188:191], v[116:119]
	v_mfma_f32_16x16x32_bf16 v[112:115], v[180:183], v[188:191], v[112:115]
	v_mfma_f32_16x16x32_bf16 v[100:103], v[172:175], v[200:203], v[100:103]
	v_mfma_f32_16x16x32_bf16 v[96:99], v[180:183], v[200:203], v[96:99]
	v_mfma_f32_16x16x32_bf16 v[84:87], v[172:175], v[208:211], v[84:87]
	v_mfma_f32_16x16x32_bf16 v[80:83], v[180:183], v[208:211], v[80:83]
	v_mfma_f32_16x16x32_bf16 v[68:71], v[172:175], v[216:219], v[68:71]
	v_mfma_f32_16x16x32_bf16 v[64:67], v[180:183], v[216:219], v[64:67]
	v_mfma_f32_16x16x32_bf16 v[116:119], v[176:179], v[196:199], v[116:119]
	v_mfma_f32_16x16x32_bf16 v[112:115], v[184:187], v[196:199], v[112:115]
	v_mfma_f32_16x16x32_bf16 v[100:103], v[176:179], v[204:207], v[100:103]
	v_mfma_f32_16x16x32_bf16 v[96:99], v[184:187], v[204:207], v[96:99]
	v_mfma_f32_16x16x32_bf16 v[84:87], v[176:179], v[212:215], v[84:87]
	v_mfma_f32_16x16x32_bf16 v[80:83], v[184:187], v[212:215], v[80:83]
	v_mfma_f32_16x16x32_bf16 v[68:71], v[176:179], v[220:223], v[68:71]
	v_mfma_f32_16x16x32_bf16 v[64:67], v[184:187], v[220:223], v[64:67]
	s_barrier
	s_setprio 0
	s_add_i32 s22, s56, s26
	v_lshl_add_u64 v[160:161], v[160:161], 0, s[12:13]
	s_mov_b32 m0, s22
	ds_read_b128 v[188:191], v167 offset:49152
	ds_read_b128 v[196:199], v167 offset:50176
	ds_read_b128 v[200:203], v167 offset:51200
	ds_read_b128 v[204:207], v167 offset:52224
	ds_read_b128 v[208:211], v167 offset:53248
	ds_read_b128 v[212:215], v167 offset:54272
	ds_read_b128 v[216:219], v167 offset:55296
	ds_read_b128 v[220:223], v167 offset:56320
	global_load_lds_dwordx4 v[160:161], off
	s_add_i32 m0, s22, 0x2000
	s_add_u32 s2, s2, 0xb0080
	v_lshl_add_u64 v[160:161], v[192:193], 0, s[12:13]
	s_addc_u32 s3, s3, 0
	s_add_i32 s22, s57, s26
	global_load_lds_dwordx4 v[160:161], off
	v_lshl_add_u64 v[160:161], s[2:3], 0, v[150:151]
	s_mov_b32 m0, s22
	s_nop 0
	global_load_lds_dwordx4 v[160:161], off
	v_lshl_add_u64 v[160:161], s[2:3], 0, v[154:155]
	s_add_i32 m0, s22, 0x2000
	s_nop 0
	global_load_lds_dwordx4 v[160:161], off
	v_lshl_add_u64 v[160:161], v[224:225], 0, s[12:13]
	s_mov_b32 m0, s36
	s_nop 0
	global_load_lds_dwordx4 v[160:161], off
	v_lshl_add_u64 v[160:161], v[226:227], 0, s[12:13]
	s_mov_b32 m0, s37
	s_nop 0
	global_load_lds_dwordx4 v[160:161], off
	s_waitcnt vmcnt(8)
	s_waitcnt lgkmcnt(0)
	s_setprio 1
	s_barrier
	v_mfma_f32_16x16x32_bf16 v[60:63], v[128:131], v[188:191], v[60:63]
	v_mfma_f32_16x16x32_bf16 v[56:59], v[136:139], v[188:191], v[56:59]
	v_mfma_f32_16x16x32_bf16 v[44:47], v[128:131], v[200:203], v[44:47]
	v_mfma_f32_16x16x32_bf16 v[40:43], v[136:139], v[200:203], v[40:43]
	v_mfma_f32_16x16x32_bf16 v[28:31], v[128:131], v[208:211], v[28:31]
	v_mfma_f32_16x16x32_bf16 v[24:27], v[136:139], v[208:211], v[24:27]
	v_mfma_f32_16x16x32_bf16 v[12:15], v[128:131], v[216:219], v[12:15]
	v_mfma_f32_16x16x32_bf16 v[8:11], v[136:139], v[216:219], v[8:11]
	v_mfma_f32_16x16x32_bf16 v[60:63], v[132:135], v[196:199], v[60:63]
	v_mfma_f32_16x16x32_bf16 v[56:59], v[156:159], v[196:199], v[56:59]
	v_mfma_f32_16x16x32_bf16 v[44:47], v[132:135], v[204:207], v[44:47]
	v_mfma_f32_16x16x32_bf16 v[40:43], v[156:159], v[204:207], v[40:43]
	v_mfma_f32_16x16x32_bf16 v[28:31], v[132:135], v[212:215], v[28:31]
	v_mfma_f32_16x16x32_bf16 v[24:27], v[156:159], v[212:215], v[24:27]
	v_mfma_f32_16x16x32_bf16 v[12:15], v[132:135], v[220:223], v[12:15]
	v_mfma_f32_16x16x32_bf16 v[8:11], v[156:159], v[220:223], v[8:11]
	v_mfma_f32_16x16x32_bf16 v[52:55], v[172:175], v[188:191], v[52:55]
	v_mfma_f32_16x16x32_bf16 v[48:51], v[180:183], v[188:191], v[48:51]
	v_mfma_f32_16x16x32_bf16 v[36:39], v[172:175], v[200:203], v[36:39]
	v_mfma_f32_16x16x32_bf16 v[32:35], v[180:183], v[200:203], v[32:35]
	v_mfma_f32_16x16x32_bf16 v[20:23], v[172:175], v[208:211], v[20:23]
	v_mfma_f32_16x16x32_bf16 v[16:19], v[180:183], v[208:211], v[16:19]
	v_mfma_f32_16x16x32_bf16 v[4:7], v[172:175], v[216:219], v[4:7]
	v_mfma_f32_16x16x32_bf16 v[0:3], v[180:183], v[216:219], v[0:3]
	v_mfma_f32_16x16x32_bf16 v[52:55], v[176:179], v[196:199], v[52:55]
	v_mfma_f32_16x16x32_bf16 v[48:51], v[184:187], v[196:199], v[48:51]
	v_mfma_f32_16x16x32_bf16 v[36:39], v[176:179], v[204:207], v[36:39]
	v_mfma_f32_16x16x32_bf16 v[32:35], v[184:187], v[204:207], v[32:35]
	v_mfma_f32_16x16x32_bf16 v[20:23], v[176:179], v[212:215], v[20:23]
	v_mfma_f32_16x16x32_bf16 v[16:19], v[184:187], v[212:215], v[16:19]
	v_mfma_f32_16x16x32_bf16 v[4:7], v[176:179], v[220:223], v[4:7]
	v_mfma_f32_16x16x32_bf16 v[0:3], v[184:187], v[220:223], v[0:3]
	s_barrier
	s_setprio 0
	s_add_i32 s55, s55, 2
	s_add_u32 s14, s14, 0x100
	s_addc_u32 s15, s15, 0
	s_add_u32 s53, s53, 0x100
	s_addc_u32 s54, s54, 0
	s_cmp_gt_u32 s55, 41
	s_cbranch_scc1 .Lgemm_kdone_6
.LBB0_891:
	ds_read_b128 v[128:131], v165
	ds_read_b128 v[132:135], v165 offset:1024
	ds_read_b128 v[136:139], v165 offset:2048
	ds_read_b128 v[156:159], v165 offset:3072
	ds_read_b128 v[172:175], v166
	ds_read_b128 v[176:179], v166 offset:1024
	ds_read_b128 v[180:183], v166 offset:2048
	ds_read_b128 v[184:187], v166 offset:3072
	s_add_u32 s2, s14, 0xfff50080
	s_addc_u32 s3, s15, -1
	s_cmp_eq_u32 s55, 40
	s_cselect_b32 s23, s1, s3
	s_cselect_b32 s22, s0, s2
	s_cselect_b32 s3, s21, s54
	s_cselect_b32 s2, s20, s53
	v_lshl_add_u64 v[160:161], s[14:15], 0, v[140:141]
	s_add_i32 m0, s27, 0xc000
	ds_read_b128 v[188:191], v167
	ds_read_b128 v[196:199], v167 offset:1024
	ds_read_b128 v[200:203], v167 offset:2048
	ds_read_b128 v[204:207], v167 offset:3072
	ds_read_b128 v[208:211], v167 offset:4096
	ds_read_b128 v[212:215], v167 offset:5120
	ds_read_b128 v[216:219], v167 offset:6144
	ds_read_b128 v[220:223], v167 offset:7168
	global_load_lds_dwordx4 v[160:161], off
	v_lshl_add_u64 v[160:161], s[14:15], 0, v[142:143]
	s_add_i32 m0, s27, 0xe000
	s_nop 0
	global_load_lds_dwordx4 v[160:161], off
	s_waitcnt vmcnt(8)
	s_waitcnt lgkmcnt(0)
	s_setprio 1
	s_barrier
	v_mfma_f32_16x16x32_bf16 v[124:127], v[128:131], v[188:191], v[124:127]
	v_mfma_f32_16x16x32_bf16 v[120:123], v[136:139], v[188:191], v[120:123]
	v_mfma_f32_16x16x32_bf16 v[108:111], v[128:131], v[200:203], v[108:111]
	v_mfma_f32_16x16x32_bf16 v[104:107], v[136:139], v[200:203], v[104:107]
	v_mfma_f32_16x16x32_bf16 v[92:95], v[128:131], v[208:211], v[92:95]
	v_mfma_f32_16x16x32_bf16 v[88:91], v[136:139], v[208:211], v[88:91]
	v_mfma_f32_16x16x32_bf16 v[76:79], v[128:131], v[216:219], v[76:79]
	v_mfma_f32_16x16x32_bf16 v[72:75], v[136:139], v[216:219], v[72:75]
	v_mfma_f32_16x16x32_bf16 v[124:127], v[132:135], v[196:199], v[124:127]
	v_mfma_f32_16x16x32_bf16 v[120:123], v[156:159], v[196:199], v[120:123]
	v_mfma_f32_16x16x32_bf16 v[108:111], v[132:135], v[204:207], v[108:111]
	v_mfma_f32_16x16x32_bf16 v[104:107], v[156:159], v[204:207], v[104:107]
	v_mfma_f32_16x16x32_bf16 v[92:95], v[132:135], v[212:215], v[92:95]
	v_mfma_f32_16x16x32_bf16 v[88:91], v[156:159], v[212:215], v[88:91]
	v_mfma_f32_16x16x32_bf16 v[76:79], v[132:135], v[220:223], v[76:79]
	v_mfma_f32_16x16x32_bf16 v[72:75], v[156:159], v[220:223], v[72:75]
	v_mfma_f32_16x16x32_bf16 v[116:119], v[172:175], v[188:191], v[116:119]
	v_mfma_f32_16x16x32_bf16 v[112:115], v[180:183], v[188:191], v[112:115]
	v_mfma_f32_16x16x32_bf16 v[100:103], v[172:175], v[200:203], v[100:103]
	v_mfma_f32_16x16x32_bf16 v[96:99], v[180:183], v[200:203], v[96:99]
	v_mfma_f32_16x16x32_bf16 v[84:87], v[172:175], v[208:211], v[84:87]
	v_mfma_f32_16x16x32_bf16 v[80:83], v[180:183], v[208:211], v[80:83]
	v_mfma_f32_16x16x32_bf16 v[68:71], v[172:175], v[216:219], v[68:71]
	v_mfma_f32_16x16x32_bf16 v[64:67], v[180:183], v[216:219], v[64:67]
	v_mfma_f32_16x16x32_bf16 v[116:119], v[176:179], v[196:199], v[116:119]
	v_mfma_f32_16x16x32_bf16 v[112:115], v[184:187], v[196:199], v[112:115]
	v_mfma_f32_16x16x32_bf16 v[100:103], v[176:179], v[204:207], v[100:103]
	v_mfma_f32_16x16x32_bf16 v[96:99], v[184:187], v[204:207], v[96:99]
	v_mfma_f32_16x16x32_bf16 v[84:87], v[176:179], v[212:215], v[84:87]
	v_mfma_f32_16x16x32_bf16 v[80:83], v[184:187], v[212:215], v[80:83]
	v_mfma_f32_16x16x32_bf16 v[68:71], v[176:179], v[220:223], v[68:71]
	v_mfma_f32_16x16x32_bf16 v[64:67], v[184:187], v[220:223], v[64:67]
	s_barrier
	s_setprio 0
	s_add_i32 s56, s43, s26
	v_lshl_add_u64 v[160:161], s[2:3], 0, v[150:151]
	s_mov_b32 m0, s56
	ds_read_b128 v[188:191], v167 offset:16384
	ds_read_b128 v[196:199], v167 offset:17408
	ds_read_b128 v[200:203], v167 offset:18432
	ds_read_b128 v[204:207], v167 offset:19456
	ds_read_b128 v[208:211], v167 offset:20480
	ds_read_b128 v[212:215], v167 offset:21504
	ds_read_b128 v[216:219], v167 offset:22528
	ds_read_b128 v[220:223], v167 offset:23552
	global_load_lds_dwordx4 v[160:161], off
	s_add_i32 m0, s56, 0x2000
	s_add_u32 s56, s2, 0xb0000
	v_lshl_add_u64 v[192:193], s[2:3], 0, v[154:155]
	s_addc_u32 s57, s3, 0
	s_add_i32 s58, s44, s26
	global_load_lds_dwordx4 v[192:193], off
	v_lshl_add_u64 v[224:225], s[56:57], 0, v[150:151]
	s_mov_b32 m0, s58
	v_lshl_add_u64 v[226:227], s[22:23], 0, v[152:153]
	global_load_lds_dwordx4 v[224:225], off
	v_lshl_add_u64 v[224:225], s[56:57], 0, v[154:155]
	s_add_i32 m0, s58, 0x2000
	s_nop 0
	global_load_lds_dwordx4 v[224:225], off
	v_lshl_add_u64 v[224:225], s[22:23], 0, v[148:149]
	s_mov_b32 m0, s27
	s_nop 0
	global_load_lds_dwordx4 v[224:225], off
	s_mov_b32 m0, s28
	s_nop 0
	global_load_lds_dwordx4 v[226:227], off
	s_waitcnt vmcnt(8)
	s_waitcnt lgkmcnt(0)
	s_setprio 1
	s_barrier
	v_mfma_f32_16x16x32_bf16 v[60:63], v[128:131], v[188:191], v[60:63]
	v_mfma_f32_16x16x32_bf16 v[56:59], v[136:139], v[188:191], v[56:59]
	v_mfma_f32_16x16x32_bf16 v[44:47], v[128:131], v[200:203], v[44:47]
	v_mfma_f32_16x16x32_bf16 v[40:43], v[136:139], v[200:203], v[40:43]
	v_mfma_f32_16x16x32_bf16 v[28:31], v[128:131], v[208:211], v[28:31]
	v_mfma_f32_16x16x32_bf16 v[24:27], v[136:139], v[208:211], v[24:27]
	v_mfma_f32_16x16x32_bf16 v[12:15], v[128:131], v[216:219], v[12:15]
	v_mfma_f32_16x16x32_bf16 v[8:11], v[136:139], v[216:219], v[8:11]
	v_mfma_f32_16x16x32_bf16 v[60:63], v[132:135], v[196:199], v[60:63]
	v_mfma_f32_16x16x32_bf16 v[56:59], v[156:159], v[196:199], v[56:59]
	v_mfma_f32_16x16x32_bf16 v[44:47], v[132:135], v[204:207], v[44:47]
	v_mfma_f32_16x16x32_bf16 v[40:43], v[156:159], v[204:207], v[40:43]
	v_mfma_f32_16x16x32_bf16 v[28:31], v[132:135], v[212:215], v[28:31]
	v_mfma_f32_16x16x32_bf16 v[24:27], v[156:159], v[212:215], v[24:27]
	v_mfma_f32_16x16x32_bf16 v[12:15], v[132:135], v[220:223], v[12:15]
	v_mfma_f32_16x16x32_bf16 v[8:11], v[156:159], v[220:223], v[8:11]
	v_mfma_f32_16x16x32_bf16 v[52:55], v[172:175], v[188:191], v[52:55]
	v_mfma_f32_16x16x32_bf16 v[48:51], v[180:183], v[188:191], v[48:51]
	v_mfma_f32_16x16x32_bf16 v[36:39], v[172:175], v[200:203], v[36:39]
	v_mfma_f32_16x16x32_bf16 v[32:35], v[180:183], v[200:203], v[32:35]
	v_mfma_f32_16x16x32_bf16 v[20:23], v[172:175], v[208:211], v[20:23]
	v_mfma_f32_16x16x32_bf16 v[16:19], v[180:183], v[208:211], v[16:19]
	v_mfma_f32_16x16x32_bf16 v[4:7], v[172:175], v[216:219], v[4:7]
	v_mfma_f32_16x16x32_bf16 v[0:3], v[180:183], v[216:219], v[0:3]
	v_mfma_f32_16x16x32_bf16 v[52:55], v[176:179], v[196:199], v[52:55]
	v_mfma_f32_16x16x32_bf16 v[48:51], v[184:187], v[196:199], v[48:51]
	v_mfma_f32_16x16x32_bf16 v[36:39], v[176:179], v[204:207], v[36:39]
	v_mfma_f32_16x16x32_bf16 v[32:35], v[184:187], v[204:207], v[32:35]
	v_mfma_f32_16x16x32_bf16 v[20:23], v[176:179], v[212:215], v[20:23]
	v_mfma_f32_16x16x32_bf16 v[16:19], v[184:187], v[212:215], v[16:19]
	v_mfma_f32_16x16x32_bf16 v[4:7], v[176:179], v[220:223], v[4:7]
	v_mfma_f32_16x16x32_bf16 v[0:3], v[184:187], v[220:223], v[0:3]
	s_barrier
	s_setprio 0
	s_add_i32 s56, 0, 0x18000
	s_add_i32 s57, 0, 0x1c000
	v_add_u32_e32 v156, s56, v162
	v_add_u32_e32 v169, s57, v162
	ds_read_b128 v[128:131], v156
	ds_read_b128 v[132:135], v156 offset:1024
	ds_read_b128 v[136:139], v156 offset:2048
	ds_read_b128 v[156:159], v156 offset:3072
	ds_read_b128 v[172:175], v169
	ds_read_b128 v[176:179], v169 offset:1024
	ds_read_b128 v[180:183], v169 offset:2048
	ds_read_b128 v[184:187], v169 offset:3072
	s_add_u32 s22, s22, 0xb0000
	s_addc_u32 s23, s23, 0
	s_mov_b32 m0, s29
	v_lshl_add_u64 v[228:229], s[22:23], 0, v[148:149]
	ds_read_b128 v[188:191], v167 offset:32768
	ds_read_b128 v[196:199], v167 offset:33792
	ds_read_b128 v[200:203], v167 offset:34816
	ds_read_b128 v[204:207], v167 offset:35840
	ds_read_b128 v[208:211], v167 offset:36864
	ds_read_b128 v[212:215], v167 offset:37888
	ds_read_b128 v[216:219], v167 offset:38912
	ds_read_b128 v[220:223], v167 offset:39936
	global_load_lds_dwordx4 v[228:229], off
	v_lshl_add_u64 v[228:229], s[22:23], 0, v[152:153]
	s_mov_b32 m0, s30
	s_nop 0
	global_load_lds_dwordx4 v[228:229], off
	s_waitcnt vmcnt(8)
	s_waitcnt lgkmcnt(0)
	s_setprio 1
	s_barrier
	v_mfma_f32_16x16x32_bf16 v[124:127], v[128:131], v[188:191], v[124:127]
	v_mfma_f32_16x16x32_bf16 v[120:123], v[136:139], v[188:191], v[120:123]
	v_mfma_f32_16x16x32_bf16 v[108:111], v[128:131], v[200:203], v[108:111]
	v_mfma_f32_16x16x32_bf16 v[104:107], v[136:139], v[200:203], v[104:107]
	v_mfma_f32_16x16x32_bf16 v[92:95], v[128:131], v[208:211], v[92:95]
	v_mfma_f32_16x16x32_bf16 v[88:91], v[136:139], v[208:211], v[88:91]
	v_mfma_f32_16x16x32_bf16 v[76:79], v[128:131], v[216:219], v[76:79]
	v_mfma_f32_16x16x32_bf16 v[72:75], v[136:139], v[216:219], v[72:75]
	v_mfma_f32_16x16x32_bf16 v[124:127], v[132:135], v[196:199], v[124:127]
	v_mfma_f32_16x16x32_bf16 v[120:123], v[156:159], v[196:199], v[120:123]
	v_mfma_f32_16x16x32_bf16 v[108:111], v[132:135], v[204:207], v[108:111]
	v_mfma_f32_16x16x32_bf16 v[104:107], v[156:159], v[204:207], v[104:107]
	v_mfma_f32_16x16x32_bf16 v[92:95], v[132:135], v[212:215], v[92:95]
	v_mfma_f32_16x16x32_bf16 v[88:91], v[156:159], v[212:215], v[88:91]
	v_mfma_f32_16x16x32_bf16 v[76:79], v[132:135], v[220:223], v[76:79]
	v_mfma_f32_16x16x32_bf16 v[72:75], v[156:159], v[220:223], v[72:75]
	v_mfma_f32_16x16x32_bf16 v[116:119], v[172:175], v[188:191], v[116:119]
	v_mfma_f32_16x16x32_bf16 v[112:115], v[180:183], v[188:191], v[112:115]
	v_mfma_f32_16x16x32_bf16 v[100:103], v[172:175], v[200:203], v[100:103]
	v_mfma_f32_16x16x32_bf16 v[96:99], v[180:183], v[200:203], v[96:99]
	v_mfma_f32_16x16x32_bf16 v[84:87], v[172:175], v[208:211], v[84:87]
	v_mfma_f32_16x16x32_bf16 v[80:83], v[180:183], v[208:211], v[80:83]
	v_mfma_f32_16x16x32_bf16 v[68:71], v[172:175], v[216:219], v[68:71]
	v_mfma_f32_16x16x32_bf16 v[64:67], v[180:183], v[216:219], v[64:67]
	v_mfma_f32_16x16x32_bf16 v[116:119], v[176:179], v[196:199], v[116:119]
	v_mfma_f32_16x16x32_bf16 v[112:115], v[184:187], v[196:199], v[112:115]
	v_mfma_f32_16x16x32_bf16 v[100:103], v[176:179], v[204:207], v[100:103]
	v_mfma_f32_16x16x32_bf16 v[96:99], v[184:187], v[204:207], v[96:99]
	v_mfma_f32_16x16x32_bf16 v[84:87], v[176:179], v[212:215], v[84:87]
	v_mfma_f32_16x16x32_bf16 v[80:83], v[184:187], v[212:215], v[80:83]
	v_mfma_f32_16x16x32_bf16 v[68:71], v[176:179], v[220:223], v[68:71]
	v_mfma_f32_16x16x32_bf16 v[64:67], v[184:187], v[220:223], v[64:67]
	s_barrier
	s_setprio 0
	s_add_i32 s22, s56, s26
	v_lshl_add_u64 v[160:161], v[160:161], 0, s[12:13]
	s_mov_b32 m0, s22
	ds_read_b128 v[188:191], v167 offset:49152
	ds_read_b128 v[196:199], v167 offset:50176
	ds_read_b128 v[200:203], v167 offset:51200
	ds_read_b128 v[204:207], v167 offset:52224
	ds_read_b128 v[208:211], v167 offset:53248
	ds_read_b128 v[212:215], v167 offset:54272
	ds_read_b128 v[216:219], v167 offset:55296
	ds_read_b128 v[220:223], v167 offset:56320
	global_load_lds_dwordx4 v[160:161], off
	s_add_i32 m0, s22, 0x2000
	s_add_u32 s2, s2, 0xb0080
	v_lshl_add_u64 v[160:161], v[192:193], 0, s[12:13]
	s_addc_u32 s3, s3, 0
	s_add_i32 s22, s57, s26
	global_load_lds_dwordx4 v[160:161], off
	v_lshl_add_u64 v[160:161], s[2:3], 0, v[150:151]
	s_mov_b32 m0, s22
	s_nop 0
	global_load_lds_dwordx4 v[160:161], off
	v_lshl_add_u64 v[160:161], s[2:3], 0, v[154:155]
	s_add_i32 m0, s22, 0x2000
	s_nop 0
	global_load_lds_dwordx4 v[160:161], off
	v_lshl_add_u64 v[160:161], v[224:225], 0, s[12:13]
	s_mov_b32 m0, s36
	s_nop 0
	global_load_lds_dwordx4 v[160:161], off
	v_lshl_add_u64 v[160:161], v[226:227], 0, s[12:13]
	s_mov_b32 m0, s37
	s_nop 0
	global_load_lds_dwordx4 v[160:161], off
	s_waitcnt vmcnt(8)
	s_waitcnt lgkmcnt(0)
	s_setprio 1
	s_barrier
	v_mfma_f32_16x16x32_bf16 v[60:63], v[128:131], v[188:191], v[60:63]
	v_mfma_f32_16x16x32_bf16 v[56:59], v[136:139], v[188:191], v[56:59]
	v_mfma_f32_16x16x32_bf16 v[44:47], v[128:131], v[200:203], v[44:47]
	v_mfma_f32_16x16x32_bf16 v[40:43], v[136:139], v[200:203], v[40:43]
	v_mfma_f32_16x16x32_bf16 v[28:31], v[128:131], v[208:211], v[28:31]
	v_mfma_f32_16x16x32_bf16 v[24:27], v[136:139], v[208:211], v[24:27]
	v_mfma_f32_16x16x32_bf16 v[12:15], v[128:131], v[216:219], v[12:15]
	v_mfma_f32_16x16x32_bf16 v[8:11], v[136:139], v[216:219], v[8:11]
	v_mfma_f32_16x16x32_bf16 v[60:63], v[132:135], v[196:199], v[60:63]
	v_mfma_f32_16x16x32_bf16 v[56:59], v[156:159], v[196:199], v[56:59]
	v_mfma_f32_16x16x32_bf16 v[44:47], v[132:135], v[204:207], v[44:47]
	v_mfma_f32_16x16x32_bf16 v[40:43], v[156:159], v[204:207], v[40:43]
	v_mfma_f32_16x16x32_bf16 v[28:31], v[132:135], v[212:215], v[28:31]
	v_mfma_f32_16x16x32_bf16 v[24:27], v[156:159], v[212:215], v[24:27]
	v_mfma_f32_16x16x32_bf16 v[12:15], v[132:135], v[220:223], v[12:15]
	v_mfma_f32_16x16x32_bf16 v[8:11], v[156:159], v[220:223], v[8:11]
	v_mfma_f32_16x16x32_bf16 v[52:55], v[172:175], v[188:191], v[52:55]
	v_mfma_f32_16x16x32_bf16 v[48:51], v[180:183], v[188:191], v[48:51]
	v_mfma_f32_16x16x32_bf16 v[36:39], v[172:175], v[200:203], v[36:39]
	v_mfma_f32_16x16x32_bf16 v[32:35], v[180:183], v[200:203], v[32:35]
	v_mfma_f32_16x16x32_bf16 v[20:23], v[172:175], v[208:211], v[20:23]
	v_mfma_f32_16x16x32_bf16 v[16:19], v[180:183], v[208:211], v[16:19]
	v_mfma_f32_16x16x32_bf16 v[4:7], v[172:175], v[216:219], v[4:7]
	v_mfma_f32_16x16x32_bf16 v[0:3], v[180:183], v[216:219], v[0:3]
	v_mfma_f32_16x16x32_bf16 v[52:55], v[176:179], v[196:199], v[52:55]
	v_mfma_f32_16x16x32_bf16 v[48:51], v[184:187], v[196:199], v[48:51]
	v_mfma_f32_16x16x32_bf16 v[36:39], v[176:179], v[204:207], v[36:39]
	v_mfma_f32_16x16x32_bf16 v[32:35], v[184:187], v[204:207], v[32:35]
	v_mfma_f32_16x16x32_bf16 v[20:23], v[176:179], v[212:215], v[20:23]
	v_mfma_f32_16x16x32_bf16 v[16:19], v[184:187], v[212:215], v[16:19]
	v_mfma_f32_16x16x32_bf16 v[4:7], v[176:179], v[220:223], v[4:7]
	v_mfma_f32_16x16x32_bf16 v[0:3], v[184:187], v[220:223], v[0:3]
	s_barrier
	s_setprio 0
	s_add_i32 s55, s55, 2
	s_add_u32 s14, s14, 0x100
	s_addc_u32 s15, s15, 0
	s_add_u32 s53, s53, 0x100
	s_addc_u32 s54, s54, 0
	s_cmp_gt_u32 s55, 41
	s_cbranch_scc0 .LBB0_891
